# sum-of-squares dedup extended to diff-QKV and the three PLAIN rstd GEMM copies; long phase-loop branches routed through in-range hops
# speedup vs baseline: 1.0339x; 1.0068x over previous
; DI int my_tid() { int t = threadIdx.x; asm volatile("" : "+v"(t)); return t; }
; __global__ void __launch_bounds__(NTHR, 2) k_mega(P p) {
;     ...
;   cg::grid_group grid = cg::this_grid();
;   unsigned* xbw = (unsigned*)(get_kargs()->ws + OFF_XBAR);
;   const unsigned xcc = (unsigned)__builtin_amdgcn_s_getreg((3 << 11) | 20) & 0xFu;
;   if (my_tid() == 0) __hip_atomic_fetch_add(xbw + 64 * xcc, 1u, __ATOMIC_RELAXED, __HIP_MEMORY_SCOPE_AGENT);
;   phase_prep(get_kargs(), smem);
;   grid.sync();
;   unsigned n_x = __hip_atomic_load(xbw + 64 * xcc, __ATOMIC_RELAXED, __HIP_MEMORY_SCOPE_AGENT), nxcd = 0;
;   for (int j = 0; j < 16; ++j) nxcd += __hip_atomic_load(xbw + 64 * j, __ATOMIC_RELAXED, __HIP_MEMORY_SCOPE_AGENT) != 0u ? 1u : 0u;
;   n_x = __builtin_amdgcn_readfirstlane(n_x); nxcd = __builtin_amdgcn_readfirstlane(nxcd);
; #pragma nounroll
;   for (int ph = 1; ph < NPHASE; ++ph) {
.LBB0_146:
	s_or_b64 exec, exec, s[2:3]
	s_lshl_b32 s4, s33, 8
	v_mov_b32_e32 v0, s4
	s_barrier
	v_mov_b32_e32 v217, 0
	global_load_dword v2, v0, s[8:9] sc1
	global_load_dword v3, v217, s[8:9] sc1
	v_mov_b32_e32 v0, 0x3e621000
	global_load_dword v4, v0, s[52:53] offset:256 sc1
	global_load_dword v5, v0, s[52:53] offset:512 sc1
	global_load_dword v6, v0, s[52:53] offset:768 sc1
	global_load_dword v7, v0, s[52:53] offset:1024 sc1
	global_load_dword v8, v0, s[52:53] offset:1280 sc1
	global_load_dword v9, v0, s[52:53] offset:1536 sc1
	global_load_dword v10, v0, s[52:53] offset:1792 sc1
	global_load_dword v11, v0, s[52:53] offset:2048 sc1
	global_load_dword v12, v0, s[52:53] offset:2304 sc1
	global_load_dword v13, v0, s[52:53] offset:2560 sc1
	global_load_dword v14, v0, s[52:53] offset:2816 sc1
	global_load_dword v15, v0, s[52:53] offset:3072 sc1
	global_load_dword v16, v0, s[52:53] offset:3328 sc1
	global_load_dword v17, v0, s[52:53] offset:3584 sc1
	global_load_dword v18, v0, s[52:53] offset:3840 sc1
	v_readlane_b32 s13, v254, 0
	s_cmpk_lt_i32 s13, 0xc0
	s_cselect_b64 s[24:25], -1, 0
	s_and_b32 s5, s13, 7
	s_ashr_i32 s2, s13, 3
	s_mul_i32 s3, s5, 24
	s_add_i32 s6, s3, s2
	s_ashr_i32 s2, s6, 31
	s_lshr_b32 s2, s2, 26
	s_add_i32 s2, s6, s2
	s_and_b32 s3, s2, 0xffffffc0
	s_lshl_b32 s2, s2, 5
	s_sub_i32 s3, s6, s3
	s_and_b32 s7, s2, 0xfffff800
	s_bfe_i32 s2, s3, 0x80000
	s_bfe_u32 s2, s2, 0x3000c
	s_add_i32 s2, s3, s2
	s_bfe_i32 s8, s2, 0x80000
	s_and_b32 s2, s2, 0xf8
	s_sub_i32 s2, s3, s2
	s_sext_i32_i8 s2, s2
	s_sext_i32_i16 s8, s8
	s_lshl_b32 s3, s2, 8
	s_ashr_i32 s1, s8, 3
	s_add_i32 s10, s3, s7
	v_writelane_b32 v254, s1, 5
	s_mov_b32 s8, s10
	s_ashr_i32 s11, s10, 31
	v_writelane_b32 v254, s8, 6
	s_lshl_b32 s2, s1, 8
	s_ashr_i32 s3, s2, 31
	v_writelane_b32 v254, s9, 7
	s_lshl_b64 s[8:9], s[10:11], 11
	v_writelane_b32 v254, s8, 8
	s_lshl_b64 s[30:31], s[2:3], 11
	s_mov_b32 s78, -4.0
	v_writelane_b32 v254, s9, 9
	s_mov_b32 s80, 0xc0c00000
	s_mov_b32 s82, 0xc1800000
	s_mov_b32 s84, 0xc1900000
	s_mov_b32 s86, 0xc1a00000
	s_mov_b32 s88, 0xc1b00000
	v_mbcnt_hi_u32_b32 v253, -1, v1
	v_mov_b32_e32 v246, 0x358637bd
	s_mov_b32 s79, 0xc0a00000
	s_mov_b32 s81, 0xc0e00000
	s_mov_b32 s83, 0xc1880000
	s_mov_b32 s85, 0xc1980000
	s_mov_b32 s87, 0xc1a80000
	s_mov_b32 s89, 0xc1b80000
	v_mov_b32_e32 v218, 0x7ffff800
	v_mov_b32_e32 v250, 0xffffe000
	s_movk_i32 s97, 0x600
	s_mov_b32 s27, 0xb0000
	s_mov_b32 s94, 0x18000
	s_mov_b32 s95, 1
	s_movk_i32 s44, 0x90
	s_mov_b32 s42, 0x20000
	s_mov_b32 s43, 0x40000
	s_mov_b32 s75, 0x60000
	s_mov_b32 s40, 0x58000
	s_mov_b32 s41, 0x108000
	s_movk_i32 s29, 0x210
	s_mov_b32 s66, 0x10000
	s_mov_b32 s67, 0x800000
	s_waitcnt vmcnt(14)
	v_cmp_ne_u32_e32 vcc, 0, v4
	s_mov_b32 s91, 0x24000
	s_mov_b32 s34, 0x15000
	v_cndmask_b32_e64 v0, 0, 1, vcc
	s_waitcnt vmcnt(13)
	v_cmp_ne_u32_e32 vcc, 0, v5
	s_mov_b32 s56, 0xc000
	s_mov_b32 s57, 0x2a000
	v_cndmask_b32_e64 v4, 0, 1, vcc
	s_waitcnt vmcnt(11)
	v_cmp_ne_u32_e32 vcc, 0, v7
	s_mov_b32 s28, 0x3f000
	s_mov_b32 s72, 0x30000
	v_cndmask_b32_e64 v5, 0, 1, vcc
	s_waitcnt vmcnt(9)
	v_cmp_ne_u32_e32 vcc, 0, v9
	v_readfirstlane_b32 s1, v2
	s_mov_b32 s51, 0
	v_cndmask_b32_e64 v7, 0, 1, vcc
	s_waitcnt vmcnt(7)
	v_cmp_ne_u32_e32 vcc, 0, v11
	v_writelane_b32 v254, s1, 10
	s_mov_b32 s76, 0x3a800000
	v_cndmask_b32_e64 v9, 0, 1, vcc
	s_waitcnt vmcnt(5)
	v_cmp_ne_u32_e32 vcc, 0, v13
	s_nop 1
	v_cndmask_b32_e64 v11, 0, 1, vcc
	s_waitcnt vmcnt(3)
	v_cmp_ne_u32_e32 vcc, 0, v15
	s_nop 1
	v_cndmask_b32_e64 v13, 0, 1, vcc
	s_waitcnt vmcnt(1)
	v_cmp_ne_u32_e32 vcc, 0, v17
	s_nop 1
	v_cndmask_b32_e64 v15, 0, 1, vcc
	v_cmp_ne_u32_e32 vcc, 0, v3
	s_nop 1
	v_addc_co_u32_e32 v0, vcc, 0, v0, vcc
	v_cmp_ne_u32_e32 vcc, 0, v6
	s_nop 1
	v_addc_co_u32_e32 v0, vcc, v0, v4, vcc
	v_cmp_ne_u32_e32 vcc, 0, v8
	s_nop 1
	v_addc_co_u32_e32 v0, vcc, v0, v5, vcc
	v_cmp_ne_u32_e32 vcc, 0, v10
	s_nop 1
	v_addc_co_u32_e32 v0, vcc, v0, v7, vcc
	v_cmp_ne_u32_e32 vcc, 0, v12
	s_nop 1
	v_addc_co_u32_e32 v0, vcc, v0, v9, vcc
	v_cmp_ne_u32_e32 vcc, 0, v14
	s_nop 1
	v_addc_co_u32_e32 v0, vcc, v0, v11, vcc
	v_cmp_ne_u32_e32 vcc, 0, v16
	s_nop 1
	v_addc_co_u32_e32 v0, vcc, v0, v13, vcc
	s_waitcnt vmcnt(0)
; template <int EPI, bool RS>
; DI void gemm_phase(unsigned char* smem, const bf16_t* __restrict__ A, int lda, const bf16_t* __restrict__ Bt, int K, int mt0, int nMt, int nNt, const EpiArgs& ea) {
;     ...
;   int nt, mtl; map_tile(tile, nMt, nNt, mtl, nt);
;   int m0 = (mt0 + mtl) * 256;
;   const char* ga = (const char*)(A + (size_t)m0 * lda);
;   const char* gb = (const char*)(Bt + (size_t)(nt * 256) * K);
	v_cmp_ne_u32_e32 vcc, 0, v18
	s_nop 1
	v_addc_co_u32_e32 v0, vcc, v0, v15, vcc
	s_nop 0
	v_readfirstlane_b32 s1, v0
	s_nop 1
	v_writelane_b32 v254, s1, 11
	s_lshl_b32 s1, s19, 9
	s_cmpk_lt_i32 s13, 0x2100
	v_writelane_b32 v254, s1, 12
	s_cselect_b64 s[2:3], -1, 0
	v_writelane_b32 v254, s2, 13
	s_nop 1
	v_writelane_b32 v254, s3, 14
	s_mul_i32 s2, s5, 0x408
	s_add_i32 s6, s6, s2
	s_mul_hi_i32 s2, s6, 0x2e8ba2e9
	s_lshr_b32 s3, s2, 31
	s_ashr_i32 s2, s2, 5
	s_add_i32 s2, s2, s3
	s_mul_i32 s3, s2, 0xb0
	s_sub_i32 s3, s6, s3
	s_sext_i32_i16 s7, s3
	s_bfe_u32 s7, s7, 0x3001c
	s_add_i32 s7, s3, s7
	s_sext_i32_i16 s8, s7
	s_and_b32 s7, s7, 0xfff8
	s_sub_i32 s3, s3, s7
	s_sext_i32_i16 s3, s3
	s_lshl_b32 s2, s2, 11
	s_lshl_b32 s3, s3, 8
	s_ashr_i32 s1, s8, 3
	s_add_i32 s8, s3, s2
	s_mov_b32 s2, s8
	s_ashr_i32 s9, s8, 31
	v_writelane_b32 v254, s2, 15
	s_nop 1
	v_writelane_b32 v254, s3, 16
	s_lshl_b64 s[2:3], s[8:9], 11
	v_writelane_b32 v254, s2, 17
	s_mul_i32 s9, s5, 0x180
	s_nop 0
	v_writelane_b32 v254, s3, 18
	s_lshl_b32 s2, s1, 8
	s_ashr_i32 s3, s2, 31
	v_writelane_b32 v254, s1, 19
	s_lshl_b64 s[2:3], s[2:3], 11
	v_writelane_b32 v254, s2, 20
	s_cmpk_lt_i32 s13, 0x600
	s_nop 0
	v_writelane_b32 v254, s3, 21
	s_cselect_b64 s[2:3], -1, 0
	v_writelane_b32 v254, s2, 22
	s_nop 1
	v_writelane_b32 v254, s3, 23
	s_mul_i32 s2, s5, 0xfffffca0
	s_add_i32 s8, s6, s2
	s_ashr_i32 s2, s8, 31
	s_lshr_b32 s2, s2, 27
	s_add_i32 s2, s8, s2
	s_and_b32 s3, s2, 0xffffffe0
	s_sub_i32 s3, s8, s3
	s_bfe_i32 s6, s3, 0x80000
	s_bfe_u32 s6, s6, 0x3000c
	s_add_i32 s6, s3, s6
	s_bfe_i32 s7, s6, 0x80000
	s_and_b32 s6, s6, 0xf8
	s_sub_i32 s3, s3, s6
	s_sext_i32_i8 s3, s3
	s_lshl_b32 s2, s2, 6
	s_and_b32 s2, s2, 0xfffff800
	s_lshl_b32 s3, s3, 8
	s_add_i32 s14, s3, s2
	s_sext_i32_i16 s7, s7
	s_ashr_i32 s15, s14, 31
	s_ashr_i32 s1, s7, 3
	s_lshl_b64 s[6:7], s[14:15], 11
	v_writelane_b32 v254, s6, 24
	s_mul_i32 s2, s1, 0xb0000
	s_ashr_i32 s3, s2, 31
	v_writelane_b32 v254, s7, 25
	s_lshl_b32 s6, s1, 8
	s_ashr_i32 s7, s6, 31
	v_writelane_b32 v254, s1, 26
	s_lshl_b64 s[10:11], s[6:7], 11
	v_writelane_b32 v254, s10, 27
	s_cmpk_lt_i32 s13, 0x1200
	s_mulk_i32 s5, 0xfe50
	v_writelane_b32 v254, s11, 28
	s_cselect_b64 s[10:11], -1, 0
	v_writelane_b32 v254, s10, 29
	s_nop 1
	v_writelane_b32 v254, s11, 30
	s_add_i32 s10, s8, s9
	s_mul_hi_i32 s8, s10, 0x2aaaaaab
	s_lshr_b32 s9, s8, 31
	s_ashr_i32 s8, s8, 4
	s_add_i32 s8, s8, s9
	s_mul_i32 s9, s8, 0x60
	s_sub_i32 s9, s10, s9
	s_bfe_i32 s11, s9, 0x80000
	s_bfe_u32 s11, s11, 0x3000c
	s_add_i32 s11, s9, s11
	s_bfe_i32 s12, s11, 0x80000
	s_and_b32 s11, s11, 0xf8
	s_sub_i32 s9, s9, s11
	s_sext_i32_i8 s9, s9
	s_lshl_b32 s8, s8, 11
	s_lshl_b32 s9, s9, 8
	s_add_i32 s16, s9, s8
	s_mov_b32 s8, s16
	s_ashr_i32 s17, s16, 31
	v_writelane_b32 v254, s8, 31
	s_sext_i32_i16 s12, s12
	s_ashr_i32 s1, s12, 3
	v_writelane_b32 v254, s9, 32
	s_lshl_b64 s[8:9], s[16:17], 11
	v_writelane_b32 v254, s8, 33
	s_nop 1
	v_writelane_b32 v254, s9, 34
	s_lshl_b32 s8, s1, 8
	s_ashr_i32 s9, s8, 31
	v_writelane_b32 v254, s1, 35
	s_lshl_b64 s[8:9], s[8:9], 11
	v_writelane_b32 v254, s8, 36
	s_cmpk_lt_i32 s13, 0x480
	s_nop 0
	v_writelane_b32 v254, s9, 37
	s_cselect_b64 s[8:9], -1, 0
	s_add_i32 s10, s10, s5
	v_writelane_b32 v254, s8, 38
	s_mul_hi_i32 s5, s10, 0x2aaaaaab
	s_lshl_b64 s[6:7], s[6:7], 10
	v_writelane_b32 v254, s9, 39
	s_lshr_b32 s8, s5, 31
	s_ashr_i32 s5, s5, 2
	s_add_i32 s5, s5, s8
	s_mul_i32 s8, s5, 24
	s_sub_i32 s8, s10, s8
	s_bfe_i32 s9, s8, 0x80000
	s_bfe_u32 s9, s9, 0x3000c
	s_add_i32 s9, s8, s9
	s_bfe_i32 s10, s9, 0x80000
	s_and_b32 s9, s9, 0xf8
	s_sub_i32 s8, s8, s9
	s_sext_i32_i8 s8, s8
	s_lshl_b32 s5, s5, 11
	s_lshl_b32 s8, s8, 8
	s_sext_i32_i16 s10, s10
	s_add_i32 s16, s8, s5
	s_ashr_i32 s1, s10, 3
	s_mov_b32 s10, s16
	s_ashr_i32 s17, s16, 31
	v_writelane_b32 v254, s10, 40
	s_mul_i32 s8, s1, 0x18000
	s_ashr_i32 s9, s8, 31
	v_writelane_b32 v254, s11, 41
	s_lshl_b64 s[10:11], s[16:17], 11
	v_writelane_b32 v254, s10, 42
	s_nop 1
	v_writelane_b32 v254, s11, 43
	s_lshl_b32 s10, s1, 8
	s_ashr_i32 s11, s10, 31
	v_writelane_b32 v254, s1, 44
	s_lshl_b64 s[10:11], s[10:11], 11
	v_writelane_b32 v254, s10, 45
	s_nop 1
	v_writelane_b32 v254, s11, 46
	s_mov_b32 s10, s14
	v_writelane_b32 v254, s10, 47
	s_nop 1
	v_writelane_b32 v254, s11, 48
	s_lshl_b64 s[10:11], s[14:15], 10
	v_writelane_b32 v254, s10, 49
	s_add_u32 s4, s52, s4
	s_addc_u32 s5, s53, 0
	v_writelane_b32 v254, s11, 50
	v_writelane_b32 v254, s6, 51
	s_add_u32 s4, s4, 0x3e622000
	s_addc_u32 s5, s5, 0
	v_writelane_b32 v254, s7, 52
	v_writelane_b32 v254, s4, 53
	s_add_u32 s10, s52, 0x3e623000
	s_addc_u32 s11, s53, 0
	v_writelane_b32 v254, s5, 54
	s_lshl_b64 s[2:3], s[2:3], 1
	v_writelane_b32 v254, s2, 55
	s_ashr_i32 s1, s0, 31
	s_add_i32 s35, 0, 0x12000
	v_writelane_b32 v254, s3, 56
	s_lshl_b64 s[2:3], s[8:9], 1
	v_writelane_b32 v254, s2, 57
	s_nop 1
	v_writelane_b32 v254, s3, 58
	s_lshl_b32 s2, s13, 11
	v_writelane_b32 v254, s2, 59
	s_mov_b64 s[2:3], s[0:1]
	s_add_i32 s0, 0, 0x24000
	v_writelane_b32 v254, s0, 60
	s_mov_b32 s0, s2
	v_writelane_b32 v254, s0, 61
	s_lshl_b64 s[8:9], s[2:3], 9
	s_nop 0
	v_writelane_b32 v254, s1, 62
	v_writelane_b32 v254, s10, 63
	s_nop 1
	v_writelane_b32 v255, s11, 0
	v_writelane_b32 v255, s8, 1
	s_nop 1
	v_writelane_b32 v255, s9, 2
	s_branch .LBB0_150
.Ltramp_exit:
	s_endpgm
.LBB0_147:
	buffer_inv sc1
	s_waitcnt vmcnt(0)

; template <int EPI, bool RS>
; DI void gemm_phase(unsigned char* smem, const bf16_t* __restrict__ A, int lda, const bf16_t* __restrict__ Bt, int K, int mt0, int nMt, int nNt, const EpiArgs& ea) {
;     ...
;     f32x16 acc[2][4];
; #pragma unroll
;     for (int a = 0; a < 2; ++a)
; #pragma unroll
;       for (int b = 0; b < 4; ++b)
; #pragma unroll
;         for (int i = 0; i < 16; ++i) acc[a][b][i] = 0.f;
;     float ssq[4] = {0.f, 0.f, 0.f, 0.f};
.LBB0_324:
	s_ashr_i32 s47, s46, 31
	s_lshl_b32 s0, s33, 8
	s_ashr_i32 s1, s0, 31
	s_lshl_b64 s[6:7], s[46:47], 11
	s_add_u32 s48, s62, s6
	s_addc_u32 s49, s63, s7
	s_lshl_b64 s[0:1], s[0:1], 11
	s_add_u32 s52, s50, s0
	v_mov_b32_e32 v227, 0
	s_addc_u32 s53, s59, s1
	s_mov_b32 s6, -2
	v_mov_b32_e32 v226, 0
	v_mov_b32_e32 v225, 0
	v_mov_b32_e32 v224, v227
	v_mov_b32_e32 v0, 0
	v_mov_b32_e32 v1, v227
	v_mov_b32_e32 v2, v227
	v_mov_b32_e32 v3, v227
	v_mov_b32_e32 v4, v227
	v_mov_b32_e32 v5, v227
	v_mov_b32_e32 v6, v227
	v_mov_b32_e32 v7, v227
	v_mov_b32_e32 v8, v227
	v_mov_b32_e32 v9, v227
	v_mov_b32_e32 v10, v227
	v_mov_b32_e32 v11, v227
	v_mov_b32_e32 v12, v227
	v_mov_b32_e32 v13, v227
	v_mov_b32_e32 v14, v227
	v_mov_b32_e32 v15, v227
	v_mov_b32_e32 v32, 0
	v_mov_b32_e32 v33, v227
	v_mov_b32_e32 v34, v227
	v_mov_b32_e32 v35, v227
	v_mov_b32_e32 v36, v227
	v_mov_b32_e32 v37, v227
	v_mov_b32_e32 v38, v227
	v_mov_b32_e32 v39, v227
	v_mov_b32_e32 v40, v227
	v_mov_b32_e32 v41, v227
	v_mov_b32_e32 v42, v227
	v_mov_b32_e32 v43, v227
	v_mov_b32_e32 v44, v227
	v_mov_b32_e32 v45, v227
	v_mov_b32_e32 v46, v227
	v_mov_b32_e32 v47, v227
	v_mov_b32_e32 v64, 0
	v_mov_b32_e32 v65, v227
	v_mov_b32_e32 v66, v227
	v_mov_b32_e32 v67, v227
	v_mov_b32_e32 v68, v227
	v_mov_b32_e32 v69, v227
	v_mov_b32_e32 v70, v227
	v_mov_b32_e32 v71, v227
	v_mov_b32_e32 v72, v227
	v_mov_b32_e32 v73, v227
	v_mov_b32_e32 v74, v227
	v_mov_b32_e32 v75, v227
	v_mov_b32_e32 v76, v227
	v_mov_b32_e32 v77, v227
	v_mov_b32_e32 v78, v227
	v_mov_b32_e32 v79, v227
	v_mov_b32_e32 v96, 0
	v_mov_b32_e32 v97, v227
	v_mov_b32_e32 v98, v227
	v_mov_b32_e32 v99, v227
	v_mov_b32_e32 v100, v227
	v_mov_b32_e32 v101, v227
	v_mov_b32_e32 v102, v227
	v_mov_b32_e32 v103, v227
	v_mov_b32_e32 v104, v227
	v_mov_b32_e32 v105, v227
	v_mov_b32_e32 v106, v227
	v_mov_b32_e32 v107, v227
	v_mov_b32_e32 v108, v227
	v_mov_b32_e32 v109, v227
	v_mov_b32_e32 v110, v227
	v_mov_b32_e32 v111, v227
	v_mov_b32_e32 v16, 0
	v_mov_b32_e32 v17, v227
	v_mov_b32_e32 v18, v227
	v_mov_b32_e32 v19, v227
	v_mov_b32_e32 v20, v227
	v_mov_b32_e32 v21, v227
	v_mov_b32_e32 v22, v227
	v_mov_b32_e32 v23, v227
	v_mov_b32_e32 v24, v227
	v_mov_b32_e32 v25, v227
	v_mov_b32_e32 v26, v227
	v_mov_b32_e32 v27, v227
	v_mov_b32_e32 v28, v227
	v_mov_b32_e32 v29, v227
	v_mov_b32_e32 v30, v227
	v_mov_b32_e32 v31, v227
	v_mov_b32_e32 v48, 0
	v_mov_b32_e32 v49, v227
	v_mov_b32_e32 v50, v227
	v_mov_b32_e32 v51, v227
	v_mov_b32_e32 v52, v227
	v_mov_b32_e32 v53, v227
	v_mov_b32_e32 v54, v227
	v_mov_b32_e32 v55, v227
	v_mov_b32_e32 v56, v227
	v_mov_b32_e32 v57, v227
	v_mov_b32_e32 v58, v227
	v_mov_b32_e32 v59, v227
	v_mov_b32_e32 v60, v227
	v_mov_b32_e32 v61, v227
	v_mov_b32_e32 v62, v227
	v_mov_b32_e32 v63, v227
	s_waitcnt vmcnt(9)
	v_mov_b32_e32 v80, 0
	v_mov_b32_e32 v81, v227
	v_mov_b32_e32 v82, v227
	v_mov_b32_e32 v83, v227
	v_mov_b32_e32 v84, v227
	v_mov_b32_e32 v85, v227
	v_mov_b32_e32 v86, v227
	v_mov_b32_e32 v87, v227
	v_mov_b32_e32 v88, v227
	v_mov_b32_e32 v89, v227
	v_mov_b32_e32 v90, v227
	v_mov_b32_e32 v91, v227
	v_mov_b32_e32 v92, v227
	v_mov_b32_e32 v93, v227
	v_mov_b32_e32 v94, v227
	v_mov_b32_e32 v95, v227
	s_waitcnt vmcnt(8)
	v_mov_b32_e32 v112, 0
	v_mov_b32_e32 v113, v227
	v_mov_b32_e32 v114, v227
	v_mov_b32_e32 v115, v227
	v_mov_b32_e32 v116, v227
	v_mov_b32_e32 v117, v227
	v_mov_b32_e32 v118, v227
	v_mov_b32_e32 v119, v227
	v_mov_b32_e32 v120, v227
	v_mov_b32_e32 v121, v227
	v_mov_b32_e32 v122, v227
	v_mov_b32_e32 v123, v227
	v_mov_b32_e32 v124, v227
	v_mov_b32_e32 v125, v227
	v_mov_b32_e32 v126, v227
	v_mov_b32_e32 v127, v227
	v_readfirstlane_b32 s100, v219
	s_nop 3
	s_bfe_u32 s100, s100, 0x20006
.LBB0_325:
	s_add_i32 s7, s6, 2
	s_cmp_lt_u32 s7, 13
	s_cselect_b64 s[0:1], -1, 0
	s_and_b64 s[10:11], s[0:1], exec
	s_cselect_b32 s10, 0, -16
	s_add_i32 s10, s10, s6
	s_waitcnt lgkmcnt(3)
	v_mfma_f32_32x32x16_bf16 v[112:127], v[192:195], v[200:203], v[112:127]
	s_lshl_b32 s12, s10, 7
	s_and_b64 s[10:11], s[0:1], exec
	s_cselect_b32 s11, s3, s49
	s_cselect_b32 s10, s2, s48
	s_addk_i32 s12, 0x280
	s_add_u32 s10, s10, s12
	s_addc_u32 s11, s11, 0
	v_mfma_f32_32x32x16_bf16 v[96:111], v[196:199], v[200:203], v[96:111]
	s_waitcnt lgkmcnt(2)
	s_waitcnt lgkmcnt(1)
	s_waitcnt lgkmcnt(0)
	s_and_b64 s[0:1], s[0:1], exec
	v_mfma_f32_32x32x16_bf16 v[80:95], v[192:195], v[212:215], v[80:95]
	s_cselect_b32 s0, s4, s52
	v_mfma_f32_32x32x16_bf16 v[64:79], v[196:199], v[212:215], v[64:79]
	s_cselect_b32 s1, s5, s53
	s_add_u32 s0, s0, s12
	s_addc_u32 s1, s1, 0
	s_cmp_eq_u32 s100, 0
	s_cbranch_scc0 .Lddp1_skip0
	v_dot2c_f32_bf16_e32 v227, v200, v200
	v_dot2c_f32_bf16_e32 v226, v212, v212
	v_dot2c_f32_bf16_e32 v225, v208, v208
	v_dot2c_f32_bf16_e32 v224, v204, v204
	v_dot2c_f32_bf16_e32 v227, v201, v201
	v_dot2c_f32_bf16_e32 v226, v213, v213
	v_dot2c_f32_bf16_e32 v225, v209, v209
	v_dot2c_f32_bf16_e32 v224, v205, v205
	v_dot2c_f32_bf16_e32 v227, v202, v202
	v_dot2c_f32_bf16_e32 v226, v214, v214
	v_dot2c_f32_bf16_e32 v225, v210, v210
	v_dot2c_f32_bf16_e32 v224, v206, v206
	v_dot2c_f32_bf16_e32 v227, v203, v203
	v_dot2c_f32_bf16_e32 v226, v215, v215
	v_dot2c_f32_bf16_e32 v225, v211, v211
	v_dot2c_f32_bf16_e32 v224, v207, v207
.Lddp1_skip0:
	v_mfma_f32_32x32x16_bf16 v[48:63], v[192:195], v[208:211], v[48:63]
	v_mfma_f32_32x32x16_bf16 v[32:47], v[196:199], v[208:211], v[32:47]
	v_mfma_f32_32x32x16_bf16 v[16:31], v[192:195], v[204:207], v[16:31]
	v_mfma_f32_32x32x16_bf16 v[0:15], v[196:199], v[204:207], v[0:15]
	v_add_u32_e32 v231, s35, v220
	v_lshl_add_u64 v[232:233], s[10:11], 0, v[216:217]
	s_waitcnt vmcnt(7)
	ds_write_b128 v231, v[132:135]
	s_waitcnt vmcnt(6)
	ds_write_b128 v231, v[128:131] offset:36864
	v_lshl_add_u64 v[234:235], s[0:1], 0, v[216:217]
	global_load_dwordx4 v[132:135], v[232:233], off
	global_load_dwordx4 v[128:131], v[234:235], off
	s_waitcnt vmcnt(7)
	ds_write_b128 v231, v[152:155] offset:9216
	s_waitcnt vmcnt(6)
	ds_write_b128 v231, v[148:151] offset:46080
	v_add_co_u32_e32 v148, vcc, s42, v232
	s_nop 1
	v_addc_co_u32_e32 v149, vcc, 0, v233, vcc
	v_add_co_u32_e32 v150, vcc, s42, v234
	s_nop 1
	v_addc_co_u32_e32 v151, vcc, 0, v235, vcc
	global_load_dwordx4 v[152:155], v[148:149], off
	s_nop 0
	global_load_dwordx4 v[148:151], v[150:151], off
	ds_read_b128 v[192:195], v229 offset:36896
	ds_read_b128 v[196:199], v229 offset:41504
	ds_read_b128 v[200:203], v230 offset:32
	ds_read_b128 v[204:207], v230 offset:4640
	ds_read_b128 v[208:211], v230 offset:9248
	ds_read_b128 v[212:215], v230 offset:13856
	s_waitcnt lgkmcnt(3)
	v_mfma_f32_32x32x16_bf16 v[112:127], v[192:195], v[200:203], v[112:127]
	s_waitcnt lgkmcnt(2)
	s_waitcnt lgkmcnt(1)
	s_waitcnt lgkmcnt(0)
	v_mfma_f32_32x32x16_bf16 v[96:111], v[196:199], v[200:203], v[96:111]
	v_mfma_f32_32x32x16_bf16 v[80:95], v[192:195], v[204:207], v[80:95]
	s_cmp_eq_u32 s100, 1
	s_cbranch_scc0 .Lddp1_skip1
	v_dot2c_f32_bf16_e32 v227, v200, v200
	v_dot2c_f32_bf16_e32 v226, v204, v204
	v_dot2c_f32_bf16_e32 v225, v208, v208
	v_dot2c_f32_bf16_e32 v224, v212, v212
	v_dot2c_f32_bf16_e32 v227, v201, v201
	v_dot2c_f32_bf16_e32 v226, v205, v205
	v_dot2c_f32_bf16_e32 v225, v209, v209
	v_dot2c_f32_bf16_e32 v224, v213, v213
	v_dot2c_f32_bf16_e32 v227, v202, v202
	v_dot2c_f32_bf16_e32 v226, v206, v206
	v_dot2c_f32_bf16_e32 v225, v210, v210
	v_dot2c_f32_bf16_e32 v224, v214, v214
	v_dot2c_f32_bf16_e32 v227, v203, v203
	v_dot2c_f32_bf16_e32 v226, v207, v207
	v_dot2c_f32_bf16_e32 v225, v211, v211
	v_dot2c_f32_bf16_e32 v224, v215, v215
.Lddp1_skip1:
	v_mfma_f32_32x32x16_bf16 v[64:79], v[196:199], v[204:207], v[64:79]
	v_mfma_f32_32x32x16_bf16 v[48:63], v[192:195], v[208:211], v[48:63]
	v_mfma_f32_32x32x16_bf16 v[32:47], v[196:199], v[208:211], v[32:47]
	v_mfma_f32_32x32x16_bf16 v[16:31], v[192:195], v[212:215], v[16:31]
	v_mfma_f32_32x32x16_bf16 v[0:15], v[196:199], v[212:215], v[0:15]
	s_waitcnt vmcnt(7)
	ds_write_b128 v231, v[136:139] offset:18432
	s_waitcnt vmcnt(6)
	ds_write_b128 v231, v[144:147] offset:55296
	v_add_co_u32_e32 v136, vcc, s43, v232
	s_nop 1
	v_addc_co_u32_e32 v137, vcc, 0, v233, vcc
	v_add_co_u32_e32 v144, vcc, s43, v234
	global_load_dwordx4 v[136:139], v[136:137], off
	s_nop 0
	v_addc_co_u32_e32 v145, vcc, 0, v235, vcc
	global_load_dwordx4 v[144:147], v[144:145], off
	s_waitcnt vmcnt(7)
	ds_write_b128 v231, v[140:143] offset:27648
	s_waitcnt vmcnt(6)
	ds_write_b128 v231, v[156:159] offset:64512
	v_add_co_u32_e32 v140, vcc, s75, v232
	s_nop 1
	v_addc_co_u32_e32 v141, vcc, 0, v233, vcc
	v_add_co_u32_e32 v156, vcc, s75, v234
	global_load_dwordx4 v[140:143], v[140:141], off
	s_nop 0
	v_addc_co_u32_e32 v157, vcc, 0, v235, vcc
	global_load_dwordx4 v[156:159], v[156:157], off
	ds_read_b128 v[192:195], v229 offset:36928
	ds_read_b128 v[196:199], v229 offset:41536
	ds_read_b128 v[200:203], v230 offset:64
	ds_read_b128 v[204:207], v230 offset:4672
	ds_read_b128 v[208:211], v230 offset:9280
	ds_read_b128 v[212:215], v230 offset:13888
	s_waitcnt lgkmcnt(3)
	v_mfma_f32_32x32x16_bf16 v[112:127], v[192:195], v[200:203], v[112:127]
	s_waitcnt lgkmcnt(2)
	s_waitcnt lgkmcnt(1)
	s_waitcnt lgkmcnt(0)
	v_mfma_f32_32x32x16_bf16 v[96:111], v[196:199], v[200:203], v[96:111]
	v_mfma_f32_32x32x16_bf16 v[80:95], v[192:195], v[204:207], v[80:95]
	s_cmp_eq_u32 s100, 2
	s_cbranch_scc0 .Lddp1_skip2
	v_dot2c_f32_bf16_e32 v227, v200, v200
	v_dot2c_f32_bf16_e32 v226, v204, v204
	v_dot2c_f32_bf16_e32 v225, v208, v208
	v_dot2c_f32_bf16_e32 v224, v212, v212
	v_dot2c_f32_bf16_e32 v227, v201, v201
	v_dot2c_f32_bf16_e32 v226, v205, v205
	v_dot2c_f32_bf16_e32 v225, v209, v209
	v_dot2c_f32_bf16_e32 v224, v213, v213
	v_dot2c_f32_bf16_e32 v227, v202, v202
	v_dot2c_f32_bf16_e32 v226, v206, v206
	v_dot2c_f32_bf16_e32 v225, v210, v210
	v_dot2c_f32_bf16_e32 v224, v214, v214
	v_dot2c_f32_bf16_e32 v227, v203, v203
	v_dot2c_f32_bf16_e32 v226, v207, v207
	v_dot2c_f32_bf16_e32 v225, v211, v211
	v_dot2c_f32_bf16_e32 v224, v215, v215
.Lddp1_skip2:
	v_mfma_f32_32x32x16_bf16 v[64:79], v[196:199], v[204:207], v[64:79]
	v_mfma_f32_32x32x16_bf16 v[48:63], v[192:195], v[208:211], v[48:63]
	v_mfma_f32_32x32x16_bf16 v[32:47], v[196:199], v[208:211], v[32:47]
	v_mfma_f32_32x32x16_bf16 v[16:31], v[192:195], v[212:215], v[16:31]
	v_mfma_f32_32x32x16_bf16 v[0:15], v[196:199], v[212:215], v[0:15]
	ds_read_b128 v[192:195], v229 offset:36960
	ds_read_b128 v[196:199], v229 offset:41568
	ds_read_b128 v[200:203], v230 offset:96
	ds_read_b128 v[204:207], v230 offset:4704
	ds_read_b128 v[208:211], v230 offset:9312
	ds_read_b128 v[212:215], v230 offset:13920
	s_waitcnt lgkmcnt(3)
	v_mfma_f32_32x32x16_bf16 v[112:127], v[192:195], v[200:203], v[112:127]
	s_waitcnt lgkmcnt(2)
	s_waitcnt lgkmcnt(1)
	s_waitcnt lgkmcnt(0)
	v_mfma_f32_32x32x16_bf16 v[96:111], v[196:199], v[200:203], v[96:111]
	v_mfma_f32_32x32x16_bf16 v[80:95], v[192:195], v[204:207], v[80:95]
	s_cmp_eq_u32 s100, 3
	s_cbranch_scc0 .Lddp1_skip3
	v_dot2c_f32_bf16_e32 v227, v200, v200
	v_dot2c_f32_bf16_e32 v226, v204, v204
	v_dot2c_f32_bf16_e32 v225, v208, v208
	v_dot2c_f32_bf16_e32 v224, v212, v212
	v_dot2c_f32_bf16_e32 v227, v201, v201
	v_dot2c_f32_bf16_e32 v226, v205, v205
	v_dot2c_f32_bf16_e32 v225, v209, v209
	v_dot2c_f32_bf16_e32 v224, v213, v213
	v_dot2c_f32_bf16_e32 v227, v202, v202
	v_dot2c_f32_bf16_e32 v226, v206, v206
	v_dot2c_f32_bf16_e32 v225, v210, v210
	v_dot2c_f32_bf16_e32 v224, v214, v214
	v_dot2c_f32_bf16_e32 v227, v203, v203
	v_dot2c_f32_bf16_e32 v226, v207, v207
	v_dot2c_f32_bf16_e32 v225, v211, v211
	v_dot2c_f32_bf16_e32 v224, v215, v215
.Lddp1_skip3:
	s_barrier
	v_mfma_f32_32x32x16_bf16 v[64:79], v[196:199], v[204:207], v[64:79]
	v_mfma_f32_32x32x16_bf16 v[48:63], v[192:195], v[208:211], v[48:63]
	v_mfma_f32_32x32x16_bf16 v[32:47], v[196:199], v[208:211], v[32:47]
	v_mfma_f32_32x32x16_bf16 v[16:31], v[192:195], v[212:215], v[16:31]
	v_mfma_f32_32x32x16_bf16 v[0:15], v[196:199], v[212:215], v[0:15]
	v_add_u32_e32 v231, s35, v222
	ds_read_b128 v[192:195], v239
	ds_read_b128 v[196:199], v239 offset:4608
	ds_read_b128 v[200:203], v231
	ds_read_b128 v[204:207], v231 offset:4608
	ds_read_b128 v[208:211], v231 offset:9216
	ds_read_b128 v[212:215], v231 offset:13824
	s_cmp_lt_u32 s7, 12
	s_cselect_b64 s[0:1], -1, 0
	s_and_b64 s[10:11], s[0:1], exec
	s_cselect_b32 s10, 0, -16
	s_add_i32 s10, s10, s6
	s_waitcnt lgkmcnt(3)
	v_mfma_f32_32x32x16_bf16 v[112:127], v[192:195], v[200:203], v[112:127]
	s_lshl_b32 s6, s10, 7
	s_and_b64 s[10:11], s[0:1], exec
	s_cselect_b32 s11, s3, s49
	s_cselect_b32 s10, s2, s48
	s_addk_i32 s6, 0x300
	s_add_u32 s10, s10, s6
	s_addc_u32 s11, s11, 0
	v_mfma_f32_32x32x16_bf16 v[96:111], v[196:199], v[200:203], v[96:111]
	s_waitcnt lgkmcnt(2)
	s_waitcnt lgkmcnt(1)
	s_waitcnt lgkmcnt(0)
	s_and_b64 s[0:1], s[0:1], exec
	v_mfma_f32_32x32x16_bf16 v[80:95], v[192:195], v[204:207], v[80:95]
	s_cselect_b32 s0, s4, s52
	v_mfma_f32_32x32x16_bf16 v[64:79], v[196:199], v[204:207], v[64:79]
	s_cselect_b32 s1, s5, s53
	s_add_u32 s0, s0, s6
	s_addc_u32 s1, s1, 0
	s_cmp_eq_u32 s100, 0
	s_cbranch_scc0 .Lddp1_skip4
	v_dot2c_f32_bf16_e32 v227, v200, v200
	v_dot2c_f32_bf16_e32 v226, v204, v204
	v_dot2c_f32_bf16_e32 v225, v208, v208
	v_dot2c_f32_bf16_e32 v224, v212, v212
	v_dot2c_f32_bf16_e32 v227, v201, v201
	v_dot2c_f32_bf16_e32 v226, v205, v205
	v_dot2c_f32_bf16_e32 v225, v209, v209
	v_dot2c_f32_bf16_e32 v224, v213, v213
	v_dot2c_f32_bf16_e32 v227, v202, v202
	v_dot2c_f32_bf16_e32 v226, v206, v206
	v_dot2c_f32_bf16_e32 v225, v210, v210
	v_dot2c_f32_bf16_e32 v224, v214, v214
	v_dot2c_f32_bf16_e32 v227, v203, v203
	v_dot2c_f32_bf16_e32 v226, v207, v207
	v_dot2c_f32_bf16_e32 v225, v211, v211
	v_dot2c_f32_bf16_e32 v224, v215, v215
.Lddp1_skip4:
	v_mfma_f32_32x32x16_bf16 v[48:63], v[192:195], v[208:211], v[48:63]
	v_mfma_f32_32x32x16_bf16 v[32:47], v[196:199], v[208:211], v[32:47]
	v_mfma_f32_32x32x16_bf16 v[16:31], v[192:195], v[212:215], v[16:31]
	v_mfma_f32_32x32x16_bf16 v[0:15], v[196:199], v[212:215], v[0:15]
	v_lshl_add_u64 v[232:233], s[10:11], 0, v[216:217]
	s_waitcnt vmcnt(8)
	ds_write_b128 v228, v[172:175]
	ds_write_b128 v228, v[160:163] offset:36864
	ds_write_b128 v228, v[184:187] offset:9216
	ds_write_b128 v228, v[180:183] offset:46080
	v_add_co_u32_e32 v180, vcc, s42, v232
	v_lshl_add_u64 v[234:235], s[0:1], 0, v[216:217]
	s_nop 0
	v_addc_co_u32_e32 v181, vcc, 0, v233, vcc
	v_add_co_u32_e32 v182, vcc, s42, v234
	global_load_dwordx4 v[172:175], v[232:233], off
	global_load_dwordx4 v[160:163], v[234:235], off
	v_addc_co_u32_e32 v183, vcc, 0, v235, vcc
	global_load_dwordx4 v[184:187], v[180:181], off
	s_nop 0
	global_load_dwordx4 v[180:183], v[182:183], off
	ds_read_b128 v[192:195], v239 offset:32
	ds_read_b128 v[196:199], v239 offset:4640
	ds_read_b128 v[200:203], v231 offset:32
	ds_read_b128 v[204:207], v231 offset:4640
	ds_read_b128 v[208:211], v231 offset:9248
	ds_read_b128 v[212:215], v231 offset:13856
	s_waitcnt lgkmcnt(3)
	v_mfma_f32_32x32x16_bf16 v[112:127], v[192:195], v[200:203], v[112:127]
	s_waitcnt lgkmcnt(2)
	s_waitcnt lgkmcnt(1)
	s_waitcnt lgkmcnt(0)
	v_mfma_f32_32x32x16_bf16 v[96:111], v[196:199], v[200:203], v[96:111]
	v_mfma_f32_32x32x16_bf16 v[80:95], v[192:195], v[204:207], v[80:95]
	s_cmp_eq_u32 s100, 1
	s_cbranch_scc0 .Lddp1_skip5
	v_dot2c_f32_bf16_e32 v227, v200, v200
	v_dot2c_f32_bf16_e32 v226, v204, v204
	v_dot2c_f32_bf16_e32 v225, v208, v208
	v_dot2c_f32_bf16_e32 v224, v212, v212
	v_dot2c_f32_bf16_e32 v227, v201, v201
	v_dot2c_f32_bf16_e32 v226, v205, v205
	v_dot2c_f32_bf16_e32 v225, v209, v209
	v_dot2c_f32_bf16_e32 v224, v213, v213
	v_dot2c_f32_bf16_e32 v227, v202, v202
	v_dot2c_f32_bf16_e32 v226, v206, v206
	v_dot2c_f32_bf16_e32 v225, v210, v210
	v_dot2c_f32_bf16_e32 v224, v214, v214
	v_dot2c_f32_bf16_e32 v227, v203, v203
	v_dot2c_f32_bf16_e32 v226, v207, v207
	v_dot2c_f32_bf16_e32 v225, v211, v211
	v_dot2c_f32_bf16_e32 v224, v215, v215
.Lddp1_skip5:
	v_mfma_f32_32x32x16_bf16 v[64:79], v[196:199], v[204:207], v[64:79]
	v_mfma_f32_32x32x16_bf16 v[48:63], v[192:195], v[208:211], v[48:63]
	v_mfma_f32_32x32x16_bf16 v[32:47], v[196:199], v[208:211], v[32:47]
	v_mfma_f32_32x32x16_bf16 v[16:31], v[192:195], v[212:215], v[16:31]
	v_mfma_f32_32x32x16_bf16 v[0:15], v[196:199], v[212:215], v[0:15]
	ds_write_b128 v228, v[164:167] offset:18432
	ds_write_b128 v228, v[176:179] offset:55296
	v_add_co_u32_e32 v164, vcc, s43, v232
	s_nop 1
	v_addc_co_u32_e32 v165, vcc, 0, v233, vcc
	v_add_co_u32_e32 v176, vcc, s43, v234
	global_load_dwordx4 v[164:167], v[164:165], off
	s_nop 0
	v_addc_co_u32_e32 v177, vcc, 0, v235, vcc
	global_load_dwordx4 v[176:179], v[176:177], off
	ds_write_b128 v228, v[168:171] offset:27648
	ds_write_b128 v228, v[188:191] offset:64512
	v_add_co_u32_e32 v168, vcc, s75, v232
	s_nop 1
	v_addc_co_u32_e32 v169, vcc, 0, v233, vcc
	v_add_co_u32_e32 v188, vcc, s75, v234
	global_load_dwordx4 v[168:171], v[168:169], off
	s_nop 0
	v_addc_co_u32_e32 v189, vcc, 0, v235, vcc
	global_load_dwordx4 v[188:191], v[188:189], off
	ds_read_b128 v[192:195], v239 offset:64
	ds_read_b128 v[196:199], v239 offset:4672
	ds_read_b128 v[200:203], v231 offset:64
	ds_read_b128 v[204:207], v231 offset:4672
	ds_read_b128 v[208:211], v231 offset:9280
	ds_read_b128 v[212:215], v231 offset:13888
	s_waitcnt lgkmcnt(3)
	v_mfma_f32_32x32x16_bf16 v[112:127], v[192:195], v[200:203], v[112:127]
	s_waitcnt lgkmcnt(2)
	s_waitcnt lgkmcnt(1)
	s_waitcnt lgkmcnt(0)
	v_mfma_f32_32x32x16_bf16 v[96:111], v[196:199], v[200:203], v[96:111]
	v_mfma_f32_32x32x16_bf16 v[80:95], v[192:195], v[204:207], v[80:95]
	s_cmp_eq_u32 s100, 2
	s_cbranch_scc0 .Lddp1_skip6
	v_dot2c_f32_bf16_e32 v227, v200, v200
	v_dot2c_f32_bf16_e32 v226, v204, v204
	v_dot2c_f32_bf16_e32 v225, v208, v208
	v_dot2c_f32_bf16_e32 v224, v212, v212
	v_dot2c_f32_bf16_e32 v227, v201, v201
	v_dot2c_f32_bf16_e32 v226, v205, v205
	v_dot2c_f32_bf16_e32 v225, v209, v209
	v_dot2c_f32_bf16_e32 v224, v213, v213
	v_dot2c_f32_bf16_e32 v227, v202, v202
	v_dot2c_f32_bf16_e32 v226, v206, v206
	v_dot2c_f32_bf16_e32 v225, v210, v210
	v_dot2c_f32_bf16_e32 v224, v214, v214
	v_dot2c_f32_bf16_e32 v227, v203, v203
	v_dot2c_f32_bf16_e32 v226, v207, v207
	v_dot2c_f32_bf16_e32 v225, v211, v211
	v_dot2c_f32_bf16_e32 v224, v215, v215
; #define G_ITER(R, kt_) do { const int k3 = (kt_) + 3; \
;         const char* pa = k3 < nk ? ga + k3 * 128 : ga_n + (k3 - nk) * 128; const char* pb = k3 < nk ? gb + k3 * 128 : gb_n + (k3 - nk) * 128; \
;         G_BODY(R, kt_, pa, pb); } while (0)
; template <int EPI, bool RS>
; DI void gemm_epilogue(unsigned char* smem, f32x16 (&acc)[2][4], const float (&ssq)[4], int K, int m0, int nt256, const EpiArgs& ea, int wt, int wf, int r, int h) {
;     ...
;   if (RS) {
; #pragma unroll
;     for (int tb = 0; tb < 4; ++tb) { float s = ssq[tb]; s += __shfl_xor(s, 32); rstd[tb] = rsqrtf(s / (float)K + EPS); }
;   }
;   if (EPI == EPI_PLAIN) {
; #pragma unroll
;     for (int tb = 0; tb < 4; ++tb) {
;       const int tok = m0 + wt * 128 + tb * 32 + r; const float rs = rstd[tb];
;       bf16_t* rowp = ea.o0 + (size_t)tok * ea.ldc;
; #pragma unroll
;       for (int fb = 0; fb < 2; ++fb)
; #pragma unroll
;         for (int g4 = 0; g4 < 4; ++g4) {
;           const int col = n0 + wc * 64 + fb * 32 + g4 * 8 + 4 * h;
;           if (col < ea.nvalid && !ea.nostore) { u32x2 w; w[0] = pk2(acc[fb][tb][4 * g4] * rs, acc[fb][tb][4 * g4 + 1] * rs); w[1] = pk2(acc[fb][tb][4 * g4 + 2] * rs, acc[fb][tb][4 * g4 + 3] * rs); *(u32x2*)(rowp + col) = w; }
; template <int EPI, bool RS>
; DI void gemm_phase(unsigned char* smem, const bf16_t* __restrict__ A, int lda, const bf16_t* __restrict__ Bt, int K, int mt0, int nMt, int nNt, const EpiArgs& ea) {
;     ...
;     if (DEEP) {
;     ...
;       for (int kt = 0; kt < nk; kt += 2) { G_ITER(rg, kt); G_ITER(rh, kt + 1); }
.Lddp1_skip6:
	v_mfma_f32_32x32x16_bf16 v[64:79], v[196:199], v[204:207], v[64:79]
	v_mfma_f32_32x32x16_bf16 v[48:63], v[192:195], v[208:211], v[48:63]
	v_mfma_f32_32x32x16_bf16 v[32:47], v[196:199], v[208:211], v[32:47]
	v_mfma_f32_32x32x16_bf16 v[16:31], v[192:195], v[212:215], v[16:31]
	v_mfma_f32_32x32x16_bf16 v[0:15], v[196:199], v[212:215], v[0:15]
	ds_read_b128 v[192:195], v239 offset:96
	ds_read_b128 v[196:199], v239 offset:4704
	ds_read_b128 v[200:203], v231 offset:96
	ds_read_b128 v[204:207], v231 offset:4704
	ds_read_b128 v[208:211], v231 offset:9312
	ds_read_b128 v[212:215], v231 offset:13920
	s_waitcnt lgkmcnt(3)
	v_mfma_f32_32x32x16_bf16 v[112:127], v[192:195], v[200:203], v[112:127]
	s_waitcnt lgkmcnt(2)
	s_waitcnt lgkmcnt(1)
	s_waitcnt lgkmcnt(0)
	v_mfma_f32_32x32x16_bf16 v[96:111], v[196:199], v[200:203], v[96:111]
	v_mfma_f32_32x32x16_bf16 v[80:95], v[192:195], v[204:207], v[80:95]
	s_cmp_eq_u32 s100, 3
	s_cbranch_scc0 .Lddp1_skip7
	v_dot2c_f32_bf16_e32 v227, v200, v200
	v_dot2c_f32_bf16_e32 v226, v204, v204
	v_dot2c_f32_bf16_e32 v225, v208, v208
	v_dot2c_f32_bf16_e32 v224, v212, v212
	v_dot2c_f32_bf16_e32 v227, v201, v201
	v_dot2c_f32_bf16_e32 v226, v205, v205
	v_dot2c_f32_bf16_e32 v225, v209, v209
	v_dot2c_f32_bf16_e32 v224, v213, v213
	v_dot2c_f32_bf16_e32 v227, v202, v202
	v_dot2c_f32_bf16_e32 v226, v206, v206
	v_dot2c_f32_bf16_e32 v225, v210, v210
	v_dot2c_f32_bf16_e32 v224, v214, v214
	v_dot2c_f32_bf16_e32 v227, v203, v203
	v_dot2c_f32_bf16_e32 v226, v207, v207
	v_dot2c_f32_bf16_e32 v225, v211, v211
	v_dot2c_f32_bf16_e32 v224, v215, v215
.Lddp1_skip7:
	s_barrier
	v_mfma_f32_32x32x16_bf16 v[64:79], v[196:199], v[204:207], v[64:79]
	v_mfma_f32_32x32x16_bf16 v[48:63], v[192:195], v[208:211], v[48:63]
	v_mfma_f32_32x32x16_bf16 v[32:47], v[196:199], v[208:211], v[32:47]
	v_mfma_f32_32x32x16_bf16 v[16:31], v[192:195], v[212:215], v[16:31]
	v_mfma_f32_32x32x16_bf16 v[0:15], v[196:199], v[212:215], v[0:15]
	ds_read_b128 v[192:195], v229 offset:36864
	ds_read_b128 v[196:199], v229 offset:41472
	ds_read_b128 v[200:203], v230
	ds_read_b128 v[212:215], v230 offset:4608
	ds_read_b128 v[208:211], v230 offset:9216
	ds_read_b128 v[204:207], v230 offset:13824
	s_cmp_gt_u32 s7, 13
	s_mov_b32 s6, s7
	s_cbranch_scc0 .LBB0_325
	v_lshlrev_b32_e32 v242, 2, v219
	v_add_u32_e32 v242, 0x24010, v242
	ds_write_b32 v242, v227
	ds_write_b32 v242, v226 offset:2048
	ds_write_b32 v242, v225 offset:4096
	ds_write_b32 v242, v224 offset:6144
	v_and_b32_e32 v243, 0x13f, v219
	v_lshlrev_b32_e32 v243, 2, v243
	v_add_u32_e32 v243, 0x24010, v243
	s_waitcnt lgkmcnt(0)
	s_barrier
	ds_read_b32 v244, v243
	ds_read_b32 v245, v243 offset:256
	ds_read_b32 v248, v243 offset:512
	ds_read_b32 v249, v243 offset:768
	s_waitcnt lgkmcnt(0)
	v_add_f32_e32 v227, v244, v245
	v_add_f32_e32 v227, v227, v248
	v_add_f32_e32 v227, v227, v249
	ds_read_b32 v244, v243 offset:2048
	ds_read_b32 v245, v243 offset:2304
	ds_read_b32 v248, v243 offset:2560
	ds_read_b32 v249, v243 offset:2816
	s_waitcnt lgkmcnt(0)
	v_add_f32_e32 v226, v244, v245
	v_add_f32_e32 v226, v226, v248
	v_add_f32_e32 v226, v226, v249
	ds_read_b32 v244, v243 offset:4096
	ds_read_b32 v245, v243 offset:4352
	ds_read_b32 v248, v243 offset:4608
	ds_read_b32 v249, v243 offset:4864
	s_waitcnt lgkmcnt(0)
	v_add_f32_e32 v225, v244, v245
	v_add_f32_e32 v225, v225, v248
	v_add_f32_e32 v225, v225, v249
	ds_read_b32 v244, v243 offset:6144
	ds_read_b32 v245, v243 offset:6400
	ds_read_b32 v248, v243 offset:6656
	ds_read_b32 v249, v243 offset:6912
	s_waitcnt lgkmcnt(0)
	v_add_f32_e32 v224, v244, v245
	v_add_f32_e32 v224, v224, v248
	v_add_f32_e32 v224, v224, v249
	v_and_b32_e32 v229, 64, v253
	v_xor_b32_e32 v228, 32, v253
	v_add_u32_e32 v229, 64, v229
	v_cmp_lt_i32_e32 vcc, v228, v229
	v_mov_b32_e32 v234, v237
	s_movk_i32 s0, 0x400
	v_cndmask_b32_e32 v228, v253, v228, vcc
	v_lshlrev_b32_e32 v230, 2, v228
	ds_bpermute_b32 v229, v230, v227
	ds_bpermute_b32 v228, v230, v226
	ds_bpermute_b32 v231, v230, v225
	ds_bpermute_b32 v230, v230, v224
	s_waitcnt lgkmcnt(2)
	v_pk_add_f32 v[226:227], v[226:227], v[228:229]
	s_nop 0
	v_pk_fma_f32 v[232:233], v[226:227], s[76:77], v[246:247] op_sel_hi:[1,0,0]
	v_mov_b32_e32 v227, v238
	v_mul_f32_e32 v226, 0x4b800000, v233
	v_cmp_gt_f32_e32 vcc, s67, v233
	v_cmp_gt_f32_e64 s[16:17], s67, v232
	s_nop 0
	v_cndmask_b32_e32 v226, v233, v226, vcc
	v_rsq_f32_e32 v226, v226
	s_nop 0
	v_mul_f32_e32 v228, 0x45800000, v226
	v_cndmask_b32_e32 v233, v226, v228, vcc
	v_add3_u32 v228, s9, v221, v234
	v_lshl_or_b32 v226, s8, 8, v236
	v_ashrrev_i32_e32 v229, 31, v228
	v_lshl_add_u32 v226, v227, 2, v226
	v_lshlrev_b64 v[234:235], 11, v[228:229]
	v_lshl_add_u64 v[234:235], s[68:69], 0, v[234:235]
	v_cmp_gt_i32_e32 vcc, s0, v226
	v_ashrrev_i32_e32 v227, 31, v226
	s_and_saveexec_b64 s[2:3], vcc
	s_cbranch_execz .LBB0_328
	v_mul_f32_e32 v112, v112, v233
	v_mul_f32_e32 v113, v113, v233
	v_cvt_pk_bf16_f32 v112, v112, v113
	v_mul_f32_e32 v113, v114, v233
	v_mul_f32_e32 v114, v115, v233
	v_cvt_pk_bf16_f32 v113, v113, v114
	v_lshl_add_u64 v[114:115], v[226:227], 1, v[234:235]
	global_store_dwordx2 v[114:115], v[112:113], off

; template <int KS, int NMAP, int EB, int NKB, int MODE>
; DI void attn_unit(unsigned char* smem, const AttnArgs& a, int t0, int head, int ehalf) {
;     ...
;   if (MODE == AT_DIFF) {
;     float ss = 0.f; const float l1 = a.lam * inv[NMAP - 1];
; #pragma unroll
;     for (int eb = 0; eb < EB; ++eb)
; #pragma unroll
;       for (int i = 0; i < 16; ++i) { const float v = oacc[0][eb][i] * inv[0] - oacc[NMAP - 1][eb][i] * l1; oacc[0][eb][i] = v; ss += v * v; }
;     ss += __shfl_xor(ss, 32);
;     const float rr = rsqrtf(ss * (1.0f / 128.0f) + EPS) * a.oscale;
; #pragma unroll
;     for (int eb = 0; eb < EB; ++eb)
; #pragma unroll
;       for (int g4 = 0; g4 < 4; ++g4) {
;         const int e = eb * 32 + g4 * 8 + 4 * h; const f32x4 g = *(const f32x4*)(a.g0 + e);
;         u32x2 w; w[0] = pk2(oacc[0][eb][4 * g4] * rr * g[0], oacc[0][eb][4 * g4 + 1] * rr * g[1]); w[1] = pk2(oacc[0][eb][4 * g4 + 2] * rr * g[2], oacc[0][eb][4 * g4 + 3] * rr * g[3]);
;         if (!a.nostore) *(u32x2*)(orow + e) = w;
;       }
.LBB0_413:
	global_load_dwordx4 v[22:25], v216, s[4:5]
	global_load_dwordx4 v[26:29], v216, s[4:5] offset:32
	global_load_dwordx4 v[42:45], v216, s[4:5] offset:64
	global_load_dwordx4 v[54:57], v216, s[4:5] offset:96
	global_load_dwordx4 v[58:61], v216, s[4:5] offset:128
	global_load_dwordx4 v[74:77], v216, s[4:5] offset:160
	global_load_dwordx4 v[86:89], v216, s[4:5] offset:192
	global_load_dwordx4 v[90:93], v216, s[4:5] offset:224
	global_load_dwordx4 v[106:109], v216, s[4:5] offset:256
	global_load_dwordx4 v[118:121], v216, s[4:5] offset:288
	global_load_dwordx4 v[122:125], v216, s[4:5] offset:320
	global_load_dwordx4 v[134:137], v216, s[4:5] offset:352
	global_load_dwordx4 v[138:141], v216, s[4:5] offset:384
	global_load_dwordx4 v[142:145], v216, s[4:5] offset:416
	global_load_dwordx4 v[146:149], v216, s[4:5] offset:448
	global_load_dwordx4 v[150:153], v216, s[4:5] offset:480
	s_waitcnt lgkmcnt(0)
	v_add_f32_e32 v8, v8, v9
	v_fmamk_f32 v8, v8, 0x3c000000, v246
	v_cmp_gt_f32_e32 vcc, s67, v8
	v_mul_f32_e32 v9, 0x4b800000, v8
	v_mov_b32_e32 v175, v217
	v_cndmask_b32_e32 v8, v8, v9, vcc
	v_rsq_f32_e32 v8, v8
	s_nop 0
	v_mul_f32_e32 v9, 0x45800000, v8
	v_cndmask_b32_e32 v8, v8, v9, vcc
	v_mul_f32_e32 v10, v189, v8
	v_pk_mul_f32 v[20:21], v[132:133], v[10:11] op_sel_hi:[1,0]
	v_lshl_add_u64 v[8:9], v[172:173], 0, v[174:175]
	v_pk_mul_f32 v[18:19], v[18:19], v[10:11] op_sel_hi:[1,0]
	v_pk_mul_f32 v[16:17], v[16:17], v[10:11] op_sel_hi:[1,0]
	v_pk_mul_f32 v[6:7], v[6:7], v[10:11] op_sel_hi:[1,0]
	v_pk_mul_f32 v[4:5], v[4:5], v[10:11] op_sel_hi:[1,0]
	v_pk_mul_f32 v[0:1], v[0:1], v[10:11] op_sel_hi:[1,0]
	s_waitcnt vmcnt(15)
	v_mov_b32_e32 v12, v22
	v_mov_b32_e32 v13, v23
	v_mov_b32_e32 v14, v24
	v_mov_b32_e32 v15, v25
	v_pk_mul_f32 v[12:13], v[20:21], v[12:13]
	v_pk_mul_f32 v[20:21], v[128:129], v[10:11] op_sel_hi:[1,0]
	v_cvt_pk_bf16_f32 v12, v12, v13
	v_pk_mul_f32 v[14:15], v[20:21], v[14:15]
	v_pk_mul_f32 v[20:21], v[116:117], v[10:11] op_sel_hi:[1,0]
	v_cvt_pk_bf16_f32 v13, v14, v15
	global_store_dwordx2 v[8:9], v[12:13], off
	s_waitcnt vmcnt(15)
	v_mov_b32_e32 v12, v26
	v_mov_b32_e32 v13, v27
	v_mov_b32_e32 v14, v28
	v_mov_b32_e32 v15, v29
	v_pk_mul_f32 v[12:13], v[20:21], v[12:13]
	v_pk_mul_f32 v[20:21], v[114:115], v[10:11] op_sel_hi:[1,0]
	v_cvt_pk_bf16_f32 v12, v12, v13
	v_pk_mul_f32 v[14:15], v[20:21], v[14:15]
	v_pk_mul_f32 v[20:21], v[112:113], v[10:11] op_sel_hi:[1,0]
	v_cvt_pk_bf16_f32 v13, v14, v15
	global_store_dwordx2 v[8:9], v[12:13], off offset:16
	s_waitcnt vmcnt(15)
	v_mov_b32_e32 v12, v42
	v_mov_b32_e32 v13, v43
	v_mov_b32_e32 v14, v44
	v_mov_b32_e32 v15, v45
	v_pk_mul_f32 v[12:13], v[20:21], v[12:13]
	v_pk_mul_f32 v[20:21], v[104:105], v[10:11] op_sel_hi:[1,0]
	v_cvt_pk_bf16_f32 v12, v12, v13
	v_pk_mul_f32 v[14:15], v[20:21], v[14:15]
	v_pk_mul_f32 v[20:21], v[102:103], v[10:11] op_sel_hi:[1,0]
	v_cvt_pk_bf16_f32 v13, v14, v15
	global_store_dwordx2 v[8:9], v[12:13], off offset:32
	s_waitcnt vmcnt(15)
	v_mov_b32_e32 v12, v54
	v_mov_b32_e32 v13, v55
	v_mov_b32_e32 v14, v56
	v_mov_b32_e32 v15, v57
	v_pk_mul_f32 v[12:13], v[20:21], v[12:13]
	v_pk_mul_f32 v[20:21], v[100:101], v[10:11] op_sel_hi:[1,0]
	v_cvt_pk_bf16_f32 v12, v12, v13
	v_pk_mul_f32 v[14:15], v[20:21], v[14:15]
	v_pk_mul_f32 v[20:21], v[98:99], v[10:11] op_sel_hi:[1,0]
	v_cvt_pk_bf16_f32 v13, v14, v15
	global_store_dwordx2 v[8:9], v[12:13], off offset:48
	s_waitcnt vmcnt(15)
	v_mov_b32_e32 v12, v58
	v_mov_b32_e32 v13, v59
	v_mov_b32_e32 v14, v60
	v_mov_b32_e32 v15, v61
	v_pk_mul_f32 v[12:13], v[20:21], v[12:13]
	v_pk_mul_f32 v[20:21], v[96:97], v[10:11] op_sel_hi:[1,0]
	v_cvt_pk_bf16_f32 v12, v12, v13
	v_pk_mul_f32 v[14:15], v[20:21], v[14:15]
	v_pk_mul_f32 v[20:21], v[84:85], v[10:11] op_sel_hi:[1,0]
	v_cvt_pk_bf16_f32 v13, v14, v15
	global_store_dwordx2 v[8:9], v[12:13], off offset:64
	s_waitcnt vmcnt(15)
	v_mov_b32_e32 v12, v74
	v_mov_b32_e32 v13, v75
	v_mov_b32_e32 v14, v76
	v_mov_b32_e32 v15, v77
	v_pk_mul_f32 v[12:13], v[20:21], v[12:13]
	v_pk_mul_f32 v[20:21], v[82:83], v[10:11] op_sel_hi:[1,0]
	v_cvt_pk_bf16_f32 v12, v12, v13
	v_pk_mul_f32 v[14:15], v[20:21], v[14:15]
	v_pk_mul_f32 v[20:21], v[80:81], v[10:11] op_sel_hi:[1,0]
	v_cvt_pk_bf16_f32 v13, v14, v15
	global_store_dwordx2 v[8:9], v[12:13], off offset:80
	s_waitcnt vmcnt(15)
; template <int KS, int NMAP, int EB, int NKB, int MODE>
; DI void attn_unit(unsigned char* smem, const AttnArgs& a, int t0, int head, int ehalf) {
;     ...
;   if (MODE == AT_DIFF) {
;     float ss = 0.f; const float l1 = a.lam * inv[NMAP - 1];
; #pragma unroll
;     for (int eb = 0; eb < EB; ++eb)
; #pragma unroll
;       for (int i = 0; i < 16; ++i) { const float v = oacc[0][eb][i] * inv[0] - oacc[NMAP - 1][eb][i] * l1; oacc[0][eb][i] = v; ss += v * v; }
;     ss += __shfl_xor(ss, 32);
;     const float rr = rsqrtf(ss * (1.0f / 128.0f) + EPS) * a.oscale;
; #pragma unroll
;     for (int eb = 0; eb < EB; ++eb)
; #pragma unroll
;       for (int g4 = 0; g4 < 4; ++g4) {
;         const int e = eb * 32 + g4 * 8 + 4 * h; const f32x4 g = *(const f32x4*)(a.g0 + e);
;         u32x2 w; w[0] = pk2(oacc[0][eb][4 * g4] * rr * g[0], oacc[0][eb][4 * g4 + 1] * rr * g[1]); w[1] = pk2(oacc[0][eb][4 * g4 + 2] * rr * g[2], oacc[0][eb][4 * g4 + 3] * rr * g[3]);
;         if (!a.nostore) *(u32x2*)(orow + e) = w;
;       }
	v_mov_b32_e32 v12, v86
	v_mov_b32_e32 v13, v87
	v_mov_b32_e32 v14, v88
	v_mov_b32_e32 v15, v89
	v_pk_mul_f32 v[12:13], v[20:21], v[12:13]
	v_pk_mul_f32 v[20:21], v[72:73], v[10:11] op_sel_hi:[1,0]
	v_cvt_pk_bf16_f32 v12, v12, v13
	v_pk_mul_f32 v[14:15], v[20:21], v[14:15]
	v_pk_mul_f32 v[20:21], v[70:71], v[10:11] op_sel_hi:[1,0]
	v_cvt_pk_bf16_f32 v13, v14, v15
	global_store_dwordx2 v[8:9], v[12:13], off offset:96
	s_waitcnt vmcnt(15)
	v_mov_b32_e32 v12, v90
	v_mov_b32_e32 v13, v91
	v_mov_b32_e32 v14, v92
	v_mov_b32_e32 v15, v93
	v_pk_mul_f32 v[12:13], v[20:21], v[12:13]
	v_pk_mul_f32 v[20:21], v[68:69], v[10:11] op_sel_hi:[1,0]
	v_cvt_pk_bf16_f32 v12, v12, v13
	v_pk_mul_f32 v[14:15], v[20:21], v[14:15]
	v_pk_mul_f32 v[20:21], v[66:67], v[10:11] op_sel_hi:[1,0]
	v_cvt_pk_bf16_f32 v13, v14, v15
	global_store_dwordx2 v[8:9], v[12:13], off offset:112
	s_waitcnt vmcnt(15)
	v_mov_b32_e32 v12, v106
	v_mov_b32_e32 v13, v107
	v_mov_b32_e32 v14, v108
	v_mov_b32_e32 v15, v109
	v_pk_mul_f32 v[12:13], v[20:21], v[12:13]
	v_pk_mul_f32 v[20:21], v[64:65], v[10:11] op_sel_hi:[1,0]
	v_cvt_pk_bf16_f32 v12, v12, v13
	v_pk_mul_f32 v[14:15], v[20:21], v[14:15]
	v_pk_mul_f32 v[20:21], v[52:53], v[10:11] op_sel_hi:[1,0]
	v_cvt_pk_bf16_f32 v13, v14, v15
	global_store_dwordx2 v[8:9], v[12:13], off offset:128
	s_waitcnt vmcnt(15)
	v_mov_b32_e32 v12, v118
	v_mov_b32_e32 v13, v119
	v_mov_b32_e32 v14, v120
	v_mov_b32_e32 v15, v121
	v_pk_mul_f32 v[12:13], v[20:21], v[12:13]
	v_pk_mul_f32 v[20:21], v[50:51], v[10:11] op_sel_hi:[1,0]
	v_cvt_pk_bf16_f32 v12, v12, v13
	v_pk_mul_f32 v[14:15], v[20:21], v[14:15]
	v_pk_mul_f32 v[20:21], v[48:49], v[10:11] op_sel_hi:[1,0]
	v_cvt_pk_bf16_f32 v13, v14, v15
	global_store_dwordx2 v[8:9], v[12:13], off offset:144
	s_waitcnt vmcnt(15)
	v_mov_b32_e32 v12, v122
	v_mov_b32_e32 v13, v123
	v_mov_b32_e32 v14, v124
	v_mov_b32_e32 v15, v125
	v_pk_mul_f32 v[12:13], v[20:21], v[12:13]
	v_pk_mul_f32 v[20:21], v[40:41], v[10:11] op_sel_hi:[1,0]
	v_cvt_pk_bf16_f32 v12, v12, v13
	v_pk_mul_f32 v[14:15], v[20:21], v[14:15]
	v_pk_mul_f32 v[20:21], v[38:39], v[10:11] op_sel_hi:[1,0]
	v_cvt_pk_bf16_f32 v13, v14, v15
	global_store_dwordx2 v[8:9], v[12:13], off offset:160
	s_waitcnt vmcnt(15)
	v_mov_b32_e32 v12, v134
	v_mov_b32_e32 v13, v135
	v_mov_b32_e32 v14, v136
	v_mov_b32_e32 v15, v137
	v_pk_mul_f32 v[12:13], v[20:21], v[12:13]
	v_pk_mul_f32 v[20:21], v[36:37], v[10:11] op_sel_hi:[1,0]
	v_cvt_pk_bf16_f32 v12, v12, v13
	v_pk_mul_f32 v[14:15], v[20:21], v[14:15]
	v_pk_mul_f32 v[20:21], v[34:35], v[10:11] op_sel_hi:[1,0]
	v_cvt_pk_bf16_f32 v13, v14, v15
	global_store_dwordx2 v[8:9], v[12:13], off offset:176
	s_waitcnt vmcnt(15)
	v_mov_b32_e32 v12, v138
	v_mov_b32_e32 v13, v139
	v_mov_b32_e32 v14, v140
	v_mov_b32_e32 v15, v141
	v_pk_mul_f32 v[12:13], v[20:21], v[12:13]
	v_pk_mul_f32 v[20:21], v[32:33], v[10:11] op_sel_hi:[1,0]
	v_cvt_pk_bf16_f32 v12, v12, v13
	v_pk_mul_f32 v[14:15], v[20:21], v[14:15]
	s_nop 0
	v_cvt_pk_bf16_f32 v13, v14, v15
	global_store_dwordx2 v[8:9], v[12:13], off offset:192
	s_waitcnt vmcnt(15)
	v_mov_b32_e32 v12, v142
	v_mov_b32_e32 v13, v143
	v_mov_b32_e32 v14, v144
	v_mov_b32_e32 v15, v145
	v_pk_mul_f32 v[12:13], v[18:19], v[12:13]
	v_pk_mul_f32 v[14:15], v[16:17], v[14:15]
	v_cvt_pk_bf16_f32 v12, v12, v13
	v_cvt_pk_bf16_f32 v13, v14, v15
	global_store_dwordx2 v[8:9], v[12:13], off offset:208
	s_waitcnt vmcnt(15)
	v_mov_b32_e32 v12, v146
	v_mov_b32_e32 v13, v147
	v_mov_b32_e32 v14, v148
	v_mov_b32_e32 v15, v149
	v_pk_mul_f32 v[6:7], v[6:7], v[12:13]
	v_pk_mul_f32 v[4:5], v[4:5], v[14:15]
	v_cvt_pk_bf16_f32 v6, v6, v7
	v_cvt_pk_bf16_f32 v7, v4, v5
	global_store_dwordx2 v[8:9], v[6:7], off offset:224
	v_pk_mul_f32 v[6:7], v[2:3], v[10:11] op_sel_hi:[1,0]
	s_waitcnt vmcnt(15)
	v_mov_b32_e32 v2, v150
	v_mov_b32_e32 v3, v151
	v_mov_b32_e32 v4, v152
	v_mov_b32_e32 v5, v153
	v_pk_mul_f32 v[2:3], v[6:7], v[2:3]
	v_pk_mul_f32 v[0:1], v[0:1], v[4:5]
	v_cvt_pk_bf16_f32 v2, v2, v3
	v_cvt_pk_bf16_f32 v3, v0, v1
	global_store_dwordx2 v[8:9], v[2:3], off offset:240
	s_branch .LBB0_397

; template <int EPI, bool RS>
; DI void gemm_phase(unsigned char* smem, const bf16_t* __restrict__ A, int lda, const bf16_t* __restrict__ Bt, int K, int mt0, int nMt, int nNt, const EpiArgs& ea) {
;     ...
;     f32x16 acc[2][4];
; #pragma unroll
;     for (int a = 0; a < 2; ++a)
; #pragma unroll
;       for (int b = 0; b < 4; ++b)
; #pragma unroll
;         for (int i = 0; i < 16; ++i) acc[a][b][i] = 0.f;
;     float ssq[4] = {0.f, 0.f, 0.f, 0.f};
.LBB0_442:
	s_lshl_b32 s0, s58, 8
	s_ashr_i32 s15, s14, 31
	s_ashr_i32 s1, s0, 31
	s_lshl_b64 s[16:17], s[14:15], 11
	s_lshl_b64 s[20:21], s[0:1], 11
	s_add_u32 s15, s36, 0x100
	s_addc_u32 s36, s37, 0
	s_add_u32 s37, s52, s16
	s_addc_u32 s60, s53, s17
	s_add_u32 s61, s54, s20
	s_addc_u32 s70, s55, s21
	s_add_u32 s2, s2, 0x100
	v_mov_b32_e32 v195, 0
	s_addc_u32 s3, s3, 0
	s_mov_b32 s71, 0
	v_mov_b32_e32 v194, 0
	v_mov_b32_e32 v193, 0
	v_mov_b32_e32 v192, 0
	v_mov_b32_e32 v0, 0
	v_mov_b32_e32 v1, v195
	v_mov_b32_e32 v2, v195
	v_mov_b32_e32 v3, v195
	v_mov_b32_e32 v4, v195
	v_mov_b32_e32 v5, v195
	v_mov_b32_e32 v6, v195
	v_mov_b32_e32 v7, v195
	v_mov_b32_e32 v8, v195
	s_waitcnt lgkmcnt(0)
	v_mov_b32_e32 v9, v195
	v_mov_b32_e32 v10, v195
	v_mov_b32_e32 v11, v195
	v_mov_b32_e32 v12, v195
	v_mov_b32_e32 v13, v195
	v_mov_b32_e32 v14, v195
	v_mov_b32_e32 v15, v195
	v_mov_b32_e32 v32, 0
	v_mov_b32_e32 v33, v195
	v_mov_b32_e32 v34, v195
	v_mov_b32_e32 v35, v195
	v_mov_b32_e32 v36, v195
	v_mov_b32_e32 v37, v195
	v_mov_b32_e32 v38, v195
	v_mov_b32_e32 v39, v195
	v_mov_b32_e32 v40, v195
	v_mov_b32_e32 v41, v195
	v_mov_b32_e32 v42, v195
	v_mov_b32_e32 v43, v195
	v_mov_b32_e32 v44, v195
	v_mov_b32_e32 v45, v195
	v_mov_b32_e32 v46, v195
	v_mov_b32_e32 v47, v195
	v_mov_b32_e32 v64, 0
	v_mov_b32_e32 v65, v195
	v_mov_b32_e32 v66, v195
	v_mov_b32_e32 v67, v195
	v_mov_b32_e32 v68, v195
	v_mov_b32_e32 v69, v195
	v_mov_b32_e32 v70, v195
	v_mov_b32_e32 v71, v195
	v_mov_b32_e32 v72, v195
	v_mov_b32_e32 v73, v195
	v_mov_b32_e32 v74, v195
	v_mov_b32_e32 v75, v195
	v_mov_b32_e32 v76, v195
	v_mov_b32_e32 v77, v195
	v_mov_b32_e32 v78, v195
	v_mov_b32_e32 v79, v195
	v_mov_b32_e32 v96, 0
	v_mov_b32_e32 v97, v195
	v_mov_b32_e32 v98, v195
	v_mov_b32_e32 v99, v195
	v_mov_b32_e32 v100, v195
	v_mov_b32_e32 v101, v195
	v_mov_b32_e32 v102, v195
	v_mov_b32_e32 v103, v195
	v_mov_b32_e32 v104, v195
	v_mov_b32_e32 v105, v195
	v_mov_b32_e32 v106, v195
	v_mov_b32_e32 v107, v195
	v_mov_b32_e32 v108, v195
	v_mov_b32_e32 v109, v195
	v_mov_b32_e32 v110, v195
	v_mov_b32_e32 v111, v195
	v_mov_b32_e32 v16, 0
	v_mov_b32_e32 v17, v195
	v_mov_b32_e32 v18, v195
	v_mov_b32_e32 v19, v195
	v_mov_b32_e32 v20, v195
	v_mov_b32_e32 v21, v195
	v_mov_b32_e32 v22, v195
	v_mov_b32_e32 v23, v195
	v_mov_b32_e32 v24, v195
	v_mov_b32_e32 v25, v195
	v_mov_b32_e32 v26, v195
	v_mov_b32_e32 v27, v195
	v_mov_b32_e32 v28, v195
	v_mov_b32_e32 v29, v195
	v_mov_b32_e32 v30, v195
	v_mov_b32_e32 v31, v195
	v_mov_b32_e32 v48, 0
	v_mov_b32_e32 v49, v195
	v_mov_b32_e32 v50, v195
	v_mov_b32_e32 v51, v195
	v_mov_b32_e32 v52, v195
	v_mov_b32_e32 v53, v195
	v_mov_b32_e32 v54, v195
	v_mov_b32_e32 v55, v195
	v_mov_b32_e32 v56, v195
	v_mov_b32_e32 v57, v195
	v_mov_b32_e32 v58, v195
	v_mov_b32_e32 v59, v195
	v_mov_b32_e32 v60, v195
	v_mov_b32_e32 v61, v195
	v_mov_b32_e32 v62, v195
	v_mov_b32_e32 v63, v195
	v_mov_b32_e32 v80, 0
	v_mov_b32_e32 v81, v195
	v_mov_b32_e32 v82, v195
	v_mov_b32_e32 v83, v195
	v_mov_b32_e32 v84, v195
	v_mov_b32_e32 v85, v195
	v_mov_b32_e32 v86, v195
	v_mov_b32_e32 v87, v195
	v_mov_b32_e32 v88, v195
	v_mov_b32_e32 v89, v195
	v_mov_b32_e32 v90, v195
	v_mov_b32_e32 v91, v195
	v_mov_b32_e32 v92, v195
	v_mov_b32_e32 v93, v195
	v_mov_b32_e32 v94, v195
	v_mov_b32_e32 v95, v195
	v_mov_b32_e32 v112, 0
	v_mov_b32_e32 v113, v195
	v_mov_b32_e32 v114, v195
	v_mov_b32_e32 v115, v195
	v_mov_b32_e32 v116, v195
	v_mov_b32_e32 v117, v195
	v_mov_b32_e32 v118, v195
	v_mov_b32_e32 v119, v195
	v_mov_b32_e32 v120, v195
	v_mov_b32_e32 v121, v195
	v_mov_b32_e32 v122, v195
	v_mov_b32_e32 v123, v195
	v_mov_b32_e32 v124, v195
	v_mov_b32_e32 v125, v195
	v_mov_b32_e32 v126, v195
	v_mov_b32_e32 v127, v195
	v_readfirstlane_b32 s100, v219
	s_nop 3
	s_bfe_u32 s100, s100, 0x20006
.LBB0_443:
	s_waitcnt lgkmcnt(3)
	s_nop 0
	v_mfma_f32_32x32x16_bf16 v[112:127], v[164:167], v[180:183], v[112:127]
	s_cmp_lt_u32 s71, 14
	s_waitcnt lgkmcnt(2)
	s_waitcnt lgkmcnt(1)
	s_waitcnt lgkmcnt(0)
	s_cselect_b32 s1, s3, s60
	s_cselect_b32 s0, s2, s37
	v_mfma_f32_32x32x16_bf16 v[96:111], v[160:163], v[180:183], v[96:111]
	s_cselect_b32 s39, s36, s70
	s_cselect_b32 s38, s15, s61
	s_bitcmp1_b32 s71, 0
	v_mfma_f32_32x32x16_bf16 v[80:95], v[164:167], v[176:179], v[80:95]
	s_cselect_b32 s18, 0x12000, 0
	s_add_i32 s71, s71, 1
	s_bitcmp1_b32 s71, 0
	v_mfma_f32_32x32x16_bf16 v[64:79], v[160:163], v[176:179], v[64:79]
	s_cselect_b32 s22, 0x12000, 0
	s_cmp_eq_u32 s100, 0
	s_cbranch_scc0 .Lddqkv_skip0
	v_dot2c_f32_bf16_e32 v195, v180, v180
	v_dot2c_f32_bf16_e32 v194, v176, v176
	v_dot2c_f32_bf16_e32 v193, v172, v172
	v_dot2c_f32_bf16_e32 v192, v168, v168
	v_dot2c_f32_bf16_e32 v195, v181, v181
	v_dot2c_f32_bf16_e32 v194, v177, v177
	v_dot2c_f32_bf16_e32 v193, v173, v173
	v_dot2c_f32_bf16_e32 v192, v169, v169
	v_dot2c_f32_bf16_e32 v195, v182, v182
	v_dot2c_f32_bf16_e32 v194, v178, v178
	v_dot2c_f32_bf16_e32 v193, v174, v174
	v_dot2c_f32_bf16_e32 v192, v170, v170
	v_dot2c_f32_bf16_e32 v195, v183, v183
	v_dot2c_f32_bf16_e32 v194, v179, v179
	v_dot2c_f32_bf16_e32 v193, v175, v175
	v_dot2c_f32_bf16_e32 v192, v171, v171
.Lddqkv_skip0:
	s_add_i32 s18, s18, 0
	s_add_i32 s93, s22, 0
	v_mfma_f32_32x32x16_bf16 v[48:63], v[164:167], v[172:175], v[48:63]
	v_mfma_f32_32x32x16_bf16 v[32:47], v[160:163], v[172:175], v[32:47]
	v_mfma_f32_32x32x16_bf16 v[16:31], v[164:167], v[168:171], v[16:31]
	v_mfma_f32_32x32x16_bf16 v[0:15], v[160:163], v[168:171], v[0:15]
	v_add_u32_e32 v196, s93, v186
	v_lshl_add_u64 v[200:201], s[0:1], 0, v[184:185]
	s_waitcnt vmcnt(7)
	ds_write_b128 v196, v[132:135]
	s_waitcnt vmcnt(6)
	ds_write_b128 v196, v[128:131] offset:36864
	v_lshl_add_u64 v[202:203], s[38:39], 0, v[184:185]
	global_load_dwordx4 v[132:135], v[200:201], off
	global_load_dwordx4 v[128:131], v[202:203], off
	s_waitcnt vmcnt(7)
	ds_write_b128 v196, v[152:155] offset:9216
	s_waitcnt vmcnt(6)
	ds_write_b128 v196, v[148:151] offset:46080
	v_add_co_u32_e32 v148, vcc, s42, v200
	v_add_u32_e32 v198, s18, v189
	s_nop 0
	v_addc_co_u32_e32 v149, vcc, 0, v201, vcc
	v_add_co_u32_e32 v150, vcc, s42, v202
	v_add_u32_e32 v204, s18, v188
	s_nop 0
	v_addc_co_u32_e32 v151, vcc, 0, v203, vcc
	global_load_dwordx4 v[152:155], v[148:149], off
	s_nop 0
	global_load_dwordx4 v[148:151], v[150:151], off
	ds_read_b128 v[160:163], v198 offset:36896
	ds_read_b128 v[164:167], v198 offset:41504
	ds_read_b128 v[168:171], v204 offset:32
	ds_read_b128 v[172:175], v204 offset:4640
	ds_read_b128 v[176:179], v204 offset:9248
	ds_read_b128 v[180:183], v204 offset:13856
	s_waitcnt lgkmcnt(3)
	v_mfma_f32_32x32x16_bf16 v[112:127], v[160:163], v[168:171], v[112:127]
	s_waitcnt lgkmcnt(2)
	s_waitcnt lgkmcnt(1)
	s_waitcnt lgkmcnt(0)
	v_mfma_f32_32x32x16_bf16 v[96:111], v[164:167], v[168:171], v[96:111]
	v_mfma_f32_32x32x16_bf16 v[80:95], v[160:163], v[172:175], v[80:95]
	s_cmp_eq_u32 s100, 1
	s_cbranch_scc0 .Lddqkv_skip1
	v_dot2c_f32_bf16_e32 v195, v168, v168
	v_dot2c_f32_bf16_e32 v194, v172, v172
	v_dot2c_f32_bf16_e32 v193, v176, v176
	v_dot2c_f32_bf16_e32 v192, v180, v180
	v_dot2c_f32_bf16_e32 v195, v169, v169
	v_dot2c_f32_bf16_e32 v194, v173, v173
	v_dot2c_f32_bf16_e32 v193, v177, v177
	v_dot2c_f32_bf16_e32 v192, v181, v181
	v_dot2c_f32_bf16_e32 v195, v170, v170
	v_dot2c_f32_bf16_e32 v194, v174, v174
	v_dot2c_f32_bf16_e32 v193, v178, v178
	v_dot2c_f32_bf16_e32 v192, v182, v182
	v_dot2c_f32_bf16_e32 v195, v171, v171
	v_dot2c_f32_bf16_e32 v194, v175, v175
	v_dot2c_f32_bf16_e32 v193, v179, v179
	v_dot2c_f32_bf16_e32 v192, v183, v183
.Lddqkv_skip1:
	v_mfma_f32_32x32x16_bf16 v[64:79], v[164:167], v[172:175], v[64:79]
	v_mfma_f32_32x32x16_bf16 v[48:63], v[160:163], v[176:179], v[48:63]
	v_mfma_f32_32x32x16_bf16 v[32:47], v[164:167], v[176:179], v[32:47]
	v_mfma_f32_32x32x16_bf16 v[16:31], v[160:163], v[180:183], v[16:31]
	v_mfma_f32_32x32x16_bf16 v[0:15], v[164:167], v[180:183], v[0:15]
	s_waitcnt vmcnt(7)
	ds_write_b128 v196, v[136:139] offset:18432
	s_waitcnt vmcnt(6)
	ds_write_b128 v196, v[144:147] offset:55296
	v_add_co_u32_e32 v136, vcc, s43, v200
	s_nop 1
	v_addc_co_u32_e32 v137, vcc, 0, v201, vcc
	v_add_co_u32_e32 v144, vcc, s43, v202
	global_load_dwordx4 v[136:139], v[136:137], off
	s_nop 0
	v_addc_co_u32_e32 v145, vcc, 0, v203, vcc
	global_load_dwordx4 v[144:147], v[144:145], off
	s_waitcnt vmcnt(7)
	ds_write_b128 v196, v[140:143] offset:27648
	s_waitcnt vmcnt(6)
	ds_write_b128 v196, v[156:159] offset:64512
	v_add_co_u32_e32 v140, vcc, s75, v200
	s_nop 1
	v_addc_co_u32_e32 v141, vcc, 0, v201, vcc
	v_add_co_u32_e32 v156, vcc, s75, v202
	global_load_dwordx4 v[140:143], v[140:141], off
	s_nop 0
	v_addc_co_u32_e32 v157, vcc, 0, v203, vcc
	global_load_dwordx4 v[156:159], v[156:157], off
	ds_read_b128 v[160:163], v198 offset:36928
	ds_read_b128 v[164:167], v198 offset:41536
	ds_read_b128 v[168:171], v204 offset:64
	ds_read_b128 v[172:175], v204 offset:4672
	ds_read_b128 v[176:179], v204 offset:9280
	ds_read_b128 v[180:183], v204 offset:13888
	s_waitcnt lgkmcnt(3)
	v_mfma_f32_32x32x16_bf16 v[112:127], v[160:163], v[168:171], v[112:127]
	s_waitcnt lgkmcnt(2)
	s_waitcnt lgkmcnt(1)
	s_waitcnt lgkmcnt(0)
	v_mfma_f32_32x32x16_bf16 v[96:111], v[164:167], v[168:171], v[96:111]
	v_mfma_f32_32x32x16_bf16 v[80:95], v[160:163], v[172:175], v[80:95]
	s_cmp_eq_u32 s100, 2
	s_cbranch_scc0 .Lddqkv_skip2
	v_dot2c_f32_bf16_e32 v195, v168, v168
	v_dot2c_f32_bf16_e32 v194, v172, v172
	v_dot2c_f32_bf16_e32 v193, v176, v176
	v_dot2c_f32_bf16_e32 v192, v180, v180
	v_dot2c_f32_bf16_e32 v195, v169, v169
	v_dot2c_f32_bf16_e32 v194, v173, v173
	v_dot2c_f32_bf16_e32 v193, v177, v177
	v_dot2c_f32_bf16_e32 v192, v181, v181
	v_dot2c_f32_bf16_e32 v195, v170, v170
	v_dot2c_f32_bf16_e32 v194, v174, v174
	v_dot2c_f32_bf16_e32 v193, v178, v178
	v_dot2c_f32_bf16_e32 v192, v182, v182
	v_dot2c_f32_bf16_e32 v195, v171, v171
	v_dot2c_f32_bf16_e32 v194, v175, v175
	v_dot2c_f32_bf16_e32 v193, v179, v179
	v_dot2c_f32_bf16_e32 v192, v183, v183
.Lddqkv_skip2:
	v_mfma_f32_32x32x16_bf16 v[64:79], v[164:167], v[172:175], v[64:79]
	v_mfma_f32_32x32x16_bf16 v[48:63], v[160:163], v[176:179], v[48:63]
	v_mfma_f32_32x32x16_bf16 v[32:47], v[164:167], v[176:179], v[32:47]
	v_mfma_f32_32x32x16_bf16 v[16:31], v[160:163], v[180:183], v[16:31]
	v_mfma_f32_32x32x16_bf16 v[0:15], v[164:167], v[180:183], v[0:15]
	ds_read_b128 v[160:163], v198 offset:36960
	ds_read_b128 v[164:167], v198 offset:41568
	ds_read_b128 v[168:171], v204 offset:96
	ds_read_b128 v[172:175], v204 offset:4704
	ds_read_b128 v[176:179], v204 offset:9312
	ds_read_b128 v[180:183], v204 offset:13920
	s_waitcnt lgkmcnt(3)
	v_mfma_f32_32x32x16_bf16 v[112:127], v[160:163], v[168:171], v[112:127]
	s_waitcnt lgkmcnt(2)
	s_waitcnt lgkmcnt(1)
	s_waitcnt lgkmcnt(0)
	v_mfma_f32_32x32x16_bf16 v[96:111], v[164:167], v[168:171], v[96:111]
	v_mfma_f32_32x32x16_bf16 v[80:95], v[160:163], v[172:175], v[80:95]
	s_cmp_eq_u32 s100, 3
	s_cbranch_scc0 .Lddqkv_skip3
	v_dot2c_f32_bf16_e32 v195, v168, v168
	v_dot2c_f32_bf16_e32 v194, v172, v172
	v_dot2c_f32_bf16_e32 v193, v176, v176
	v_dot2c_f32_bf16_e32 v192, v180, v180
	v_dot2c_f32_bf16_e32 v195, v169, v169
	v_dot2c_f32_bf16_e32 v194, v173, v173
	v_dot2c_f32_bf16_e32 v193, v177, v177
	v_dot2c_f32_bf16_e32 v192, v181, v181
	v_dot2c_f32_bf16_e32 v195, v170, v170
	v_dot2c_f32_bf16_e32 v194, v174, v174
	v_dot2c_f32_bf16_e32 v193, v178, v178
	v_dot2c_f32_bf16_e32 v192, v182, v182
	v_dot2c_f32_bf16_e32 v195, v171, v171
	v_dot2c_f32_bf16_e32 v194, v175, v175
	v_dot2c_f32_bf16_e32 v193, v179, v179
	v_dot2c_f32_bf16_e32 v192, v183, v183
; template <int EPI, bool RS>
; DI void gemm_epilogue(unsigned char* smem, f32x16 (&acc)[2][4], const float (&ssq)[4], int K, int m0, int nt256, const EpiArgs& ea, int wt, int wf, int r, int h) {
;     ...
;   if (RS) {
; #pragma unroll
;     for (int tb = 0; tb < 4; ++tb) { float s = ssq[tb]; s += __shfl_xor(s, 32); rstd[tb] = rsqrtf(s / (float)K + EPS); }
;   }
;     ...
;     const int sec = nt >> 3, head = nt & 7;
;     if (sec < 2) {
;       const float* g = (sec == 0 ? ea.g0 : ea.g1) + wc * 64; const float sc = sec == 0 ? 0.125f * LOG2E : 1.f; bf16_t* ob = sec == 0 ? ea.o0 : ea.o1;
; #pragma unroll
;       for (int tb = 0; tb < 4; ++tb) {
;         const int tok = m0 + wt * 128 + tb * 32 + r; const float a = rstd[tb]; float ss = 0.f;
; #pragma unroll
;         for (int fb = 0; fb < 2; ++fb)
; #pragma unroll
;           for (int i = 0; i < 16; ++i) { const float v = acc[fb][tb][i] * a; acc[fb][tb][i] = v; ss += v * v; }
;         ss += __shfl_xor(ss, 32);
;         const float rr = rsqrtf(ss * (1.0f / 64.0f) + EPS) * sc;
;         bf16_t* op = ob + (size_t)tok * 1024 + head * 128 + wc * 64;
; #pragma unroll
;         for (int fb = 0; fb < 2; ++fb)
; #pragma unroll
;           for (int g4 = 0; g4 < 4; ++g4) {
;             const int d = fb * 32 + g4 * 8 + 4 * h;
;             const f32x4 gg = *(const f32x4*)(g + d);
;             u32x2 w; w[0] = pk2(acc[fb][tb][4 * g4] * rr * gg[0], acc[fb][tb][4 * g4 + 1] * rr * gg[1]); w[1] = pk2(acc[fb][tb][4 * g4 + 2] * rr * gg[2], acc[fb][tb][4 * g4 + 3] * rr * gg[3]);
;             *(u32x2*)(op + d) = w;
;           }
;       }
;     } else {
; #pragma unroll
;       for (int tb = 0; tb < 4; ++tb) {
;         const int tok = m0 + wt * 128 + tb * 32 + r; int ss0, S; tok_info(tok, ss0, S); const int pos = tok - ss0;
;         const float a = rstd[tb];
;         const unsigned vb = ((unsigned)ss0 * 1024u + (unsigned)(head * 128) * (unsigned)S + (unsigned)(pos >> 5) * 4096u + (unsigned)(wc * 64 + 4 * h) * 32u + (unsigned)(pos & 31)) * 2u, eS = 64u;
; #pragma unroll
;         for (int fb = 0; fb < 2; ++fb)
; #pragma unroll
; template <int EPI, bool RS>
; DI void gemm_phase(unsigned char* smem, const bf16_t* __restrict__ A, int lda, const bf16_t* __restrict__ Bt, int K, int mt0, int nMt, int nNt, const EpiArgs& ea) {
;     ...
;     if (DEEP) {
;     ...
;       for (int kt = 0; kt < nk; kt += 2) { G_ITER(rg, kt); G_ITER(rh, kt + 1); }
.Lddqkv_skip3:
	s_barrier
	v_mfma_f32_32x32x16_bf16 v[64:79], v[164:167], v[172:175], v[64:79]
	v_mfma_f32_32x32x16_bf16 v[48:63], v[160:163], v[176:179], v[48:63]
	v_mfma_f32_32x32x16_bf16 v[32:47], v[164:167], v[176:179], v[32:47]
	v_mfma_f32_32x32x16_bf16 v[16:31], v[160:163], v[180:183], v[16:31]
	v_mfma_f32_32x32x16_bf16 v[0:15], v[164:167], v[180:183], v[0:15]
	v_add_u32_e32 v160, s93, v189
	v_add_u32_e32 v168, s93, v188
	ds_read_b128 v[164:167], v160 offset:36864
	ds_read_b128 v[160:163], v160 offset:41472
	ds_read_b128 v[180:183], v168
	ds_read_b128 v[176:179], v168 offset:4608
	ds_read_b128 v[172:175], v168 offset:9216
	ds_read_b128 v[168:171], v168 offset:13824
	s_add_u32 s15, s15, 0x80
	s_addc_u32 s36, s36, 0
	s_add_u32 s37, s37, 0x80
	s_addc_u32 s60, s60, 0
	s_add_u32 s61, s61, 0x80
	s_addc_u32 s70, s70, 0
	s_add_u32 s2, s2, 0x80
	s_addc_u32 s3, s3, 0
	s_cmp_eq_u32 s71, 16
	s_cbranch_scc0 .LBB0_443
	v_lshlrev_b32_e32 v210, 2, v219
	v_add_u32_e32 v210, 0x24010, v210
	ds_write_b32 v210, v195
	ds_write_b32 v210, v194 offset:2048
	ds_write_b32 v210, v193 offset:4096
	ds_write_b32 v210, v192 offset:6144
	v_and_b32_e32 v211, 0x13f, v219
	v_lshlrev_b32_e32 v211, 2, v211
	v_add_u32_e32 v211, 0x24010, v211
	s_waitcnt lgkmcnt(0)
	s_barrier
	ds_read_b32 v212, v211
	ds_read_b32 v213, v211 offset:256
	ds_read_b32 v214, v211 offset:512
	ds_read_b32 v215, v211 offset:768
	ds_read_b32 v220, v211 offset:2048
	ds_read_b32 v221, v211 offset:2304
	ds_read_b32 v222, v211 offset:2560
	ds_read_b32 v223, v211 offset:2816
	ds_read_b32 v224, v211 offset:4096
	ds_read_b32 v225, v211 offset:4352
	ds_read_b32 v226, v211 offset:4608
	ds_read_b32 v227, v211 offset:4864
	ds_read_b32 v228, v211 offset:6144
	ds_read_b32 v229, v211 offset:6400
	ds_read_b32 v230, v211 offset:6656
	ds_read_b32 v231, v211 offset:6912
	s_waitcnt lgkmcnt(0)
	v_add_f32_e32 v195, v212, v213
	v_add_f32_e32 v195, v195, v214
	v_add_f32_e32 v195, v195, v215
	v_add_f32_e32 v194, v220, v221
	v_add_f32_e32 v194, v194, v222
	v_add_f32_e32 v194, v194, v223
	v_add_f32_e32 v193, v224, v225
	v_add_f32_e32 v193, v193, v226
	v_add_f32_e32 v193, v193, v227
	v_add_f32_e32 v192, v228, v229
	v_add_f32_e32 v192, v192, v230
	v_add_f32_e32 v192, v192, v231
	v_and_b32_e32 v198, 64, v253
	v_xor_b32_e32 v196, 32, v253
	v_add_u32_e32 v198, 64, v198
	v_cmp_lt_i32_e32 vcc, v196, v198
	s_mov_b32 s0, 0x358637bd
	v_mov_b32_e32 v200, v197
	v_cndmask_b32_e32 v196, v253, v196, vcc
	v_lshlrev_b32_e32 v209, 2, v196
	ds_bpermute_b32 v203, v209, v195
	ds_bpermute_b32 v202, v209, v194
	v_mov_b32_e32 v201, v191
	s_mov_b32 s76, 0x3a800000
	v_add3_u32 v206, s59, v187, v201
	s_waitcnt lgkmcnt(0)
	v_pk_add_f32 v[194:195], v[194:195], v[202:203]
	v_mov_b64_e32 v[202:203], s[0:1]
	s_mov_b32 s0, 0x3a800000
	v_pk_fma_f32 v[194:195], v[194:195], s[0:1], v[202:203] op_sel_hi:[1,0,0]
	s_nop 0
	v_mul_f32_e32 v196, 0x4b800000, v195
	v_cmp_gt_f32_e64 s[2:3], s67, v195
	v_cmp_gt_f32_e32 vcc, s67, v194
	s_nop 0
	v_cndmask_b32_e64 v195, v195, v196, s[2:3]
	v_rsq_f32_e32 v195, v195
	s_nop 0
	v_mul_f32_e32 v196, 0x45800000, v195
	v_cndmask_b32_e64 v208, v195, v196, s[2:3]
	v_mul_f32_e32 v195, 0x4b800000, v194
	v_cndmask_b32_e32 v194, v194, v195, vcc
	v_rsq_f32_e32 v194, v194
	s_nop 0
	v_mul_f32_e32 v195, 0x45800000, v194
	v_cndmask_b32_e32 v204, v194, v195, vcc
	ds_bpermute_b32 v195, v209, v193
	ds_bpermute_b32 v194, v209, v192
	s_waitcnt lgkmcnt(0)
	v_pk_add_f32 v[192:193], v[192:193], v[194:195]
	s_nop 0
	v_pk_fma_f32 v[192:193], v[192:193], s[0:1], v[202:203] op_sel_hi:[1,0,0]
	s_lshl_b32 s0, s33, 1
	v_mul_f32_e32 v194, 0x4b800000, v193
	v_cmp_gt_f32_e64 s[2:3], s67, v193
	v_cmp_gt_f32_e32 vcc, s67, v192
	s_cmp_lt_i32 s33, 8
	v_cndmask_b32_e64 v193, v193, v194, s[2:3]
	v_rsq_f32_e32 v193, v193
	v_add_u32_e32 v202, 32, v206
	v_mul_f32_e32 v194, 0x45800000, v193
	v_cndmask_b32_e64 v198, v193, v194, s[2:3]
	v_mul_f32_e32 v193, 0x4b800000, v192
	v_cndmask_b32_e32 v192, v192, v193, vcc
	v_rsq_f32_e32 v192, v192
	s_mov_b64 s[2:3], -1
	v_add_u32_e32 v194, 64, v206
	v_mul_f32_e32 v193, 0x45800000, v192
	v_cndmask_b32_e32 v196, v192, v193, vcc
	v_and_or_b32 v193, s0, 6, v199
	v_add_u32_e32 v192, 0x60, v206
	s_cbranch_scc1 .LBB0_446
	v_cmp_gt_i32_e32 vcc, s66, v206
	v_lshlrev_b32_e32 v195, 7, v193
	v_lshl_add_u32 v201, v200, 7, v205
	v_cndmask_b32_e32 v203, v218, v250, vcc
	v_and_b32_e32 v203, v203, v206
	v_sub_u32_e32 v207, v206, v203
	v_cndmask_b32_e64 v210, 11, 13, vcc
	v_and_or_b32 v201, v206, 31, v201
	v_lshlrev_b32_e32 v203, 10, v203
	v_lshlrev_b32_e32 v210, v210, v195
	v_lshlrev_b32_e32 v207, 7, v207
	v_and_b32_e32 v207, 0x7ffff000, v207
	v_add3_u32 v203, v210, v201, v203
	v_add_lshl_u32 v203, v203, v207, 1
	v_mul_f32_e32 v207, v112, v208
	v_cvt_pk_bf16_f32 v207, v207, s0
	v_mul_f32_e32 v210, v113, v208
	global_store_short v203, v207, s[8:9]
	v_add_u32_e32 v207, 64, v203
	v_cvt_pk_bf16_f32 v210, v210, s0
	global_store_short v207, v210, s[8:9]
	v_mul_f32_e32 v210, v114, v208
	v_add_u32_e32 v207, 0x80, v203
	v_cvt_pk_bf16_f32 v210, v210, s0
	global_store_short v207, v210, s[8:9]
	v_mul_f32_e32 v210, v115, v208
	v_add_u32_e32 v207, 0xc0, v203
	v_cvt_pk_bf16_f32 v210, v210, s0
	global_store_short v207, v210, s[8:9]
	v_mul_f32_e32 v210, v116, v208
	v_add_u32_e32 v207, 0x200, v203
	v_cvt_pk_bf16_f32 v210, v210, s0
	global_store_short v207, v210, s[8:9]
	v_mul_f32_e32 v210, v117, v208
	v_add_u32_e32 v207, 0x240, v203
	v_cvt_pk_bf16_f32 v210, v210, s0
	global_store_short v207, v210, s[8:9]
	v_mul_f32_e32 v210, v118, v208
	v_add_u32_e32 v207, 0x280, v203
	v_cvt_pk_bf16_f32 v210, v210, s0
	global_store_short v207, v210, s[8:9]
	v_mul_f32_e32 v210, v119, v208
; DI void tok_info(int t, int& seq_start, int& S) { if (t < TP) { seq_start = t & ~8191; S = 8192; } else { seq_start = TP + ((t - TP) & ~2047); S = 2048; } }
; DI void st_bf16(bf16_t* p, float v) { *p = (bf16_t)(pk2(v, 0.f) & 0xffffu); }
; template <int EPI, bool RS>
; DI void gemm_epilogue(unsigned char* smem, f32x16 (&acc)[2][4], const float (&ssq)[4], int K, int m0, int nt256, const EpiArgs& ea, int wt, int wf, int r, int h) {
;     ...
;     } else {
; #pragma unroll
;       for (int tb = 0; tb < 4; ++tb) {
;         const int tok = m0 + wt * 128 + tb * 32 + r; int ss0, S; tok_info(tok, ss0, S); const int pos = tok - ss0;
;         const float a = rstd[tb];
;         const unsigned vb = ((unsigned)ss0 * 1024u + (unsigned)(head * 128) * (unsigned)S + (unsigned)(pos >> 5) * 4096u + (unsigned)(wc * 64 + 4 * h) * 32u + (unsigned)(pos & 31)) * 2u, eS = 64u;
; #pragma unroll
;         for (int fb = 0; fb < 2; ++fb)
; #pragma unroll
;           for (int i = 0; i < 16; ++i) { const unsigned e = fb * 32 + 8 * (i >> 2) + (i & 3); st_bf16((bf16_t*)((char*)ea.o2 + (vb + e * eS)), acc[fb][tb][i] * a); }
;       }
	v_add_u32_e32 v207, 0x2c0, v203
	v_cvt_pk_bf16_f32 v210, v210, s0
	global_store_short v207, v210, s[8:9]
	v_mul_f32_e32 v210, v120, v208
	v_add_u32_e32 v207, 0x400, v203
	v_cvt_pk_bf16_f32 v210, v210, s0
	global_store_short v207, v210, s[8:9]
	v_mul_f32_e32 v210, v121, v208
	v_add_u32_e32 v207, 0x440, v203
	v_cvt_pk_bf16_f32 v210, v210, s0
	global_store_short v207, v210, s[8:9]
	v_mul_f32_e32 v210, v122, v208
	v_add_u32_e32 v207, 0x480, v203
	v_cvt_pk_bf16_f32 v210, v210, s0
	global_store_short v207, v210, s[8:9]
	v_mul_f32_e32 v210, v123, v208
	v_add_u32_e32 v207, 0x4c0, v203
	v_cvt_pk_bf16_f32 v210, v210, s0
	global_store_short v207, v210, s[8:9]
	v_mul_f32_e32 v210, v124, v208
	v_add_u32_e32 v207, 0x600, v203
	v_cvt_pk_bf16_f32 v210, v210, s0
	global_store_short v207, v210, s[8:9]
	v_mul_f32_e32 v210, v125, v208
	v_add_u32_e32 v207, 0x640, v203
	v_cvt_pk_bf16_f32 v210, v210, s0
	global_store_short v207, v210, s[8:9]
	v_mul_f32_e32 v210, v126, v208
	v_add_u32_e32 v207, 0x680, v203
	v_cvt_pk_bf16_f32 v210, v210, s0
	global_store_short v207, v210, s[8:9]
	v_mul_f32_e32 v210, v127, v208
	v_add_u32_e32 v207, 0x6c0, v203
	v_cvt_pk_bf16_f32 v210, v210, s0
	global_store_short v207, v210, s[8:9]
	v_mul_f32_e32 v210, v96, v208
	v_add_u32_e32 v207, 0x800, v203
	v_cvt_pk_bf16_f32 v210, v210, s0
	global_store_short v207, v210, s[8:9]
	v_mul_f32_e32 v210, v97, v208
	v_add_u32_e32 v207, 0x840, v203
	v_cvt_pk_bf16_f32 v210, v210, s0
	global_store_short v207, v210, s[8:9]
	v_mul_f32_e32 v210, v98, v208
	v_add_u32_e32 v207, 0x880, v203
	v_cvt_pk_bf16_f32 v210, v210, s0
	global_store_short v207, v210, s[8:9]
	v_mul_f32_e32 v210, v99, v208
	v_add_u32_e32 v207, 0x8c0, v203
	v_cvt_pk_bf16_f32 v210, v210, s0
	global_store_short v207, v210, s[8:9]
	v_mul_f32_e32 v210, v100, v208
	v_add_u32_e32 v207, 0xa00, v203
	v_cvt_pk_bf16_f32 v210, v210, s0
	global_store_short v207, v210, s[8:9]
	v_mul_f32_e32 v210, v101, v208
	v_add_u32_e32 v207, 0xa40, v203
	v_cvt_pk_bf16_f32 v210, v210, s0
	global_store_short v207, v210, s[8:9]
	v_mul_f32_e32 v210, v102, v208
	v_add_u32_e32 v207, 0xa80, v203
	v_cvt_pk_bf16_f32 v210, v210, s0
	global_store_short v207, v210, s[8:9]
	v_mul_f32_e32 v210, v103, v208
	v_add_u32_e32 v207, 0xac0, v203
	v_cvt_pk_bf16_f32 v210, v210, s0
	global_store_short v207, v210, s[8:9]
	v_mul_f32_e32 v210, v104, v208
	v_add_u32_e32 v207, 0xc00, v203
	v_cvt_pk_bf16_f32 v210, v210, s0
	global_store_short v207, v210, s[8:9]
	v_mul_f32_e32 v210, v105, v208
	v_add_u32_e32 v207, 0xc40, v203
	v_cvt_pk_bf16_f32 v210, v210, s0
	global_store_short v207, v210, s[8:9]
	v_mul_f32_e32 v210, v106, v208
	v_add_u32_e32 v207, 0xc80, v203
	v_cvt_pk_bf16_f32 v210, v210, s0
	global_store_short v207, v210, s[8:9]
	v_mul_f32_e32 v210, v107, v208
	v_add_u32_e32 v207, 0xcc0, v203
	v_cvt_pk_bf16_f32 v210, v210, s0
	global_store_short v207, v210, s[8:9]
	v_mul_f32_e32 v210, v108, v208
	v_add_u32_e32 v207, 0xe00, v203
	v_cvt_pk_bf16_f32 v210, v210, s0
	global_store_short v207, v210, s[8:9]
	v_mul_f32_e32 v210, v109, v208
	v_add_u32_e32 v207, 0xe40, v203
	v_cvt_pk_bf16_f32 v210, v210, s0
	global_store_short v207, v210, s[8:9]
	v_mul_f32_e32 v210, v110, v208
	v_add_u32_e32 v207, 0xe80, v203
	v_cvt_pk_bf16_f32 v210, v210, s0
	global_store_short v207, v210, s[8:9]
	v_mul_f32_e32 v207, v111, v208
	v_add_u32_e32 v203, 0xec0, v203
	v_cvt_pk_bf16_f32 v207, v207, s0
	v_cmp_gt_i32_e32 vcc, s66, v202
	global_store_short v203, v207, s[8:9]
	s_mov_b64 s[2:3], 0
	v_cndmask_b32_e32 v203, v218, v250, vcc
	v_and_b32_e32 v203, v203, v202
	v_sub_u32_e32 v207, v202, v203
	v_cndmask_b32_e64 v210, 11, 13, vcc
	v_lshlrev_b32_e32 v203, 10, v203
	v_lshlrev_b32_e32 v210, v210, v195
	v_lshlrev_b32_e32 v207, 7, v207
	v_and_b32_e32 v207, 0x7ffff000, v207
	v_add3_u32 v203, v210, v201, v203
	v_add_lshl_u32 v203, v203, v207, 1
	v_mul_f32_e32 v207, v80, v204
	v_cvt_pk_bf16_f32 v207, v207, s0
	v_mul_f32_e32 v210, v81, v204
	global_store_short v203, v207, s[8:9]
	v_add_u32_e32 v207, 64, v203
	v_cvt_pk_bf16_f32 v210, v210, s0
	global_store_short v207, v210, s[8:9]
	v_mul_f32_e32 v210, v82, v204
	v_add_u32_e32 v207, 0x80, v203
	v_cvt_pk_bf16_f32 v210, v210, s0
	global_store_short v207, v210, s[8:9]
	v_mul_f32_e32 v210, v83, v204
	v_add_u32_e32 v207, 0xc0, v203
	v_cvt_pk_bf16_f32 v210, v210, s0
	global_store_short v207, v210, s[8:9]
	v_mul_f32_e32 v210, v84, v204
	v_add_u32_e32 v207, 0x200, v203
	v_cvt_pk_bf16_f32 v210, v210, s0
	global_store_short v207, v210, s[8:9]
	v_mul_f32_e32 v210, v85, v204
	v_add_u32_e32 v207, 0x240, v203
	v_cvt_pk_bf16_f32 v210, v210, s0
	global_store_short v207, v210, s[8:9]
	v_mul_f32_e32 v210, v86, v204
	v_add_u32_e32 v207, 0x280, v203
	v_cvt_pk_bf16_f32 v210, v210, s0
	global_store_short v207, v210, s[8:9]
	v_mul_f32_e32 v210, v87, v204
	v_add_u32_e32 v207, 0x2c0, v203
	v_cvt_pk_bf16_f32 v210, v210, s0
	global_store_short v207, v210, s[8:9]
	v_mul_f32_e32 v210, v88, v204
	v_add_u32_e32 v207, 0x400, v203
	v_cvt_pk_bf16_f32 v210, v210, s0
	global_store_short v207, v210, s[8:9]
	v_mul_f32_e32 v210, v89, v204
	v_add_u32_e32 v207, 0x440, v203
	v_cvt_pk_bf16_f32 v210, v210, s0
	global_store_short v207, v210, s[8:9]
	v_mul_f32_e32 v210, v90, v204
	v_add_u32_e32 v207, 0x480, v203
	v_cvt_pk_bf16_f32 v210, v210, s0
	global_store_short v207, v210, s[8:9]
	v_mul_f32_e32 v210, v91, v204
	v_add_u32_e32 v207, 0x4c0, v203
	v_cvt_pk_bf16_f32 v210, v210, s0
	global_store_short v207, v210, s[8:9]
	v_mul_f32_e32 v210, v92, v204
	v_add_u32_e32 v207, 0x600, v203
	v_cvt_pk_bf16_f32 v210, v210, s0
	global_store_short v207, v210, s[8:9]
	v_mul_f32_e32 v210, v93, v204
	v_add_u32_e32 v207, 0x640, v203
; DI void tok_info(int t, int& seq_start, int& S) { if (t < TP) { seq_start = t & ~8191; S = 8192; } else { seq_start = TP + ((t - TP) & ~2047); S = 2048; } }
; DI void st_bf16(bf16_t* p, float v) { *p = (bf16_t)(pk2(v, 0.f) & 0xffffu); }
; template <int EPI, bool RS>
; DI void gemm_epilogue(unsigned char* smem, f32x16 (&acc)[2][4], const float (&ssq)[4], int K, int m0, int nt256, const EpiArgs& ea, int wt, int wf, int r, int h) {
;     ...
;     } else {
; #pragma unroll
;       for (int tb = 0; tb < 4; ++tb) {
;         const int tok = m0 + wt * 128 + tb * 32 + r; int ss0, S; tok_info(tok, ss0, S); const int pos = tok - ss0;
;         const float a = rstd[tb];
;         const unsigned vb = ((unsigned)ss0 * 1024u + (unsigned)(head * 128) * (unsigned)S + (unsigned)(pos >> 5) * 4096u + (unsigned)(wc * 64 + 4 * h) * 32u + (unsigned)(pos & 31)) * 2u, eS = 64u;
; #pragma unroll
;         for (int fb = 0; fb < 2; ++fb)
; #pragma unroll
;           for (int i = 0; i < 16; ++i) { const unsigned e = fb * 32 + 8 * (i >> 2) + (i & 3); st_bf16((bf16_t*)((char*)ea.o2 + (vb + e * eS)), acc[fb][tb][i] * a); }
;       }
	v_cvt_pk_bf16_f32 v210, v210, s0
	global_store_short v207, v210, s[8:9]
	v_mul_f32_e32 v210, v94, v204
	v_add_u32_e32 v207, 0x680, v203
	v_cvt_pk_bf16_f32 v210, v210, s0
	global_store_short v207, v210, s[8:9]
	v_mul_f32_e32 v210, v95, v204
	v_add_u32_e32 v207, 0x6c0, v203
	v_cvt_pk_bf16_f32 v210, v210, s0
	global_store_short v207, v210, s[8:9]
	v_mul_f32_e32 v210, v64, v204
	v_add_u32_e32 v207, 0x800, v203
	v_cvt_pk_bf16_f32 v210, v210, s0
	global_store_short v207, v210, s[8:9]
	v_mul_f32_e32 v210, v65, v204
	v_add_u32_e32 v207, 0x840, v203
	v_cvt_pk_bf16_f32 v210, v210, s0
	global_store_short v207, v210, s[8:9]
	v_mul_f32_e32 v210, v66, v204
	v_add_u32_e32 v207, 0x880, v203
	v_cvt_pk_bf16_f32 v210, v210, s0
	global_store_short v207, v210, s[8:9]
	v_mul_f32_e32 v210, v67, v204
	v_add_u32_e32 v207, 0x8c0, v203
	v_cvt_pk_bf16_f32 v210, v210, s0
	global_store_short v207, v210, s[8:9]
	v_mul_f32_e32 v210, v68, v204
	v_add_u32_e32 v207, 0xa00, v203
	v_cvt_pk_bf16_f32 v210, v210, s0
	global_store_short v207, v210, s[8:9]
	v_mul_f32_e32 v210, v69, v204
	v_add_u32_e32 v207, 0xa40, v203
	v_cvt_pk_bf16_f32 v210, v210, s0
	global_store_short v207, v210, s[8:9]
	v_mul_f32_e32 v210, v70, v204
	v_add_u32_e32 v207, 0xa80, v203
	v_cvt_pk_bf16_f32 v210, v210, s0
	global_store_short v207, v210, s[8:9]
	v_mul_f32_e32 v210, v71, v204
	v_add_u32_e32 v207, 0xac0, v203
	v_cvt_pk_bf16_f32 v210, v210, s0
	global_store_short v207, v210, s[8:9]
	v_mul_f32_e32 v210, v72, v204
	v_add_u32_e32 v207, 0xc00, v203
	v_cvt_pk_bf16_f32 v210, v210, s0
	global_store_short v207, v210, s[8:9]
	v_mul_f32_e32 v210, v73, v204
	v_add_u32_e32 v207, 0xc40, v203
	v_cvt_pk_bf16_f32 v210, v210, s0
	global_store_short v207, v210, s[8:9]
	v_mul_f32_e32 v210, v74, v204
	v_add_u32_e32 v207, 0xc80, v203
	v_cvt_pk_bf16_f32 v210, v210, s0
	global_store_short v207, v210, s[8:9]
	v_mul_f32_e32 v210, v75, v204
	v_add_u32_e32 v207, 0xcc0, v203
	v_cvt_pk_bf16_f32 v210, v210, s0
	global_store_short v207, v210, s[8:9]
	v_mul_f32_e32 v210, v76, v204
	v_add_u32_e32 v207, 0xe00, v203
	v_cvt_pk_bf16_f32 v210, v210, s0
	global_store_short v207, v210, s[8:9]
	v_mul_f32_e32 v210, v77, v204
	v_add_u32_e32 v207, 0xe40, v203
	v_cvt_pk_bf16_f32 v210, v210, s0
	global_store_short v207, v210, s[8:9]
	v_mul_f32_e32 v210, v78, v204
	v_add_u32_e32 v207, 0xe80, v203
	v_cvt_pk_bf16_f32 v210, v210, s0
	global_store_short v207, v210, s[8:9]
	v_mul_f32_e32 v207, v79, v204
	v_add_u32_e32 v203, 0xec0, v203
	v_cvt_pk_bf16_f32 v207, v207, s0
	v_cmp_gt_i32_e32 vcc, s66, v194
	global_store_short v203, v207, s[8:9]
	s_nop 0
	v_cndmask_b32_e32 v203, v218, v250, vcc
	v_and_b32_e32 v203, v203, v194
	v_sub_u32_e32 v207, v194, v203
	v_cndmask_b32_e64 v210, 11, 13, vcc
	v_lshlrev_b32_e32 v203, 10, v203
	v_lshlrev_b32_e32 v210, v210, v195
	v_lshlrev_b32_e32 v207, 7, v207
	v_and_b32_e32 v207, 0x7ffff000, v207
	v_add3_u32 v203, v210, v201, v203
	v_add_lshl_u32 v203, v203, v207, 1
	v_mul_f32_e32 v207, v48, v198
	v_cvt_pk_bf16_f32 v207, v207, s0
	v_mul_f32_e32 v210, v49, v198
	global_store_short v203, v207, s[8:9]
	v_add_u32_e32 v207, 64, v203
	v_cvt_pk_bf16_f32 v210, v210, s0
	global_store_short v207, v210, s[8:9]
	v_mul_f32_e32 v210, v50, v198
	v_add_u32_e32 v207, 0x80, v203
	v_cvt_pk_bf16_f32 v210, v210, s0
	global_store_short v207, v210, s[8:9]
	v_mul_f32_e32 v210, v51, v198
	v_add_u32_e32 v207, 0xc0, v203
	v_cvt_pk_bf16_f32 v210, v210, s0
	global_store_short v207, v210, s[8:9]
	v_mul_f32_e32 v210, v52, v198
	v_add_u32_e32 v207, 0x200, v203
	v_cvt_pk_bf16_f32 v210, v210, s0
	global_store_short v207, v210, s[8:9]
	v_mul_f32_e32 v210, v53, v198
	v_add_u32_e32 v207, 0x240, v203
	v_cvt_pk_bf16_f32 v210, v210, s0
	global_store_short v207, v210, s[8:9]
	v_mul_f32_e32 v210, v54, v198
	v_add_u32_e32 v207, 0x280, v203
	v_cvt_pk_bf16_f32 v210, v210, s0
	global_store_short v207, v210, s[8:9]
	v_mul_f32_e32 v210, v55, v198
	v_add_u32_e32 v207, 0x2c0, v203
	v_cvt_pk_bf16_f32 v210, v210, s0
	global_store_short v207, v210, s[8:9]
	v_mul_f32_e32 v210, v56, v198
	v_add_u32_e32 v207, 0x400, v203
	v_cvt_pk_bf16_f32 v210, v210, s0
	global_store_short v207, v210, s[8:9]
	v_mul_f32_e32 v210, v57, v198
	v_add_u32_e32 v207, 0x440, v203
	v_cvt_pk_bf16_f32 v210, v210, s0
	global_store_short v207, v210, s[8:9]
	v_mul_f32_e32 v210, v58, v198
	v_add_u32_e32 v207, 0x480, v203
	v_cvt_pk_bf16_f32 v210, v210, s0
	global_store_short v207, v210, s[8:9]
	v_mul_f32_e32 v210, v59, v198
	v_add_u32_e32 v207, 0x4c0, v203
	v_cvt_pk_bf16_f32 v210, v210, s0
	global_store_short v207, v210, s[8:9]
	v_mul_f32_e32 v210, v60, v198
	v_add_u32_e32 v207, 0x600, v203
	v_cvt_pk_bf16_f32 v210, v210, s0
	global_store_short v207, v210, s[8:9]
	v_mul_f32_e32 v210, v61, v198
	v_add_u32_e32 v207, 0x640, v203
	v_cvt_pk_bf16_f32 v210, v210, s0
	global_store_short v207, v210, s[8:9]
	v_mul_f32_e32 v210, v62, v198
	v_add_u32_e32 v207, 0x680, v203
	v_cvt_pk_bf16_f32 v210, v210, s0
	global_store_short v207, v210, s[8:9]
	v_mul_f32_e32 v210, v63, v198
	v_add_u32_e32 v207, 0x6c0, v203
	v_cvt_pk_bf16_f32 v210, v210, s0
	global_store_short v207, v210, s[8:9]
	v_mul_f32_e32 v210, v32, v198
	v_add_u32_e32 v207, 0x800, v203
	v_cvt_pk_bf16_f32 v210, v210, s0
	global_store_short v207, v210, s[8:9]
	v_mul_f32_e32 v210, v33, v198
	v_add_u32_e32 v207, 0x840, v203
	v_cvt_pk_bf16_f32 v210, v210, s0
	global_store_short v207, v210, s[8:9]
	v_mul_f32_e32 v210, v34, v198
	v_add_u32_e32 v207, 0x880, v203
	v_cvt_pk_bf16_f32 v210, v210, s0
	global_store_short v207, v210, s[8:9]
	v_mul_f32_e32 v210, v35, v198
	v_add_u32_e32 v207, 0x8c0, v203
	v_cvt_pk_bf16_f32 v210, v210, s0
	global_store_short v207, v210, s[8:9]
; DI void tok_info(int t, int& seq_start, int& S) { if (t < TP) { seq_start = t & ~8191; S = 8192; } else { seq_start = TP + ((t - TP) & ~2047); S = 2048; } }
; DI void st_bf16(bf16_t* p, float v) { *p = (bf16_t)(pk2(v, 0.f) & 0xffffu); }
; template <int EPI, bool RS>
; DI void gemm_epilogue(unsigned char* smem, f32x16 (&acc)[2][4], const float (&ssq)[4], int K, int m0, int nt256, const EpiArgs& ea, int wt, int wf, int r, int h) {
;     ...
;     } else {
; #pragma unroll
;       for (int tb = 0; tb < 4; ++tb) {
;         const int tok = m0 + wt * 128 + tb * 32 + r; int ss0, S; tok_info(tok, ss0, S); const int pos = tok - ss0;
;         const float a = rstd[tb];
;         const unsigned vb = ((unsigned)ss0 * 1024u + (unsigned)(head * 128) * (unsigned)S + (unsigned)(pos >> 5) * 4096u + (unsigned)(wc * 64 + 4 * h) * 32u + (unsigned)(pos & 31)) * 2u, eS = 64u;
; #pragma unroll
;         for (int fb = 0; fb < 2; ++fb)
; #pragma unroll
;           for (int i = 0; i < 16; ++i) { const unsigned e = fb * 32 + 8 * (i >> 2) + (i & 3); st_bf16((bf16_t*)((char*)ea.o2 + (vb + e * eS)), acc[fb][tb][i] * a); }
;       }
	v_mul_f32_e32 v210, v36, v198
	v_add_u32_e32 v207, 0xa00, v203
	v_cvt_pk_bf16_f32 v210, v210, s0
	global_store_short v207, v210, s[8:9]
	v_mul_f32_e32 v210, v37, v198
	v_add_u32_e32 v207, 0xa40, v203
	v_cvt_pk_bf16_f32 v210, v210, s0
	global_store_short v207, v210, s[8:9]
	v_mul_f32_e32 v210, v38, v198
	v_add_u32_e32 v207, 0xa80, v203
	v_cvt_pk_bf16_f32 v210, v210, s0
	global_store_short v207, v210, s[8:9]
	v_mul_f32_e32 v210, v39, v198
	v_add_u32_e32 v207, 0xac0, v203
	v_cvt_pk_bf16_f32 v210, v210, s0
	global_store_short v207, v210, s[8:9]
	v_mul_f32_e32 v210, v40, v198
	v_add_u32_e32 v207, 0xc00, v203
	v_cvt_pk_bf16_f32 v210, v210, s0
	global_store_short v207, v210, s[8:9]
	v_mul_f32_e32 v210, v41, v198
	v_add_u32_e32 v207, 0xc40, v203
	v_cvt_pk_bf16_f32 v210, v210, s0
	global_store_short v207, v210, s[8:9]
	v_mul_f32_e32 v210, v42, v198
	v_add_u32_e32 v207, 0xc80, v203
	v_cvt_pk_bf16_f32 v210, v210, s0
	global_store_short v207, v210, s[8:9]
	v_mul_f32_e32 v210, v43, v198
	v_add_u32_e32 v207, 0xcc0, v203
	v_cvt_pk_bf16_f32 v210, v210, s0
	global_store_short v207, v210, s[8:9]
	v_mul_f32_e32 v210, v44, v198
	v_add_u32_e32 v207, 0xe00, v203
	v_cvt_pk_bf16_f32 v210, v210, s0
	global_store_short v207, v210, s[8:9]
	v_mul_f32_e32 v210, v45, v198
	v_add_u32_e32 v207, 0xe40, v203
	v_cvt_pk_bf16_f32 v210, v210, s0
	global_store_short v207, v210, s[8:9]
	v_mul_f32_e32 v210, v46, v198
	v_add_u32_e32 v207, 0xe80, v203
	v_cvt_pk_bf16_f32 v210, v210, s0
	global_store_short v207, v210, s[8:9]
	v_mul_f32_e32 v207, v47, v198
	v_add_u32_e32 v203, 0xec0, v203
	v_cvt_pk_bf16_f32 v207, v207, s0
	v_cmp_gt_i32_e32 vcc, s66, v192
	global_store_short v203, v207, s[8:9]
	s_nop 0
	v_cndmask_b32_e32 v203, v218, v250, vcc
	v_and_b32_e32 v203, v203, v192
	v_sub_u32_e32 v207, v192, v203
	v_cndmask_b32_e64 v210, 11, 13, vcc
	v_lshlrev_b32_e32 v203, 10, v203
	v_lshlrev_b32_e32 v195, v210, v195
	v_lshlrev_b32_e32 v207, 7, v207
	v_and_b32_e32 v207, 0x7ffff000, v207
	v_add3_u32 v195, v195, v201, v203
	v_mul_f32_e32 v201, v16, v196
	v_add_lshl_u32 v195, v195, v207, 1
	v_cvt_pk_bf16_f32 v201, v201, s0
	v_mul_f32_e32 v203, v17, v196
	global_store_short v195, v201, s[8:9]
	v_add_u32_e32 v201, 64, v195
	v_cvt_pk_bf16_f32 v203, v203, s0
	global_store_short v201, v203, s[8:9]
	v_mul_f32_e32 v203, v18, v196
	v_add_u32_e32 v201, 0x80, v195
	v_cvt_pk_bf16_f32 v203, v203, s0
	global_store_short v201, v203, s[8:9]
	v_mul_f32_e32 v203, v19, v196
	v_add_u32_e32 v201, 0xc0, v195
	v_cvt_pk_bf16_f32 v203, v203, s0
	global_store_short v201, v203, s[8:9]
	v_mul_f32_e32 v203, v20, v196
	v_add_u32_e32 v201, 0x200, v195
	v_cvt_pk_bf16_f32 v203, v203, s0
	global_store_short v201, v203, s[8:9]
	v_mul_f32_e32 v203, v21, v196
	v_add_u32_e32 v201, 0x240, v195
	v_cvt_pk_bf16_f32 v203, v203, s0
	global_store_short v201, v203, s[8:9]
	v_mul_f32_e32 v203, v22, v196
	v_add_u32_e32 v201, 0x280, v195
	v_cvt_pk_bf16_f32 v203, v203, s0
	global_store_short v201, v203, s[8:9]
	v_mul_f32_e32 v203, v23, v196
	v_add_u32_e32 v201, 0x2c0, v195
	v_cvt_pk_bf16_f32 v203, v203, s0
	global_store_short v201, v203, s[8:9]
	v_mul_f32_e32 v203, v24, v196
	v_add_u32_e32 v201, 0x400, v195
	v_cvt_pk_bf16_f32 v203, v203, s0
	global_store_short v201, v203, s[8:9]
	v_mul_f32_e32 v203, v25, v196
	v_add_u32_e32 v201, 0x440, v195
	v_cvt_pk_bf16_f32 v203, v203, s0
	global_store_short v201, v203, s[8:9]
	v_mul_f32_e32 v203, v26, v196
	v_add_u32_e32 v201, 0x480, v195
	v_cvt_pk_bf16_f32 v203, v203, s0
	global_store_short v201, v203, s[8:9]
	v_mul_f32_e32 v203, v27, v196
	v_add_u32_e32 v201, 0x4c0, v195
	v_cvt_pk_bf16_f32 v203, v203, s0
	global_store_short v201, v203, s[8:9]
	v_mul_f32_e32 v203, v28, v196
	v_add_u32_e32 v201, 0x600, v195
	v_cvt_pk_bf16_f32 v203, v203, s0
	global_store_short v201, v203, s[8:9]
	v_mul_f32_e32 v203, v29, v196
	v_add_u32_e32 v201, 0x640, v195
	v_cvt_pk_bf16_f32 v203, v203, s0
	global_store_short v201, v203, s[8:9]
	v_mul_f32_e32 v203, v30, v196
	v_add_u32_e32 v201, 0x680, v195
	v_cvt_pk_bf16_f32 v203, v203, s0
	global_store_short v201, v203, s[8:9]
	v_mul_f32_e32 v203, v31, v196
	v_add_u32_e32 v201, 0x6c0, v195
	v_cvt_pk_bf16_f32 v203, v203, s0
	global_store_short v201, v203, s[8:9]
	v_mul_f32_e32 v203, v0, v196
	v_add_u32_e32 v201, 0x800, v195
	v_cvt_pk_bf16_f32 v203, v203, s0
	global_store_short v201, v203, s[8:9]
	v_mul_f32_e32 v203, v1, v196
	v_add_u32_e32 v201, 0x840, v195
	v_cvt_pk_bf16_f32 v203, v203, s0
	global_store_short v201, v203, s[8:9]
	v_mul_f32_e32 v203, v2, v196
	v_add_u32_e32 v201, 0x880, v195
	v_cvt_pk_bf16_f32 v203, v203, s0
	global_store_short v201, v203, s[8:9]
	v_mul_f32_e32 v203, v3, v196
	v_add_u32_e32 v201, 0x8c0, v195
	v_cvt_pk_bf16_f32 v203, v203, s0
	global_store_short v201, v203, s[8:9]
	v_mul_f32_e32 v203, v4, v196
	v_add_u32_e32 v201, 0xa00, v195
	v_cvt_pk_bf16_f32 v203, v203, s0
	global_store_short v201, v203, s[8:9]
	v_mul_f32_e32 v203, v5, v196
	v_add_u32_e32 v201, 0xa40, v195
	v_cvt_pk_bf16_f32 v203, v203, s0
	global_store_short v201, v203, s[8:9]
	v_mul_f32_e32 v203, v6, v196
	v_add_u32_e32 v201, 0xa80, v195
	v_cvt_pk_bf16_f32 v203, v203, s0
	global_store_short v201, v203, s[8:9]
	v_mul_f32_e32 v203, v7, v196
	v_add_u32_e32 v201, 0xac0, v195
	v_cvt_pk_bf16_f32 v203, v203, s0
	global_store_short v201, v203, s[8:9]
	v_mul_f32_e32 v203, v8, v196
	v_add_u32_e32 v201, 0xc00, v195
	v_cvt_pk_bf16_f32 v203, v203, s0
	global_store_short v201, v203, s[8:9]
	v_mul_f32_e32 v203, v9, v196
	v_add_u32_e32 v201, 0xc40, v195
	v_cvt_pk_bf16_f32 v203, v203, s0
	global_store_short v201, v203, s[8:9]
	v_mul_f32_e32 v203, v10, v196
	v_add_u32_e32 v201, 0xc80, v195
	v_cvt_pk_bf16_f32 v203, v203, s0
	global_store_short v201, v203, s[8:9]
	v_mul_f32_e32 v203, v11, v196
	v_add_u32_e32 v201, 0xcc0, v195
	v_cvt_pk_bf16_f32 v203, v203, s0
	global_store_short v201, v203, s[8:9]
	v_mul_f32_e32 v203, v12, v196
	v_add_u32_e32 v201, 0xe00, v195
	v_cvt_pk_bf16_f32 v203, v203, s0
	global_store_short v201, v203, s[8:9]
	v_mul_f32_e32 v203, v13, v196
	v_add_u32_e32 v201, 0xe40, v195
	v_cvt_pk_bf16_f32 v203, v203, s0
	global_store_short v201, v203, s[8:9]
	v_mul_f32_e32 v203, v14, v196
	v_add_u32_e32 v201, 0xe80, v195
	v_cvt_pk_bf16_f32 v203, v203, s0
	global_store_short v201, v203, s[8:9]
	v_mul_f32_e32 v201, v15, v196
	v_add_u32_e32 v195, 0xec0, v195
	v_cvt_pk_bf16_f32 v201, v201, s0
	global_store_short v195, v201, s[8:9]

; template <int KS, int NMAP, int EB, int NKB, int MODE>
; DI void attn_unit(unsigned char* smem, const AttnArgs& a, int t0, int head, int ehalf) {
;     ...
;   for (int kt = kt_lo; kt < kt_hi; ++kt) {
;     const int cur = DBUF ? ((kt - kt_lo) & 1) : 0;
;     const unsigned char* ks = smem + cur * TILEB; const unsigned char* vs = ks + KT * KP;
;     if (DBUF) {
;       if (kt + 1 < kt_hi) AT_WRITE(cur ^ 1);
;       if (kt + 2 < kt_hi) AT_LOAD((kt + 2) * KT);
;     } else {
;       __syncthreads();
;       AT_WRITE(0);
;       __syncthreads();
;       if (kt + 1 < kt_hi) AT_LOAD((kt + 1) * KT);
;     }
;     __builtin_amdgcn_sched_barrier(0);
; #pragma unroll
;     for (int kb = 0; kb < NKB; ++kb) {
;       bf16x8 pf[NMAP][2];
;       f32x16 cinit;
;       if (MODE == AT_DIFF) {
;         const float dbase = (float)(posq - kt * KT - 32 * kb - 8 * h);
; #pragma unroll
;         for (int i = 0; i < 16; ++i) { const float d = dbase - (float)(16 * (i >> 3) + (i & 7)); cinit[i] = fmaf(-slope2, fabsf(d), negM); }
;       } else {
; #pragma unroll
;         for (int i = 0; i < 16; ++i) cinit[i] = negM;
;       }
; #pragma unroll
;       for (int c = 0; c < NMAP; ++c) {
;         f32x16 sacc;
; #pragma unroll
;         for (int s = 0; s < KS; ++s) {
;           const bf16x8 kf = *(const bf16x8*)(ks + (32 * kb + r) * KP + (c * KS + s) * 32 + 16 * h);
;           const bf16x8 qv = QLDS ? *(const bf16x8*)(qs + qoff + (c * KS + s) * 32) : qf[QLDS ? 0 : c * KS + s];
;           sacc = (s == 0) ? MFMA(kf, qv, cinit) : MFMA(kf, qv, sacc);
;         }
;         float ls = 0.f;
; #pragma unroll
;         for (int i = 0; i < 16; ++i) { sacc[i] = __builtin_amdgcn_exp2f(sacc[i]); ls += sacc[i]; }
;         lsum[c] += ls;
; #pragma unroll
;         for (int cc = 0; cc < 2; ++cc) { u32x4 u;
; #pragma unroll
;           for (int j = 0; j < 4; ++j) u[j] = pk2(sacc[8 * cc + 2 * j], sacc[8 * cc + 2 * j + 1]);
;           pf[c][cc] = __builtin_bit_cast(bf16x8, u); }
;       }
; #pragma unroll
;       for (int eb = 0; eb < EB; ++eb)
; #pragma unroll
;         for (int cc = 0; cc < 2; ++cc) {
;           const bf16x8 vf = *(const bf16x8*)(vs + (eb * 32 + r) * VP + (32 * kb + 16 * cc + 8 * h) * 2);
; #pragma unroll
;           for (int c = 0; c < NMAP; ++c) oacc[c][eb] = MFMA(vf, pf[c][cc], oacc[c][eb]);
;         }
;     }
;     if (DBUF) __syncthreads();
;   }
.LBB0_486:
	s_mulk_i32 s1, 0x5800
	v_add_u32_e32 v133, s1, v132
	v_add_u32_e32 v143, v133, v126
	v_add_u32_e32 v133, v133, v127
	ds_read_b128 v[174:177], v143
	ds_read_b128 v[178:181], v143 offset:32
	ds_read_b128 v[182:185], v143 offset:64
	ds_read_b128 v[186:189], v143 offset:96
	ds_read_b128 v[190:193], v143 offset:128
	ds_read_b128 v[194:197], v143 offset:160
	ds_read_b128 v[198:201], v143 offset:6656
	ds_read_b128 v[202:205], v143 offset:6688
	ds_read_b128 v[206:209], v143 offset:6720
	ds_read_b128 v[210:213], v143 offset:6752
	ds_read_b128 v[220:223], v143 offset:6784
	ds_read_b128 v[224:227], v143 offset:6816
	s_add_i32 s50, s50, 64
	s_cmp_lg_u32 s11, s12
	s_waitcnt lgkmcnt(11)
	v_mfma_f32_32x32x16_bf16 v[64:79], v[174:177], v[88:91], v[0:15]
	s_waitcnt lgkmcnt(10)
	v_mfma_f32_32x32x16_bf16 v[64:79], v[178:181], v[92:95], v[64:79]
	s_waitcnt lgkmcnt(9)
	v_mfma_f32_32x32x16_bf16 v[64:79], v[182:185], v[96:99], v[64:79]
	s_waitcnt lgkmcnt(8)
	v_mfma_f32_32x32x16_bf16 v[64:79], v[186:189], v[100:103], v[64:79]
	s_waitcnt lgkmcnt(7)
	v_mfma_f32_32x32x16_bf16 v[64:79], v[190:193], v[104:107], v[64:79]
	s_waitcnt lgkmcnt(6)
	v_mfma_f32_32x32x16_bf16 v[64:79], v[194:197], v[108:111], v[64:79]
	s_waitcnt lgkmcnt(5)
	v_mfma_f32_32x32x16_bf16 v[48:63], v[198:201], v[88:91], v[0:15]
	ds_read_b128 v[228:231], v133 offset:13312
	ds_read_b128 v[232:235], v133 offset:17920
	ds_read_b128 v[236:239], v133 offset:13344
	ds_read_b128 v[240:243], v133 offset:17952
	s_waitcnt lgkmcnt(8)
	v_mfma_f32_32x32x16_bf16 v[48:63], v[202:205], v[92:95], v[48:63]
	ds_read_b128 v[174:177], v133 offset:13376
	ds_read_b128 v[178:181], v133 offset:17984
	ds_read_b128 v[182:185], v133 offset:13408
	ds_read_b128 v[186:189], v133 offset:18016
	s_waitcnt lgkmcnt(11)
	v_mfma_f32_32x32x16_bf16 v[48:63], v[206:209], v[96:99], v[48:63]
	v_exp_f32_e32 v151, v64
	v_exp_f32_e32 v152, v65
	v_exp_f32_e32 v153, v66
	v_exp_f32_e32 v154, v67
	s_waitcnt lgkmcnt(10)
	v_mfma_f32_32x32x16_bf16 v[48:63], v[210:213], v[100:103], v[48:63]
	v_exp_f32_e32 v155, v68
	v_exp_f32_e32 v156, v69
	v_exp_f32_e32 v157, v70
	v_exp_f32_e32 v158, v71
	s_waitcnt lgkmcnt(9)
	v_mfma_f32_32x32x16_bf16 v[48:63], v[220:223], v[104:107], v[48:63]
	v_cvt_pk_bf16_f32 v134, v151, v152
	v_cvt_pk_bf16_f32 v135, v153, v154
	v_cvt_pk_bf16_f32 v136, v155, v156
	v_cvt_pk_bf16_f32 v137, v157, v158
	v_exp_f32_e32 v159, v72
	v_exp_f32_e32 v160, v73
	s_waitcnt lgkmcnt(8)
	v_mfma_f32_32x32x16_bf16 v[48:63], v[224:227], v[108:111], v[48:63]
	v_exp_f32_e32 v161, v74
	v_exp_f32_e32 v162, v75
	v_exp_f32_e32 v163, v76
	v_exp_f32_e32 v164, v77
	s_waitcnt lgkmcnt(7)
	v_mfma_f32_32x32x16_bf16 v[32:47], v[228:231], v[134:137], v[32:47]
	v_exp_f32_e32 v165, v78
	v_exp_f32_e32 v166, v79
	v_cvt_pk_bf16_f32 v138, v159, v160
	v_cvt_pk_bf16_f32 v139, v161, v162
	v_cvt_pk_bf16_f32 v140, v163, v164
	v_add_f32_e32 v133, v151, v152
	v_cvt_pk_bf16_f32 v141, v165, v166
	v_add_f32_e32 v124, v124, v153
	s_waitcnt lgkmcnt(6)
	v_mfma_f32_32x32x16_bf16 v[16:31], v[232:235], v[134:137], v[16:31]
	v_exp_f32_e32 v167, v48
	v_exp_f32_e32 v168, v49
	v_exp_f32_e32 v169, v50
	v_exp_f32_e32 v170, v51
	s_waitcnt lgkmcnt(5)
	v_mfma_f32_32x32x16_bf16 v[32:47], v[236:239], v[138:141], v[32:47]
	v_exp_f32_e32 v171, v52
	v_exp_f32_e32 v172, v53
	v_exp_f32_e32 v142, v54
	v_exp_f32_e32 v143, v55
	s_waitcnt lgkmcnt(4)
	v_mfma_f32_32x32x16_bf16 v[16:31], v[240:243], v[138:141], v[16:31]
	v_cvt_pk_bf16_f32 v64, v167, v168
	v_cvt_pk_bf16_f32 v65, v169, v170
	v_cvt_pk_bf16_f32 v66, v171, v172
	v_cvt_pk_bf16_f32 v67, v142, v143
	v_exp_f32_e32 v144, v56
	v_exp_f32_e32 v145, v57
	s_waitcnt lgkmcnt(3)
	v_mfma_f32_32x32x16_bf16 v[32:47], v[174:177], v[64:67], v[32:47]
	v_exp_f32_e32 v244, v58
	v_exp_f32_e32 v245, v59
	v_exp_f32_e32 v248, v60
	v_exp_f32_e32 v249, v61
	s_waitcnt lgkmcnt(2)
	v_mfma_f32_32x32x16_bf16 v[16:31], v[178:181], v[64:67], v[16:31]
	v_exp_f32_e32 v251, v62
	v_exp_f32_e32 v252, v63
	v_cvt_pk_bf16_f32 v68, v144, v145
	v_cvt_pk_bf16_f32 v69, v244, v245
	v_cvt_pk_bf16_f32 v70, v248, v249
	v_add_f32_e32 v133, v133, v154
	v_cvt_pk_bf16_f32 v71, v251, v252
	v_add_f32_e32 v124, v124, v155
	v_add_f32_e32 v133, v133, v156
	s_waitcnt lgkmcnt(1)
	v_mfma_f32_32x32x16_bf16 v[32:47], v[182:185], v[68:71], v[32:47]
	v_add_f32_e32 v124, v124, v157
	v_add_f32_e32 v133, v133, v158
	v_add_f32_e32 v124, v124, v159
	v_add_f32_e32 v133, v133, v160
	v_add_f32_e32 v124, v124, v161
	v_add_f32_e32 v133, v133, v162
	v_add_f32_e32 v124, v124, v163
	v_add_f32_e32 v133, v133, v164
	s_waitcnt lgkmcnt(0)
	s_barrier
; template <int KS, int NMAP, int EB, int NKB, int MODE>
; DI void attn_unit(unsigned char* smem, const AttnArgs& a, int t0, int head, int ehalf) {
;     ...
;   }
;     ...
;   float inv[NMAP];
; #pragma unroll
;   for (int c = 0; c < NMAP; ++c) { float l = lsum[c]; l += __shfl_xor(l, 32); inv[c] = 1.0f / l; }
;   if (MODE == AT_DIFF) {
;     float ss = 0.f; const float l1 = a.lam * inv[NMAP - 1];
; #pragma unroll
;     for (int eb = 0; eb < EB; ++eb)
; #pragma unroll
;       for (int i = 0; i < 16; ++i) { const float v = oacc[0][eb][i] * inv[0] - oacc[NMAP - 1][eb][i] * l1; oacc[0][eb][i] = v; ss += v * v; }
;     ss += __shfl_xor(ss, 32);
;     const float rr = rsqrtf(ss * (1.0f / 128.0f) + EPS) * a.oscale;
; #pragma unroll
;     for (int eb = 0; eb < EB; ++eb)
; #pragma unroll
;       for (int g4 = 0; g4 < 4; ++g4) {
;         const int e = eb * 32 + g4 * 8 + 4 * h; const f32x4 g = *(const f32x4*)(a.g0 + e);
;         u32x2 w; w[0] = pk2(oacc[0][eb][4 * g4] * rr * g[0], oacc[0][eb][4 * g4 + 1] * rr * g[1]); w[1] = pk2(oacc[0][eb][4 * g4 + 2] * rr * g[2], oacc[0][eb][4 * g4 + 3] * rr * g[3]);
;         if (!a.nostore) *(u32x2*)(orow + e) = w;
;       }
;   } else {
; #pragma unroll
;     for (int eb = 0; eb < EB; ++eb)
; #pragma unroll
;       for (int g4 = 0; g4 < 4; ++g4) {
;         const int e = eb * 32 + g4 * 8 + 4 * h; const float iv = inv[0];
;         u32x2 w; w[0] = pk2(oacc[0][eb][4 * g4] * iv, oacc[0][eb][4 * g4 + 1] * iv); w[1] = pk2(oacc[0][eb][4 * g4 + 2] * iv, oacc[0][eb][4 * g4 + 3] * iv);
;         *(u32x2*)(orow + e) = w;
;       }
;   }
	v_mfma_f32_32x32x16_bf16 v[16:31], v[186:189], v[68:71], v[16:31]
	v_add_f32_e32 v124, v124, v165
	v_add_f32_e32 v133, v133, v166
	v_add_f32_e32 v124, v124, v167
	v_add_f32_e32 v133, v133, v168
	v_add_f32_e32 v124, v124, v169
	v_add_f32_e32 v133, v133, v170
	v_add_f32_e32 v124, v124, v171
	v_add_f32_e32 v133, v133, v172
	v_add_f32_e32 v124, v124, v142
	v_add_f32_e32 v133, v133, v143
	v_add_f32_e32 v124, v124, v144
	v_add_f32_e32 v133, v133, v145
	v_add_f32_e32 v124, v124, v244
	v_add_f32_e32 v133, v133, v245
	v_add_f32_e32 v124, v124, v248
	v_add_f32_e32 v133, v133, v249
	v_add_f32_e32 v124, v124, v251
	v_add_f32_e32 v133, v133, v252
	v_add_f32_e32 v124, v124, v133
	s_cbranch_scc1 .LBB0_474
	ds_bpermute_b32 v50, v147, v124
	v_lshlrev_b64 v[48:49], 10, v[116:117]
	v_lshl_add_u64 v[48:49], s[54:55], 0, v[48:49]
	s_lshl_b32 s50, s10, 1
	v_lshl_add_u64 v[48:49], v[48:49], 0, s[50:51]
	s_waitcnt lgkmcnt(0)
	v_add_f32_e32 v50, v124, v50
	v_div_scale_f32 v51, s[0:1], v50, v50, 1.0
	v_rcp_f32_e32 v52, v51
	v_lshlrev_b32_e32 v216, 3, v146
	s_mov_b64 s[2:3], 0
	v_fma_f32 v53, -v51, v52, 1.0
	v_fmac_f32_e32 v52, v53, v52
	v_div_scale_f32 v53, vcc, 1.0, v50, 1.0
	v_mul_f32_e32 v54, v53, v52
	v_fma_f32 v55, -v51, v54, v53
	v_fmac_f32_e32 v54, v55, v52
	v_fma_f32 v51, -v51, v54, v53
	v_div_fmas_f32 v51, v51, v52, v54
	v_div_fixup_f32 v50, v51, v50, 1.0
	v_mul_f32_e32 v32, v32, v50
	v_mul_f32_e32 v33, v33, v50
	v_mul_f32_e32 v16, v16, v50
	v_mul_f32_e32 v17, v17, v50
	v_cvt_pk_bf16_f32 v32, v32, v33
	v_mul_f32_e32 v33, v34, v50
	v_mul_f32_e32 v34, v35, v50
	v_cvt_pk_bf16_f32 v16, v16, v17
	v_mul_f32_e32 v17, v18, v50
	v_mul_f32_e32 v18, v19, v50
	v_cvt_pk_bf16_f32 v33, v33, v34
	v_lshl_add_u64 v[34:35], v[48:49], 0, v[216:217]
	v_cvt_pk_bf16_f32 v17, v17, v18
	global_store_dwordx2 v[34:35], v[32:33], off
	v_mul_f32_e32 v32, v36, v50
	v_mul_f32_e32 v33, v37, v50
	global_store_dwordx2 v[34:35], v[16:17], off offset:64
	v_mul_f32_e32 v16, v20, v50
	v_mul_f32_e32 v17, v21, v50
	v_cvt_pk_bf16_f32 v32, v32, v33
	v_mul_f32_e32 v33, v38, v50
	v_mul_f32_e32 v36, v39, v50
	v_cvt_pk_bf16_f32 v16, v16, v17
	v_mul_f32_e32 v17, v22, v50
	v_mul_f32_e32 v18, v23, v50
	v_cvt_pk_bf16_f32 v33, v33, v36
	v_cvt_pk_bf16_f32 v17, v17, v18
	global_store_dwordx2 v[34:35], v[32:33], off offset:16
	v_mul_f32_e32 v32, v40, v50
	v_mul_f32_e32 v33, v41, v50
	global_store_dwordx2 v[34:35], v[16:17], off offset:80
	v_mul_f32_e32 v16, v24, v50
	v_mul_f32_e32 v17, v25, v50
	v_cvt_pk_bf16_f32 v32, v32, v33
	v_mul_f32_e32 v33, v42, v50
	v_mul_f32_e32 v36, v43, v50
	v_cvt_pk_bf16_f32 v16, v16, v17
	v_mul_f32_e32 v17, v26, v50
	v_mul_f32_e32 v18, v27, v50
	v_cvt_pk_bf16_f32 v33, v33, v36
	v_cvt_pk_bf16_f32 v17, v17, v18
	global_store_dwordx2 v[34:35], v[32:33], off offset:32
	v_mul_f32_e32 v32, v44, v50
	v_mul_f32_e32 v33, v45, v50
	global_store_dwordx2 v[34:35], v[16:17], off offset:96
	v_mul_f32_e32 v16, v28, v50
	v_mul_f32_e32 v17, v29, v50
	v_cvt_pk_bf16_f32 v32, v32, v33
	v_mul_f32_e32 v33, v46, v50
	v_mul_f32_e32 v36, v47, v50
	v_cvt_pk_bf16_f32 v16, v16, v17
	v_mul_f32_e32 v17, v30, v50
	v_mul_f32_e32 v18, v31, v50
	v_cvt_pk_bf16_f32 v33, v33, v36
	v_cvt_pk_bf16_f32 v17, v17, v18
	global_store_dwordx2 v[34:35], v[32:33], off offset:48
	global_store_dwordx2 v[34:35], v[16:17], off offset:112
	s_branch .LBB0_453
.Ltramp_147:
	s_branch .LBB0_147

; DI void run_phase(KargP p, int ph, unsigned char* smem) {
;     ...
;   int q = ph - 1, layer = 0;
;   for (;;) { const int n = (layer & 1) ? 9 : 10; if (q < n) break; q -= n; ++layer; }
;   const int j = layer >> 1;
;   const int nm = (layer & 1) ? 3 : 4;
;   if (q < nm) {
;     if (!(layer & 1)) {
.Ltramp_149:
	s_branch .LBB0_149
.LBB0_488:
	s_and_b64 vcc, exec, s[2:3]
	s_cbranch_vccz .LBB0_582
	s_cmp_lg_u32 s74, 0
	s_mov_b64 s[22:23], -1
	s_cselect_b64 s[38:39], -1, 0
	s_andn2_b64 vcc, exec, s[38:39]
	s_cbranch_vccz .LBB0_583

; template <int EPI, bool RS>
; DI void gemm_phase(unsigned char* smem, const bf16_t* __restrict__ A, int lda, const bf16_t* __restrict__ Bt, int K, int mt0, int nMt, int nNt, const EpiArgs& ea) {
;     ...
;     f32x16 acc[2][4];
; #pragma unroll
;     for (int a = 0; a < 2; ++a)
; #pragma unroll
;       for (int b = 0; b < 4; ++b)
; #pragma unroll
;         for (int i = 0; i < 16; ++i) acc[a][b][i] = 0.f;
;     float ssq[4] = {0.f, 0.f, 0.f, 0.f};
.LBB0_506:
	s_lshl_b32 s0, s60, 8
	s_mul_i32 s6, s33, 0x540
	s_mul_hi_i32 s1, s33, 0x540
	s_add_u32 s46, s54, s6
	s_addc_u32 s47, s55, s1
	s_mul_i32 s1, s60, 0x30000
	s_mul_hi_i32 s0, s0, 0x300
	s_add_u32 s48, s50, s1
	v_mov_b32_e32 v227, 0
	s_addc_u32 s49, s36, s0
	s_mov_b32 s6, 0
	v_mov_b32_e32 v226, 0
	v_mov_b32_e32 v225, 0
	v_mov_b32_e32 v224, v227
	v_mov_b32_e32 v0, 0
	v_mov_b32_e32 v1, v227
	v_mov_b32_e32 v2, v227
	v_mov_b32_e32 v3, v227
	v_mov_b32_e32 v4, v227
	v_mov_b32_e32 v5, v227
	v_mov_b32_e32 v6, v227
	v_mov_b32_e32 v7, v227
	v_mov_b32_e32 v8, v227
	v_mov_b32_e32 v9, v227
	v_mov_b32_e32 v10, v227
	v_mov_b32_e32 v11, v227
	v_mov_b32_e32 v12, v227
	v_mov_b32_e32 v13, v227
	v_mov_b32_e32 v14, v227
	v_mov_b32_e32 v15, v227
	v_mov_b32_e32 v32, 0
	v_mov_b32_e32 v33, v227
	v_mov_b32_e32 v34, v227
	v_mov_b32_e32 v35, v227
	v_mov_b32_e32 v36, v227
	v_mov_b32_e32 v37, v227
	v_mov_b32_e32 v38, v227
	v_mov_b32_e32 v39, v227
	v_mov_b32_e32 v40, v227
	v_mov_b32_e32 v41, v227
	v_mov_b32_e32 v42, v227
	v_mov_b32_e32 v43, v227
	v_mov_b32_e32 v44, v227
	v_mov_b32_e32 v45, v227
	v_mov_b32_e32 v46, v227
	v_mov_b32_e32 v47, v227
	v_mov_b32_e32 v64, 0
	v_mov_b32_e32 v65, v227
	v_mov_b32_e32 v66, v227
	v_mov_b32_e32 v67, v227
	v_mov_b32_e32 v68, v227
	v_mov_b32_e32 v69, v227
	v_mov_b32_e32 v70, v227
	v_mov_b32_e32 v71, v227
	v_mov_b32_e32 v72, v227
	v_mov_b32_e32 v73, v227
	v_mov_b32_e32 v74, v227
	v_mov_b32_e32 v75, v227
	v_mov_b32_e32 v76, v227
	v_mov_b32_e32 v77, v227
	v_mov_b32_e32 v78, v227
	v_mov_b32_e32 v79, v227
	v_mov_b32_e32 v96, 0
	v_mov_b32_e32 v97, v227
	v_mov_b32_e32 v98, v227
	v_mov_b32_e32 v99, v227
	v_mov_b32_e32 v100, v227
	v_mov_b32_e32 v101, v227
	v_mov_b32_e32 v102, v227
	v_mov_b32_e32 v103, v227
	v_mov_b32_e32 v104, v227
	v_mov_b32_e32 v105, v227
	v_mov_b32_e32 v106, v227
	v_mov_b32_e32 v107, v227
	v_mov_b32_e32 v108, v227
	v_mov_b32_e32 v109, v227
	v_mov_b32_e32 v110, v227
	v_mov_b32_e32 v111, v227
	v_mov_b32_e32 v16, 0
	v_mov_b32_e32 v17, v227
	v_mov_b32_e32 v18, v227
	v_mov_b32_e32 v19, v227
	v_mov_b32_e32 v20, v227
	v_mov_b32_e32 v21, v227
	v_mov_b32_e32 v22, v227
	v_mov_b32_e32 v23, v227
	v_mov_b32_e32 v24, v227
	v_mov_b32_e32 v25, v227
	v_mov_b32_e32 v26, v227
	v_mov_b32_e32 v27, v227
	v_mov_b32_e32 v28, v227
	v_mov_b32_e32 v29, v227
	v_mov_b32_e32 v30, v227
	v_mov_b32_e32 v31, v227
	v_mov_b32_e32 v48, 0
	v_mov_b32_e32 v49, v227
	v_mov_b32_e32 v50, v227
	v_mov_b32_e32 v51, v227
	v_mov_b32_e32 v52, v227
	v_mov_b32_e32 v53, v227
	v_mov_b32_e32 v54, v227
	v_mov_b32_e32 v55, v227
	v_mov_b32_e32 v56, v227
	v_mov_b32_e32 v57, v227
	v_mov_b32_e32 v58, v227
	v_mov_b32_e32 v59, v227
	v_mov_b32_e32 v60, v227
	v_mov_b32_e32 v61, v227
	v_mov_b32_e32 v62, v227
	v_mov_b32_e32 v63, v227
	s_waitcnt vmcnt(9)
	v_mov_b32_e32 v80, 0
	v_mov_b32_e32 v81, v227
	v_mov_b32_e32 v82, v227
	v_mov_b32_e32 v83, v227
	v_mov_b32_e32 v84, v227
	v_mov_b32_e32 v85, v227
	v_mov_b32_e32 v86, v227
	v_mov_b32_e32 v87, v227
	v_mov_b32_e32 v88, v227
	v_mov_b32_e32 v89, v227
	v_mov_b32_e32 v90, v227
	v_mov_b32_e32 v91, v227
	v_mov_b32_e32 v92, v227
	v_mov_b32_e32 v93, v227
	v_mov_b32_e32 v94, v227
	v_mov_b32_e32 v95, v227
	s_waitcnt vmcnt(8)
	v_mov_b32_e32 v112, 0
	v_mov_b32_e32 v113, v227
	v_mov_b32_e32 v114, v227
	v_mov_b32_e32 v115, v227
	v_mov_b32_e32 v116, v227
	v_mov_b32_e32 v117, v227
	v_mov_b32_e32 v118, v227
	v_mov_b32_e32 v119, v227
	v_mov_b32_e32 v120, v227
	v_mov_b32_e32 v121, v227
	v_mov_b32_e32 v122, v227
	v_mov_b32_e32 v123, v227
	v_mov_b32_e32 v124, v227
	v_mov_b32_e32 v125, v227
	v_mov_b32_e32 v126, v227
	v_mov_b32_e32 v127, v227
	v_readfirstlane_b32 s100, v219
	s_nop 3
	s_bfe_u32 s100, s100, 0x20006
.LBB0_507:
	s_cmp_lt_u32 s6, 3
	s_cselect_b64 s[0:1], -1, 0
	s_and_b64 s[10:11], s[0:1], exec
	s_cselect_b32 s7, 0, -6
	s_add_i32 s7, s7, s6
	s_waitcnt lgkmcnt(3)
	v_mfma_f32_32x32x16_bf16 v[112:127], v[192:195], v[200:203], v[112:127]
	s_lshl_b32 s7, s7, 7
	s_and_b64 s[10:11], s[0:1], exec
	s_cselect_b32 s11, s3, s47
	s_cselect_b32 s10, s2, s46
	s_addk_i32 s7, 0x180
	s_add_u32 s10, s10, s7
	s_addc_u32 s11, s11, 0
	v_mfma_f32_32x32x16_bf16 v[96:111], v[196:199], v[200:203], v[96:111]
	s_waitcnt lgkmcnt(2)
	s_waitcnt lgkmcnt(1)
	s_waitcnt lgkmcnt(0)
	s_and_b64 s[0:1], s[0:1], exec
	v_mfma_f32_32x32x16_bf16 v[80:95], v[192:195], v[212:215], v[80:95]
	s_cselect_b32 s0, s4, s48
	v_mfma_f32_32x32x16_bf16 v[64:79], v[196:199], v[212:215], v[64:79]
	s_cselect_b32 s1, s5, s49
	s_add_u32 s0, s0, s7
	s_addc_u32 s1, s1, 0
	s_cmp_eq_u32 s100, 0
	s_cbranch_scc0 .Lddp2_skip0
	v_dot2c_f32_bf16_e32 v227, v200, v200
	v_dot2c_f32_bf16_e32 v226, v212, v212
	v_dot2c_f32_bf16_e32 v225, v208, v208
	v_dot2c_f32_bf16_e32 v224, v204, v204
	v_dot2c_f32_bf16_e32 v227, v201, v201
	v_dot2c_f32_bf16_e32 v226, v213, v213
	v_dot2c_f32_bf16_e32 v225, v209, v209
	v_dot2c_f32_bf16_e32 v224, v205, v205
	v_dot2c_f32_bf16_e32 v227, v202, v202
	v_dot2c_f32_bf16_e32 v226, v214, v214
	v_dot2c_f32_bf16_e32 v225, v210, v210
	v_dot2c_f32_bf16_e32 v224, v206, v206
	v_dot2c_f32_bf16_e32 v227, v203, v203
	v_dot2c_f32_bf16_e32 v226, v215, v215
	v_dot2c_f32_bf16_e32 v225, v211, v211
	v_dot2c_f32_bf16_e32 v224, v207, v207
; #define G_ITER(R, kt_) do { const int k3 = (kt_) + 3; \
;         const char* pa = k3 < nk ? ga + k3 * 128 : ga_n + (k3 - nk) * 128; const char* pb = k3 < nk ? gb + k3 * 128 : gb_n + (k3 - nk) * 128; \
;         G_BODY(R, kt_, pa, pb); } while (0)
; template <int EPI, bool RS>
; DI void gemm_phase(unsigned char* smem, const bf16_t* __restrict__ A, int lda, const bf16_t* __restrict__ Bt, int K, int mt0, int nMt, int nNt, const EpiArgs& ea) {
;     ...
;     if (DEEP) {
;     ...
;       for (int kt = 0; kt < nk; kt += 2) { G_ITER(rg, kt); G_ITER(rh, kt + 1); }
.Lddp2_skip0:
	v_mfma_f32_32x32x16_bf16 v[48:63], v[192:195], v[208:211], v[48:63]
	v_mfma_f32_32x32x16_bf16 v[32:47], v[196:199], v[208:211], v[32:47]
	v_mfma_f32_32x32x16_bf16 v[16:31], v[192:195], v[204:207], v[16:31]
	v_mfma_f32_32x32x16_bf16 v[0:15], v[196:199], v[204:207], v[0:15]
	v_add_u32_e32 v231, s35, v237
	v_lshl_add_u64 v[232:233], s[10:11], 0, v[216:217]
	s_waitcnt vmcnt(7)
	ds_write_b128 v231, v[132:135]
	s_waitcnt vmcnt(6)
	ds_write_b128 v231, v[128:131] offset:36864
	v_lshl_add_u64 v[240:241], s[0:1], 0, v[220:221]
	global_load_dwordx4 v[132:135], v[232:233], off
	global_load_dwordx4 v[128:131], v[240:241], off
	s_waitcnt vmcnt(7)
	ds_write_b128 v231, v[152:155] offset:9216
	s_waitcnt vmcnt(6)
	ds_write_b128 v231, v[148:151] offset:46080
	v_add_co_u32_e32 v148, vcc, s34, v232
	s_nop 1
	v_addc_co_u32_e32 v149, vcc, 0, v233, vcc
	v_add_co_u32_e32 v150, vcc, s56, v240
	s_nop 1
	v_addc_co_u32_e32 v151, vcc, 0, v241, vcc
	global_load_dwordx4 v[152:155], v[148:149], off
	s_nop 0
	global_load_dwordx4 v[148:151], v[150:151], off
	ds_read_b128 v[192:195], v229 offset:36896
	ds_read_b128 v[196:199], v229 offset:41504
	ds_read_b128 v[200:203], v230 offset:32
	ds_read_b128 v[204:207], v230 offset:4640
	ds_read_b128 v[208:211], v230 offset:9248
	ds_read_b128 v[212:215], v230 offset:13856
	s_waitcnt lgkmcnt(3)
	v_mfma_f32_32x32x16_bf16 v[112:127], v[192:195], v[200:203], v[112:127]
	s_waitcnt lgkmcnt(2)
	s_waitcnt lgkmcnt(1)
	s_waitcnt lgkmcnt(0)
	v_mfma_f32_32x32x16_bf16 v[96:111], v[196:199], v[200:203], v[96:111]
	v_mfma_f32_32x32x16_bf16 v[80:95], v[192:195], v[204:207], v[80:95]
	s_cmp_eq_u32 s100, 1
	s_cbranch_scc0 .Lddp2_skip1
	v_dot2c_f32_bf16_e32 v227, v200, v200
	v_dot2c_f32_bf16_e32 v226, v204, v204
	v_dot2c_f32_bf16_e32 v225, v208, v208
	v_dot2c_f32_bf16_e32 v224, v212, v212
	v_dot2c_f32_bf16_e32 v227, v201, v201
	v_dot2c_f32_bf16_e32 v226, v205, v205
	v_dot2c_f32_bf16_e32 v225, v209, v209
	v_dot2c_f32_bf16_e32 v224, v213, v213
	v_dot2c_f32_bf16_e32 v227, v202, v202
	v_dot2c_f32_bf16_e32 v226, v206, v206
	v_dot2c_f32_bf16_e32 v225, v210, v210
	v_dot2c_f32_bf16_e32 v224, v214, v214
	v_dot2c_f32_bf16_e32 v227, v203, v203
	v_dot2c_f32_bf16_e32 v226, v207, v207
	v_dot2c_f32_bf16_e32 v225, v211, v211
	v_dot2c_f32_bf16_e32 v224, v215, v215
.Lddp2_skip1:
	v_mfma_f32_32x32x16_bf16 v[64:79], v[196:199], v[204:207], v[64:79]
	v_mfma_f32_32x32x16_bf16 v[48:63], v[192:195], v[208:211], v[48:63]
	v_mfma_f32_32x32x16_bf16 v[32:47], v[196:199], v[208:211], v[32:47]
	v_mfma_f32_32x32x16_bf16 v[16:31], v[192:195], v[212:215], v[16:31]
	v_mfma_f32_32x32x16_bf16 v[0:15], v[196:199], v[212:215], v[0:15]
	s_waitcnt vmcnt(7)
	ds_write_b128 v231, v[136:139] offset:18432
	s_waitcnt vmcnt(6)
	ds_write_b128 v231, v[144:147] offset:55296
	v_add_co_u32_e32 v136, vcc, s57, v232
	s_nop 1
	v_addc_co_u32_e32 v137, vcc, 0, v233, vcc
	v_add_co_u32_e32 v144, vcc, s94, v240
	global_load_dwordx4 v[136:139], v[136:137], off
	s_nop 0
	v_addc_co_u32_e32 v145, vcc, 0, v241, vcc
	global_load_dwordx4 v[144:147], v[144:145], off
	s_waitcnt vmcnt(7)
	ds_write_b128 v231, v[140:143] offset:27648
	s_waitcnt vmcnt(6)
	ds_write_b128 v231, v[156:159] offset:64512
	v_add_co_u32_e32 v140, vcc, s28, v232
	s_nop 1
	v_addc_co_u32_e32 v141, vcc, 0, v233, vcc
	v_add_co_u32_e32 v156, vcc, s91, v240
	global_load_dwordx4 v[140:143], v[140:141], off
	s_nop 0
	v_addc_co_u32_e32 v157, vcc, 0, v241, vcc
	global_load_dwordx4 v[156:159], v[156:157], off
	ds_read_b128 v[192:195], v229 offset:36928
	ds_read_b128 v[196:199], v229 offset:41536
	ds_read_b128 v[200:203], v230 offset:64
	ds_read_b128 v[204:207], v230 offset:4672
	ds_read_b128 v[208:211], v230 offset:9280
	ds_read_b128 v[212:215], v230 offset:13888
	s_waitcnt lgkmcnt(3)
	v_mfma_f32_32x32x16_bf16 v[112:127], v[192:195], v[200:203], v[112:127]
	s_waitcnt lgkmcnt(2)
	s_waitcnt lgkmcnt(1)
	s_waitcnt lgkmcnt(0)
	v_mfma_f32_32x32x16_bf16 v[96:111], v[196:199], v[200:203], v[96:111]
	v_mfma_f32_32x32x16_bf16 v[80:95], v[192:195], v[204:207], v[80:95]
	s_cmp_eq_u32 s100, 2
	s_cbranch_scc0 .Lddp2_skip2
	v_dot2c_f32_bf16_e32 v227, v200, v200
	v_dot2c_f32_bf16_e32 v226, v204, v204
	v_dot2c_f32_bf16_e32 v225, v208, v208
	v_dot2c_f32_bf16_e32 v224, v212, v212
	v_dot2c_f32_bf16_e32 v227, v201, v201
	v_dot2c_f32_bf16_e32 v226, v205, v205
	v_dot2c_f32_bf16_e32 v225, v209, v209
	v_dot2c_f32_bf16_e32 v224, v213, v213
	v_dot2c_f32_bf16_e32 v227, v202, v202
	v_dot2c_f32_bf16_e32 v226, v206, v206
	v_dot2c_f32_bf16_e32 v225, v210, v210
	v_dot2c_f32_bf16_e32 v224, v214, v214
	v_dot2c_f32_bf16_e32 v227, v203, v203
	v_dot2c_f32_bf16_e32 v226, v207, v207
	v_dot2c_f32_bf16_e32 v225, v211, v211
	v_dot2c_f32_bf16_e32 v224, v215, v215

; #define G_ITER(R, kt_) do { const int k3 = (kt_) + 3; \
;         const char* pa = k3 < nk ? ga + k3 * 128 : ga_n + (k3 - nk) * 128; const char* pb = k3 < nk ? gb + k3 * 128 : gb_n + (k3 - nk) * 128; \
;         G_BODY(R, kt_, pa, pb); } while (0)
; template <int EPI, bool RS>
; DI void gemm_phase(unsigned char* smem, const bf16_t* __restrict__ A, int lda, const bf16_t* __restrict__ Bt, int K, int mt0, int nMt, int nNt, const EpiArgs& ea) {
;     ...
;     if (DEEP) {
;     ...
;       for (int kt = 0; kt < nk; kt += 2) { G_ITER(rg, kt); G_ITER(rh, kt + 1); }
.Lddp2_skip3:
	s_barrier
	v_mfma_f32_32x32x16_bf16 v[64:79], v[196:199], v[204:207], v[64:79]
	v_mfma_f32_32x32x16_bf16 v[48:63], v[192:195], v[208:211], v[48:63]
	v_mfma_f32_32x32x16_bf16 v[32:47], v[196:199], v[208:211], v[32:47]
	v_mfma_f32_32x32x16_bf16 v[16:31], v[192:195], v[212:215], v[16:31]
	v_mfma_f32_32x32x16_bf16 v[0:15], v[196:199], v[212:215], v[0:15]
	v_add_u32_e32 v231, s35, v222
	ds_read_b128 v[192:195], v239
	ds_read_b128 v[196:199], v239 offset:4608
	ds_read_b128 v[200:203], v231
	ds_read_b128 v[204:207], v231 offset:4608
	ds_read_b128 v[208:211], v231 offset:9216
	ds_read_b128 v[212:215], v231 offset:13824
	s_waitcnt lgkmcnt(3)
	v_mfma_f32_32x32x16_bf16 v[112:127], v[192:195], v[200:203], v[112:127]
	s_cmp_eq_u32 s6, 0
	s_cselect_b32 s0, 0, -6
	s_cselect_b32 s1, s3, s47
	s_cselect_b32 s7, s2, s46
	s_cselect_b32 s10, s4, s48
	s_cselect_b32 s11, s5, s49
	s_add_i32 s0, s0, s6
	v_mfma_f32_32x32x16_bf16 v[96:111], v[196:199], v[200:203], v[96:111]
	s_lshl_b32 s0, s0, 7
	s_add_i32 s12, s0, 0x200
	s_waitcnt lgkmcnt(2)
	s_waitcnt lgkmcnt(1)
	s_waitcnt lgkmcnt(0)
	s_add_u32 s0, s7, s12
	v_mfma_f32_32x32x16_bf16 v[80:95], v[192:195], v[204:207], v[80:95]
	s_addc_u32 s1, s1, 0
	v_mfma_f32_32x32x16_bf16 v[64:79], v[196:199], v[204:207], v[64:79]
	s_add_u32 s10, s10, s12
	v_mfma_f32_32x32x16_bf16 v[48:63], v[192:195], v[208:211], v[48:63]
	s_addc_u32 s11, s11, 0
	s_cmp_eq_u32 s100, 0
	s_cbranch_scc0 .Lddp2_skip4
	v_dot2c_f32_bf16_e32 v227, v200, v200
	v_dot2c_f32_bf16_e32 v226, v204, v204
	v_dot2c_f32_bf16_e32 v225, v208, v208
	v_dot2c_f32_bf16_e32 v224, v212, v212
	v_dot2c_f32_bf16_e32 v227, v201, v201
	v_dot2c_f32_bf16_e32 v226, v205, v205
	v_dot2c_f32_bf16_e32 v225, v209, v209
	v_dot2c_f32_bf16_e32 v224, v213, v213
	v_dot2c_f32_bf16_e32 v227, v202, v202
	v_dot2c_f32_bf16_e32 v226, v206, v206
	v_dot2c_f32_bf16_e32 v225, v210, v210
	v_dot2c_f32_bf16_e32 v224, v214, v214
	v_dot2c_f32_bf16_e32 v227, v203, v203
	v_dot2c_f32_bf16_e32 v226, v207, v207
	v_dot2c_f32_bf16_e32 v225, v211, v211
	v_dot2c_f32_bf16_e32 v224, v215, v215
.Lddp2_skip4:
	v_mfma_f32_32x32x16_bf16 v[32:47], v[196:199], v[208:211], v[32:47]
	v_mfma_f32_32x32x16_bf16 v[16:31], v[192:195], v[212:215], v[16:31]
	v_mfma_f32_32x32x16_bf16 v[0:15], v[196:199], v[212:215], v[0:15]
	v_lshl_add_u64 v[232:233], s[0:1], 0, v[216:217]
	ds_write_b128 v228, v[172:175]
	ds_write_b128 v228, v[160:163] offset:36864
	ds_write_b128 v228, v[184:187] offset:9216
	ds_write_b128 v228, v[180:183] offset:46080
	v_add_co_u32_e32 v180, vcc, s34, v232
	v_lshl_add_u64 v[240:241], s[10:11], 0, v[220:221]
	s_nop 0
	v_addc_co_u32_e32 v181, vcc, 0, v233, vcc
	v_add_co_u32_e32 v182, vcc, s56, v240
	global_load_dwordx4 v[172:175], v[232:233], off
	global_load_dwordx4 v[160:163], v[240:241], off
	v_addc_co_u32_e32 v183, vcc, 0, v241, vcc
	global_load_dwordx4 v[184:187], v[180:181], off
	s_nop 0
	global_load_dwordx4 v[180:183], v[182:183], off
	ds_read_b128 v[192:195], v239 offset:32
	ds_read_b128 v[196:199], v239 offset:4640
	ds_read_b128 v[200:203], v231 offset:32
	ds_read_b128 v[204:207], v231 offset:4640
	ds_read_b128 v[208:211], v231 offset:9248
	ds_read_b128 v[212:215], v231 offset:13856
	s_waitcnt lgkmcnt(3)
	v_mfma_f32_32x32x16_bf16 v[112:127], v[192:195], v[200:203], v[112:127]
	s_waitcnt lgkmcnt(2)
	s_waitcnt lgkmcnt(1)
	s_waitcnt lgkmcnt(0)
	v_mfma_f32_32x32x16_bf16 v[96:111], v[196:199], v[200:203], v[96:111]
	v_mfma_f32_32x32x16_bf16 v[80:95], v[192:195], v[204:207], v[80:95]
	s_cmp_eq_u32 s100, 1
	s_cbranch_scc0 .Lddp2_skip5
	v_dot2c_f32_bf16_e32 v227, v200, v200
	v_dot2c_f32_bf16_e32 v226, v204, v204
	v_dot2c_f32_bf16_e32 v225, v208, v208
	v_dot2c_f32_bf16_e32 v224, v212, v212
	v_dot2c_f32_bf16_e32 v227, v201, v201
	v_dot2c_f32_bf16_e32 v226, v205, v205
	v_dot2c_f32_bf16_e32 v225, v209, v209
	v_dot2c_f32_bf16_e32 v224, v213, v213
	v_dot2c_f32_bf16_e32 v227, v202, v202
	v_dot2c_f32_bf16_e32 v226, v206, v206
	v_dot2c_f32_bf16_e32 v225, v210, v210
	v_dot2c_f32_bf16_e32 v224, v214, v214
	v_dot2c_f32_bf16_e32 v227, v203, v203
	v_dot2c_f32_bf16_e32 v226, v207, v207
	v_dot2c_f32_bf16_e32 v225, v211, v211
	v_dot2c_f32_bf16_e32 v224, v215, v215
.Lddp2_skip5:
	v_mfma_f32_32x32x16_bf16 v[64:79], v[196:199], v[204:207], v[64:79]
	v_mfma_f32_32x32x16_bf16 v[48:63], v[192:195], v[208:211], v[48:63]
	v_mfma_f32_32x32x16_bf16 v[32:47], v[196:199], v[208:211], v[32:47]
	v_mfma_f32_32x32x16_bf16 v[16:31], v[192:195], v[212:215], v[16:31]
	v_mfma_f32_32x32x16_bf16 v[0:15], v[196:199], v[212:215], v[0:15]
	ds_write_b128 v228, v[164:167] offset:18432
	ds_write_b128 v228, v[176:179] offset:55296
	v_add_co_u32_e32 v164, vcc, s57, v232
	s_nop 1
	v_addc_co_u32_e32 v165, vcc, 0, v233, vcc
	v_add_co_u32_e32 v176, vcc, s94, v240
	global_load_dwordx4 v[164:167], v[164:165], off
	s_nop 0
	v_addc_co_u32_e32 v177, vcc, 0, v241, vcc
	global_load_dwordx4 v[176:179], v[176:177], off
	ds_write_b128 v228, v[168:171] offset:27648
	ds_write_b128 v228, v[188:191] offset:64512
	v_add_co_u32_e32 v168, vcc, s28, v232
	s_nop 1
	v_addc_co_u32_e32 v169, vcc, 0, v233, vcc
	v_add_co_u32_e32 v188, vcc, s91, v240
	global_load_dwordx4 v[168:171], v[168:169], off
	s_nop 0
	v_addc_co_u32_e32 v189, vcc, 0, v241, vcc
	global_load_dwordx4 v[188:191], v[188:189], off
	ds_read_b128 v[192:195], v239 offset:64
	ds_read_b128 v[196:199], v239 offset:4672
	ds_read_b128 v[200:203], v231 offset:64
	ds_read_b128 v[204:207], v231 offset:4672
	ds_read_b128 v[208:211], v231 offset:9280
	ds_read_b128 v[212:215], v231 offset:13888
	s_waitcnt lgkmcnt(3)
	v_mfma_f32_32x32x16_bf16 v[112:127], v[192:195], v[200:203], v[112:127]
	s_waitcnt lgkmcnt(2)
	s_waitcnt lgkmcnt(1)
	s_waitcnt lgkmcnt(0)
	v_mfma_f32_32x32x16_bf16 v[96:111], v[196:199], v[200:203], v[96:111]
	v_mfma_f32_32x32x16_bf16 v[80:95], v[192:195], v[204:207], v[80:95]
	s_cmp_eq_u32 s100, 2
	s_cbranch_scc0 .Lddp2_skip6
	v_dot2c_f32_bf16_e32 v227, v200, v200
	v_dot2c_f32_bf16_e32 v226, v204, v204
	v_dot2c_f32_bf16_e32 v225, v208, v208
	v_dot2c_f32_bf16_e32 v224, v212, v212
	v_dot2c_f32_bf16_e32 v227, v201, v201
	v_dot2c_f32_bf16_e32 v226, v205, v205
	v_dot2c_f32_bf16_e32 v225, v209, v209
	v_dot2c_f32_bf16_e32 v224, v213, v213
	v_dot2c_f32_bf16_e32 v227, v202, v202
	v_dot2c_f32_bf16_e32 v226, v206, v206
	v_dot2c_f32_bf16_e32 v225, v210, v210
	v_dot2c_f32_bf16_e32 v224, v214, v214
	v_dot2c_f32_bf16_e32 v227, v203, v203
	v_dot2c_f32_bf16_e32 v226, v207, v207
	v_dot2c_f32_bf16_e32 v225, v211, v211
	v_dot2c_f32_bf16_e32 v224, v215, v215

; #define G_ITER(R, kt_) do { const int k3 = (kt_) + 3; \
;         const char* pa = k3 < nk ? ga + k3 * 128 : ga_n + (k3 - nk) * 128; const char* pb = k3 < nk ? gb + k3 * 128 : gb_n + (k3 - nk) * 128; \
;         G_BODY(R, kt_, pa, pb); } while (0)
; template <int EPI, bool RS>
; DI void gemm_epilogue(unsigned char* smem, f32x16 (&acc)[2][4], const float (&ssq)[4], int K, int m0, int nt256, const EpiArgs& ea, int wt, int wf, int r, int h) {
;     ...
;   if (RS) {
; #pragma unroll
;     for (int tb = 0; tb < 4; ++tb) { float s = ssq[tb]; s += __shfl_xor(s, 32); rstd[tb] = rsqrtf(s / (float)K + EPS); }
;   }
;   if (EPI == EPI_PLAIN) {
; #pragma unroll
;     for (int tb = 0; tb < 4; ++tb) {
;       const int tok = m0 + wt * 128 + tb * 32 + r; const float rs = rstd[tb];
;       bf16_t* rowp = ea.o0 + (size_t)tok * ea.ldc;
; #pragma unroll
;       for (int fb = 0; fb < 2; ++fb)
; #pragma unroll
;         for (int g4 = 0; g4 < 4; ++g4) {
;           const int col = n0 + wc * 64 + fb * 32 + g4 * 8 + 4 * h;
;           if (col < ea.nvalid && !ea.nostore) { u32x2 w; w[0] = pk2(acc[fb][tb][4 * g4] * rs, acc[fb][tb][4 * g4 + 1] * rs); w[1] = pk2(acc[fb][tb][4 * g4 + 2] * rs, acc[fb][tb][4 * g4 + 3] * rs); *(u32x2*)(rowp + col) = w; }
; template <int EPI, bool RS>
; DI void gemm_phase(unsigned char* smem, const bf16_t* __restrict__ A, int lda, const bf16_t* __restrict__ Bt, int K, int mt0, int nMt, int nNt, const EpiArgs& ea) {
;     ...
;       for (int kt = 0; kt < nk; kt += 2) { G_ITER(rg, kt); G_ITER(rh, kt + 1); }
.Lddp2_skip7:
	s_barrier
	v_mfma_f32_32x32x16_bf16 v[64:79], v[196:199], v[204:207], v[64:79]
	v_mfma_f32_32x32x16_bf16 v[48:63], v[192:195], v[208:211], v[48:63]
	v_mfma_f32_32x32x16_bf16 v[32:47], v[196:199], v[208:211], v[32:47]
	v_mfma_f32_32x32x16_bf16 v[16:31], v[192:195], v[212:215], v[16:31]
	v_mfma_f32_32x32x16_bf16 v[0:15], v[196:199], v[212:215], v[0:15]
	ds_read_b128 v[192:195], v229 offset:36864
	ds_read_b128 v[196:199], v229 offset:41472
	ds_read_b128 v[200:203], v230
	ds_read_b128 v[212:215], v230 offset:4608
	ds_read_b128 v[208:211], v230 offset:9216
	ds_read_b128 v[204:207], v230 offset:13824
	s_add_i32 s0, s6, 2
	s_cmp_gt_u32 s6, 3
	s_mov_b32 s6, s0
	s_cbranch_scc0 .LBB0_507
	v_lshlrev_b32_e32 v242, 2, v219
	v_add_u32_e32 v242, 0x24010, v242
	ds_write_b32 v242, v227
	ds_write_b32 v242, v226 offset:2048
	ds_write_b32 v242, v225 offset:4096
	ds_write_b32 v242, v224 offset:6144
	v_and_b32_e32 v243, 0x13f, v219
	v_lshlrev_b32_e32 v243, 2, v243
	v_add_u32_e32 v243, 0x24010, v243
	s_waitcnt lgkmcnt(0)
	s_barrier
	ds_read_b32 v244, v243
	ds_read_b32 v245, v243 offset:256
	ds_read_b32 v248, v243 offset:512
	ds_read_b32 v249, v243 offset:768
	s_waitcnt lgkmcnt(0)
	v_add_f32_e32 v227, v244, v245
	v_add_f32_e32 v227, v227, v248
	v_add_f32_e32 v227, v227, v249
	ds_read_b32 v244, v243 offset:2048
	ds_read_b32 v245, v243 offset:2304
	ds_read_b32 v248, v243 offset:2560
	ds_read_b32 v249, v243 offset:2816
	s_waitcnt lgkmcnt(0)
	v_add_f32_e32 v226, v244, v245
	v_add_f32_e32 v226, v226, v248
	v_add_f32_e32 v226, v226, v249
	ds_read_b32 v244, v243 offset:4096
	ds_read_b32 v245, v243 offset:4352
	ds_read_b32 v248, v243 offset:4608
	ds_read_b32 v249, v243 offset:4864
	s_waitcnt lgkmcnt(0)
	v_add_f32_e32 v225, v244, v245
	v_add_f32_e32 v225, v225, v248
	v_add_f32_e32 v225, v225, v249
	ds_read_b32 v244, v243 offset:6144
	ds_read_b32 v245, v243 offset:6400
	ds_read_b32 v248, v243 offset:6656
	ds_read_b32 v249, v243 offset:6912
	s_waitcnt lgkmcnt(0)
	v_add_f32_e32 v224, v244, v245
	v_add_f32_e32 v224, v224, v248
	v_add_f32_e32 v224, v224, v249
	v_and_b32_e32 v229, 64, v253
	v_xor_b32_e32 v228, 32, v253
	v_add_u32_e32 v229, 64, v229
	v_cmp_lt_i32_e32 vcc, v228, v229
	s_mov_b32 s2, 0x43c00000
	v_mov_b32_e32 v233, v235
	v_cndmask_b32_e32 v228, v253, v228, vcc
	v_lshlrev_b32_e32 v232, 2, v228
	ds_bpermute_b32 v229, v232, v227
	ds_bpermute_b32 v228, v232, v226
	s_waitcnt lgkmcnt(0)
	v_pk_add_f32 v[226:227], v[226:227], v[228:229]
	s_nop 0
	v_div_scale_f32 v228, s[0:1], s2, s2, v227
	v_rcp_f32_e32 v229, v228
	v_div_scale_f32 v230, vcc, v227, s2, v227
	v_fma_f32 v231, -v228, v229, 1.0
	v_fmac_f32_e32 v229, v231, v229
	v_mul_f32_e32 v231, v230, v229
	v_fma_f32 v240, -v228, v231, v230
	v_fmac_f32_e32 v231, v240, v229
	v_fma_f32 v228, -v228, v231, v230
	v_div_scale_f32 v230, s[0:1], s2, s2, v226
	v_rcp_f32_e32 v240, v230
	v_div_fmas_f32 v228, v228, v229, v231
	v_div_fixup_f32 v227, v228, s2, v227
	s_mov_b32 s0, 0x358637bd
	v_fma_f32 v228, -v230, v240, 1.0
	v_fmac_f32_e32 v240, v228, v240
	v_div_scale_f32 v228, vcc, v226, s2, v226
	v_mul_f32_e32 v229, v228, v240
	v_fma_f32 v231, -v230, v229, v228
	v_fmac_f32_e32 v229, v231, v240
	v_fma_f32 v228, -v230, v229, v228
	v_div_fmas_f32 v228, v228, v240, v229
	v_div_fixup_f32 v226, v228, s2, v226
	v_pk_add_f32 v[230:231], v[226:227], s[0:1] op_sel_hi:[1,0]
	v_mov_b32_e32 v227, v236
	v_mul_f32_e32 v226, 0x4b800000, v231
	v_cmp_gt_f32_e64 s[2:3], s67, v231
	ds_bpermute_b32 v229, v232, v225
	v_cmp_gt_f32_e32 vcc, s67, v230
	v_cndmask_b32_e64 v226, v231, v226, s[2:3]
	v_rsq_f32_e32 v226, v226
	v_add3_u32 v231, s9, v238, v233
	v_mul_f32_e32 v228, 0x45800000, v226
	v_cndmask_b32_e64 v240, v226, v228, s[2:3]
	ds_bpermute_b32 v228, v232, v224
	v_mov_b64_e32 v[232:233], s[68:69]
	v_lshl_or_b32 v226, s8, 8, v234
	v_mad_i64_i32 v[232:233], s[0:1], v231, s97, v[232:233]
	v_lshl_add_u32 v226, v227, 2, v226
	s_movk_i32 s0, 0x300
	v_cmp_gt_i32_e64 s[2:3], s0, v226
	v_ashrrev_i32_e32 v227, 31, v226
	s_and_saveexec_b64 s[4:5], s[2:3]
	s_cbranch_execz .LBB0_510
	v_mul_f32_e32 v112, v112, v240
	v_mul_f32_e32 v113, v113, v240
	v_cvt_pk_bf16_f32 v112, v112, v113
	v_mul_f32_e32 v113, v114, v240
	v_mul_f32_e32 v114, v115, v240
	v_cvt_pk_bf16_f32 v113, v113, v114
	v_lshl_add_u64 v[114:115], v[226:227], 1, v[232:233]
	global_store_dwordx2 v[114:115], v[112:113], off

; #define G_ITER(R, kt_) do { const int k3 = (kt_) + 3; \
;         const char* pa = k3 < nk ? ga + k3 * 128 : ga_n + (k3 - nk) * 128; const char* pb = k3 < nk ? gb + k3 * 128 : gb_n + (k3 - nk) * 128; \
;         G_BODY(R, kt_, pa, pb); } while (0)
; template <int EPI, bool RS>
; DI void gemm_phase(unsigned char* smem, const bf16_t* __restrict__ A, int lda, const bf16_t* __restrict__ Bt, int K, int mt0, int nMt, int nNt, const EpiArgs& ea) {
;     ...
;     f32x16 acc[2][4];
; #pragma unroll
;     for (int a = 0; a < 2; ++a)
; #pragma unroll
;       for (int b = 0; b < 4; ++b)
; #pragma unroll
;         for (int i = 0; i < 16; ++i) acc[a][b][i] = 0.f;
;     float ssq[4] = {0.f, 0.f, 0.f, 0.f};
;     ...
;     if (DEEP) {
;     ...
;       for (int kt = 0; kt < nk; kt += 2) { G_ITER(rg, kt); G_ITER(rh, kt + 1); }
.LBB0_604:
	s_ashr_i32 s37, s36, 31
	s_lshl_b32 s6, s33, 8
	s_ashr_i32 s7, s6, 31
	s_lshl_b64 s[10:11], s[36:37], 11
	s_add_u32 s46, s62, s10
	s_addc_u32 s47, s63, s11
	s_lshl_b64 s[6:7], s[6:7], 11
	s_add_u32 s48, s50, s6
	v_mov_b32_e32 v227, 0
	s_addc_u32 s49, s52, s7
	s_mov_b32 s6, -2
	v_mov_b32_e32 v226, 0
	v_mov_b32_e32 v225, 0
	v_mov_b32_e32 v224, v227
	v_mov_b32_e32 v0, 0
	v_mov_b32_e32 v1, v227
	v_mov_b32_e32 v2, v227
	v_mov_b32_e32 v3, v227
	v_mov_b32_e32 v4, v227
	v_mov_b32_e32 v5, v227
	v_mov_b32_e32 v6, v227
	v_mov_b32_e32 v7, v227
	v_mov_b32_e32 v8, v227
	v_mov_b32_e32 v9, v227
	v_mov_b32_e32 v10, v227
	v_mov_b32_e32 v11, v227
	v_mov_b32_e32 v12, v227
	v_mov_b32_e32 v13, v227
	v_mov_b32_e32 v14, v227
	v_mov_b32_e32 v15, v227
	v_mov_b32_e32 v32, 0
	v_mov_b32_e32 v33, v227
	v_mov_b32_e32 v34, v227
	v_mov_b32_e32 v35, v227
	v_mov_b32_e32 v36, v227
	v_mov_b32_e32 v37, v227
	v_mov_b32_e32 v38, v227
	v_mov_b32_e32 v39, v227
	v_mov_b32_e32 v40, v227
	v_mov_b32_e32 v41, v227
	v_mov_b32_e32 v42, v227
	v_mov_b32_e32 v43, v227
	v_mov_b32_e32 v44, v227
	v_mov_b32_e32 v45, v227
	v_mov_b32_e32 v46, v227
	v_mov_b32_e32 v47, v227
	v_mov_b32_e32 v64, 0
	v_mov_b32_e32 v65, v227
	v_mov_b32_e32 v66, v227
	v_mov_b32_e32 v67, v227
	v_mov_b32_e32 v68, v227
	v_mov_b32_e32 v69, v227
	v_mov_b32_e32 v70, v227
	v_mov_b32_e32 v71, v227
	v_mov_b32_e32 v72, v227
	v_mov_b32_e32 v73, v227
	v_mov_b32_e32 v74, v227
	v_mov_b32_e32 v75, v227
	v_mov_b32_e32 v76, v227
	v_mov_b32_e32 v77, v227
	v_mov_b32_e32 v78, v227
	v_mov_b32_e32 v79, v227
	v_mov_b32_e32 v96, 0
	v_mov_b32_e32 v97, v227
	v_mov_b32_e32 v98, v227
	v_mov_b32_e32 v99, v227
	v_mov_b32_e32 v100, v227
	v_mov_b32_e32 v101, v227
	v_mov_b32_e32 v102, v227
	v_mov_b32_e32 v103, v227
	v_mov_b32_e32 v104, v227
	v_mov_b32_e32 v105, v227
	v_mov_b32_e32 v106, v227
	v_mov_b32_e32 v107, v227
	v_mov_b32_e32 v108, v227
	v_mov_b32_e32 v109, v227
	v_mov_b32_e32 v110, v227
	v_mov_b32_e32 v111, v227
	v_mov_b32_e32 v16, 0
	v_mov_b32_e32 v17, v227
	v_mov_b32_e32 v18, v227
	v_mov_b32_e32 v19, v227
	v_mov_b32_e32 v20, v227
	v_mov_b32_e32 v21, v227
	v_mov_b32_e32 v22, v227
	v_mov_b32_e32 v23, v227
	v_mov_b32_e32 v24, v227
	v_mov_b32_e32 v25, v227
	v_mov_b32_e32 v26, v227
	v_mov_b32_e32 v27, v227
	v_mov_b32_e32 v28, v227
	v_mov_b32_e32 v29, v227
	v_mov_b32_e32 v30, v227
	v_mov_b32_e32 v31, v227
	v_mov_b32_e32 v48, 0
	v_mov_b32_e32 v49, v227
	v_mov_b32_e32 v50, v227
	v_mov_b32_e32 v51, v227
	v_mov_b32_e32 v52, v227
	v_mov_b32_e32 v53, v227
	v_mov_b32_e32 v54, v227
	v_mov_b32_e32 v55, v227
	v_mov_b32_e32 v56, v227
	v_mov_b32_e32 v57, v227
	v_mov_b32_e32 v58, v227
	v_mov_b32_e32 v59, v227
	v_mov_b32_e32 v60, v227
	v_mov_b32_e32 v61, v227
	v_mov_b32_e32 v62, v227
	v_mov_b32_e32 v63, v227
	s_waitcnt vmcnt(9)
	v_mov_b32_e32 v80, 0
	v_mov_b32_e32 v81, v227
	v_mov_b32_e32 v82, v227
	v_mov_b32_e32 v83, v227
	v_mov_b32_e32 v84, v227
	v_mov_b32_e32 v85, v227
	v_mov_b32_e32 v86, v227
	v_mov_b32_e32 v87, v227
	v_mov_b32_e32 v88, v227
	v_mov_b32_e32 v89, v227
	v_mov_b32_e32 v90, v227
	v_mov_b32_e32 v91, v227
	v_mov_b32_e32 v92, v227
	v_mov_b32_e32 v93, v227
	v_mov_b32_e32 v94, v227
	v_mov_b32_e32 v95, v227
	s_waitcnt vmcnt(8)
	v_mov_b32_e32 v112, 0
	v_mov_b32_e32 v113, v227
	v_mov_b32_e32 v114, v227
	v_mov_b32_e32 v115, v227
	v_mov_b32_e32 v116, v227
	v_mov_b32_e32 v117, v227
	v_mov_b32_e32 v118, v227
	v_mov_b32_e32 v119, v227
	v_mov_b32_e32 v120, v227
	v_mov_b32_e32 v121, v227
	v_mov_b32_e32 v122, v227
	v_mov_b32_e32 v123, v227
	v_mov_b32_e32 v124, v227
	v_mov_b32_e32 v125, v227
	v_mov_b32_e32 v126, v227
	v_mov_b32_e32 v127, v227
	v_readfirstlane_b32 s100, v219
	s_nop 3
	s_bfe_u32 s100, s100, 0x20006
.LBB0_605:
	s_add_i32 s7, s6, 2
	s_cmp_lt_u32 s7, 13
	s_cselect_b64 s[10:11], -1, 0
	s_and_b64 s[12:13], s[10:11], exec
	s_cselect_b32 s12, 0, -16
	s_add_i32 s12, s12, s6
	s_waitcnt lgkmcnt(3)
	v_mfma_f32_32x32x16_bf16 v[112:127], v[192:195], v[200:203], v[112:127]
	s_lshl_b32 s14, s12, 7
	s_and_b64 s[12:13], s[10:11], exec
	s_cselect_b32 s13, s3, s47
	s_cselect_b32 s12, s2, s46
	s_addk_i32 s14, 0x280
	s_add_u32 s12, s12, s14
	s_addc_u32 s13, s13, 0
	v_mfma_f32_32x32x16_bf16 v[96:111], v[196:199], v[200:203], v[96:111]
	s_waitcnt lgkmcnt(2)
	s_waitcnt lgkmcnt(1)
	s_waitcnt lgkmcnt(0)
	s_and_b64 s[10:11], s[10:11], exec
	v_mfma_f32_32x32x16_bf16 v[80:95], v[192:195], v[212:215], v[80:95]
	s_cselect_b32 s10, s4, s48
	v_mfma_f32_32x32x16_bf16 v[64:79], v[196:199], v[212:215], v[64:79]
	s_cselect_b32 s11, s5, s49
	s_add_u32 s10, s10, s14
	s_addc_u32 s11, s11, 0
	s_cmp_eq_u32 s100, 0
	s_cbranch_scc0 .Lddp3_skip0
	v_dot2c_f32_bf16_e32 v227, v200, v200
	v_dot2c_f32_bf16_e32 v226, v212, v212
	v_dot2c_f32_bf16_e32 v225, v208, v208
	v_dot2c_f32_bf16_e32 v224, v204, v204
	v_dot2c_f32_bf16_e32 v227, v201, v201
	v_dot2c_f32_bf16_e32 v226, v213, v213
	v_dot2c_f32_bf16_e32 v225, v209, v209
	v_dot2c_f32_bf16_e32 v224, v205, v205
	v_dot2c_f32_bf16_e32 v227, v202, v202
	v_dot2c_f32_bf16_e32 v226, v214, v214
	v_dot2c_f32_bf16_e32 v225, v210, v210
	v_dot2c_f32_bf16_e32 v224, v206, v206
	v_dot2c_f32_bf16_e32 v227, v203, v203
	v_dot2c_f32_bf16_e32 v226, v215, v215
	v_dot2c_f32_bf16_e32 v225, v211, v211
	v_dot2c_f32_bf16_e32 v224, v207, v207
; #define G_ITER(R, kt_) do { const int k3 = (kt_) + 3; \
;         const char* pa = k3 < nk ? ga + k3 * 128 : ga_n + (k3 - nk) * 128; const char* pb = k3 < nk ? gb + k3 * 128 : gb_n + (k3 - nk) * 128; \
;         G_BODY(R, kt_, pa, pb); } while (0)
; template <int EPI, bool RS>
; DI void gemm_phase(unsigned char* smem, const bf16_t* __restrict__ A, int lda, const bf16_t* __restrict__ Bt, int K, int mt0, int nMt, int nNt, const EpiArgs& ea) {
;     ...
;     if (DEEP) {
;     ...
;       for (int kt = 0; kt < nk; kt += 2) { G_ITER(rg, kt); G_ITER(rh, kt + 1); }
.Lddp3_skip0:
	v_mfma_f32_32x32x16_bf16 v[48:63], v[192:195], v[208:211], v[48:63]
	v_mfma_f32_32x32x16_bf16 v[32:47], v[196:199], v[208:211], v[32:47]
	v_mfma_f32_32x32x16_bf16 v[16:31], v[192:195], v[204:207], v[16:31]
	v_mfma_f32_32x32x16_bf16 v[0:15], v[196:199], v[204:207], v[0:15]
	v_add_u32_e32 v231, s35, v220
	v_lshl_add_u64 v[232:233], s[12:13], 0, v[216:217]
	s_waitcnt vmcnt(7)
	ds_write_b128 v231, v[132:135]
	s_waitcnt vmcnt(6)
	ds_write_b128 v231, v[128:131] offset:36864
	v_lshl_add_u64 v[238:239], s[10:11], 0, v[216:217]
	global_load_dwordx4 v[132:135], v[232:233], off
	global_load_dwordx4 v[128:131], v[238:239], off
	s_waitcnt vmcnt(7)
	ds_write_b128 v231, v[152:155] offset:9216
	s_waitcnt vmcnt(6)
	ds_write_b128 v231, v[148:151] offset:46080
	v_add_co_u32_e32 v148, vcc, s42, v232
	s_nop 1
	v_addc_co_u32_e32 v149, vcc, 0, v233, vcc
	v_add_co_u32_e32 v150, vcc, s42, v238
	s_nop 1
	v_addc_co_u32_e32 v151, vcc, 0, v239, vcc
	global_load_dwordx4 v[152:155], v[148:149], off
	s_nop 0
	global_load_dwordx4 v[148:151], v[150:151], off
	ds_read_b128 v[192:195], v229 offset:36896
	ds_read_b128 v[196:199], v229 offset:41504
	ds_read_b128 v[200:203], v230 offset:32
	ds_read_b128 v[204:207], v230 offset:4640
	ds_read_b128 v[208:211], v230 offset:9248
	ds_read_b128 v[212:215], v230 offset:13856
	s_waitcnt lgkmcnt(3)
	v_mfma_f32_32x32x16_bf16 v[112:127], v[192:195], v[200:203], v[112:127]
	s_waitcnt lgkmcnt(2)
	s_waitcnt lgkmcnt(1)
	s_waitcnt lgkmcnt(0)
	v_mfma_f32_32x32x16_bf16 v[96:111], v[196:199], v[200:203], v[96:111]
	v_mfma_f32_32x32x16_bf16 v[80:95], v[192:195], v[204:207], v[80:95]
	s_cmp_eq_u32 s100, 1
	s_cbranch_scc0 .Lddp3_skip1
	v_dot2c_f32_bf16_e32 v227, v200, v200
	v_dot2c_f32_bf16_e32 v226, v204, v204
	v_dot2c_f32_bf16_e32 v225, v208, v208
	v_dot2c_f32_bf16_e32 v224, v212, v212
	v_dot2c_f32_bf16_e32 v227, v201, v201
	v_dot2c_f32_bf16_e32 v226, v205, v205
	v_dot2c_f32_bf16_e32 v225, v209, v209
	v_dot2c_f32_bf16_e32 v224, v213, v213
	v_dot2c_f32_bf16_e32 v227, v202, v202
	v_dot2c_f32_bf16_e32 v226, v206, v206
	v_dot2c_f32_bf16_e32 v225, v210, v210
	v_dot2c_f32_bf16_e32 v224, v214, v214
	v_dot2c_f32_bf16_e32 v227, v203, v203
	v_dot2c_f32_bf16_e32 v226, v207, v207
	v_dot2c_f32_bf16_e32 v225, v211, v211
	v_dot2c_f32_bf16_e32 v224, v215, v215
.Lddp3_skip1:
	v_mfma_f32_32x32x16_bf16 v[64:79], v[196:199], v[204:207], v[64:79]
	v_mfma_f32_32x32x16_bf16 v[48:63], v[192:195], v[208:211], v[48:63]
	v_mfma_f32_32x32x16_bf16 v[32:47], v[196:199], v[208:211], v[32:47]
	v_mfma_f32_32x32x16_bf16 v[16:31], v[192:195], v[212:215], v[16:31]
	v_mfma_f32_32x32x16_bf16 v[0:15], v[196:199], v[212:215], v[0:15]
	s_waitcnt vmcnt(7)
	ds_write_b128 v231, v[136:139] offset:18432
	s_waitcnt vmcnt(6)
	ds_write_b128 v231, v[144:147] offset:55296
	v_add_co_u32_e32 v136, vcc, s43, v232
	s_nop 1
	v_addc_co_u32_e32 v137, vcc, 0, v233, vcc
	v_add_co_u32_e32 v144, vcc, s43, v238
	global_load_dwordx4 v[136:139], v[136:137], off
	s_nop 0
	v_addc_co_u32_e32 v145, vcc, 0, v239, vcc
	global_load_dwordx4 v[144:147], v[144:145], off
	s_waitcnt vmcnt(7)
	ds_write_b128 v231, v[140:143] offset:27648
	s_waitcnt vmcnt(6)
	ds_write_b128 v231, v[156:159] offset:64512
	v_add_co_u32_e32 v140, vcc, s75, v232
	s_nop 1
	v_addc_co_u32_e32 v141, vcc, 0, v233, vcc
	v_add_co_u32_e32 v156, vcc, s75, v238
	global_load_dwordx4 v[140:143], v[140:141], off
	s_nop 0
	v_addc_co_u32_e32 v157, vcc, 0, v239, vcc
	global_load_dwordx4 v[156:159], v[156:157], off
	ds_read_b128 v[192:195], v229 offset:36928
	ds_read_b128 v[196:199], v229 offset:41536
	ds_read_b128 v[200:203], v230 offset:64
	ds_read_b128 v[204:207], v230 offset:4672
	ds_read_b128 v[208:211], v230 offset:9280
	ds_read_b128 v[212:215], v230 offset:13888
	s_waitcnt lgkmcnt(3)
	v_mfma_f32_32x32x16_bf16 v[112:127], v[192:195], v[200:203], v[112:127]
	s_waitcnt lgkmcnt(2)
	s_waitcnt lgkmcnt(1)
	s_waitcnt lgkmcnt(0)
	v_mfma_f32_32x32x16_bf16 v[96:111], v[196:199], v[200:203], v[96:111]
	v_mfma_f32_32x32x16_bf16 v[80:95], v[192:195], v[204:207], v[80:95]
	s_cmp_eq_u32 s100, 2
	s_cbranch_scc0 .Lddp3_skip2
	v_dot2c_f32_bf16_e32 v227, v200, v200
	v_dot2c_f32_bf16_e32 v226, v204, v204
	v_dot2c_f32_bf16_e32 v225, v208, v208
	v_dot2c_f32_bf16_e32 v224, v212, v212
	v_dot2c_f32_bf16_e32 v227, v201, v201
	v_dot2c_f32_bf16_e32 v226, v205, v205
	v_dot2c_f32_bf16_e32 v225, v209, v209
	v_dot2c_f32_bf16_e32 v224, v213, v213
	v_dot2c_f32_bf16_e32 v227, v202, v202
	v_dot2c_f32_bf16_e32 v226, v206, v206
	v_dot2c_f32_bf16_e32 v225, v210, v210
	v_dot2c_f32_bf16_e32 v224, v214, v214
	v_dot2c_f32_bf16_e32 v227, v203, v203
	v_dot2c_f32_bf16_e32 v226, v207, v207
	v_dot2c_f32_bf16_e32 v225, v211, v211
	v_dot2c_f32_bf16_e32 v224, v215, v215

; #define G_ITER(R, kt_) do { const int k3 = (kt_) + 3; \
;         const char* pa = k3 < nk ? ga + k3 * 128 : ga_n + (k3 - nk) * 128; const char* pb = k3 < nk ? gb + k3 * 128 : gb_n + (k3 - nk) * 128; \
;         G_BODY(R, kt_, pa, pb); } while (0)
; template <int EPI, bool RS>
; DI void gemm_phase(unsigned char* smem, const bf16_t* __restrict__ A, int lda, const bf16_t* __restrict__ Bt, int K, int mt0, int nMt, int nNt, const EpiArgs& ea) {
;     ...
;     if (DEEP) {
;     ...
;       for (int kt = 0; kt < nk; kt += 2) { G_ITER(rg, kt); G_ITER(rh, kt + 1); }
.Lddp3_skip3:
	s_barrier
	v_mfma_f32_32x32x16_bf16 v[64:79], v[196:199], v[204:207], v[64:79]
	v_mfma_f32_32x32x16_bf16 v[48:63], v[192:195], v[208:211], v[48:63]
	v_mfma_f32_32x32x16_bf16 v[32:47], v[196:199], v[208:211], v[32:47]
	v_mfma_f32_32x32x16_bf16 v[16:31], v[192:195], v[212:215], v[16:31]
	v_mfma_f32_32x32x16_bf16 v[0:15], v[196:199], v[212:215], v[0:15]
	v_add_u32_e32 v231, s35, v222
	ds_read_b128 v[192:195], v237
	ds_read_b128 v[196:199], v237 offset:4608
	ds_read_b128 v[200:203], v231
	ds_read_b128 v[204:207], v231 offset:4608
	ds_read_b128 v[208:211], v231 offset:9216
	ds_read_b128 v[212:215], v231 offset:13824
	s_cmp_lt_u32 s7, 12
	s_cselect_b64 s[10:11], -1, 0
	s_and_b64 s[12:13], s[10:11], exec
	s_cselect_b32 s12, 0, -16
	s_add_i32 s12, s12, s6
	s_waitcnt lgkmcnt(3)
	v_mfma_f32_32x32x16_bf16 v[112:127], v[192:195], v[200:203], v[112:127]
	s_lshl_b32 s6, s12, 7
	s_and_b64 s[12:13], s[10:11], exec
	s_cselect_b32 s13, s3, s47
	s_cselect_b32 s12, s2, s46
	s_addk_i32 s6, 0x300
	s_add_u32 s12, s12, s6
	s_addc_u32 s13, s13, 0
	v_mfma_f32_32x32x16_bf16 v[96:111], v[196:199], v[200:203], v[96:111]
	s_waitcnt lgkmcnt(2)
	s_waitcnt lgkmcnt(1)
	s_waitcnt lgkmcnt(0)
	s_and_b64 s[10:11], s[10:11], exec
	v_mfma_f32_32x32x16_bf16 v[80:95], v[192:195], v[204:207], v[80:95]
	s_cselect_b32 s10, s4, s48
	v_mfma_f32_32x32x16_bf16 v[64:79], v[196:199], v[204:207], v[64:79]
	s_cselect_b32 s11, s5, s49
	s_add_u32 s10, s10, s6
	s_addc_u32 s11, s11, 0
	s_cmp_eq_u32 s100, 0
	s_cbranch_scc0 .Lddp3_skip4
	v_dot2c_f32_bf16_e32 v227, v200, v200
	v_dot2c_f32_bf16_e32 v226, v204, v204
	v_dot2c_f32_bf16_e32 v225, v208, v208
	v_dot2c_f32_bf16_e32 v224, v212, v212
	v_dot2c_f32_bf16_e32 v227, v201, v201
	v_dot2c_f32_bf16_e32 v226, v205, v205
	v_dot2c_f32_bf16_e32 v225, v209, v209
	v_dot2c_f32_bf16_e32 v224, v213, v213
	v_dot2c_f32_bf16_e32 v227, v202, v202
	v_dot2c_f32_bf16_e32 v226, v206, v206
	v_dot2c_f32_bf16_e32 v225, v210, v210
	v_dot2c_f32_bf16_e32 v224, v214, v214
	v_dot2c_f32_bf16_e32 v227, v203, v203
	v_dot2c_f32_bf16_e32 v226, v207, v207
	v_dot2c_f32_bf16_e32 v225, v211, v211
	v_dot2c_f32_bf16_e32 v224, v215, v215
.Lddp3_skip4:
	v_mfma_f32_32x32x16_bf16 v[48:63], v[192:195], v[208:211], v[48:63]
	v_mfma_f32_32x32x16_bf16 v[32:47], v[196:199], v[208:211], v[32:47]
	v_mfma_f32_32x32x16_bf16 v[16:31], v[192:195], v[212:215], v[16:31]
	v_mfma_f32_32x32x16_bf16 v[0:15], v[196:199], v[212:215], v[0:15]
	v_lshl_add_u64 v[232:233], s[12:13], 0, v[216:217]
	ds_write_b128 v228, v[172:175]
	ds_write_b128 v228, v[160:163] offset:36864
	ds_write_b128 v228, v[184:187] offset:9216
	ds_write_b128 v228, v[180:183] offset:46080
	v_add_co_u32_e32 v180, vcc, s42, v232
	v_lshl_add_u64 v[238:239], s[10:11], 0, v[216:217]
	s_nop 0
	v_addc_co_u32_e32 v181, vcc, 0, v233, vcc
	v_add_co_u32_e32 v182, vcc, s42, v238
	global_load_dwordx4 v[172:175], v[232:233], off
	global_load_dwordx4 v[160:163], v[238:239], off
	v_addc_co_u32_e32 v183, vcc, 0, v239, vcc
	global_load_dwordx4 v[184:187], v[180:181], off
	s_nop 0
	global_load_dwordx4 v[180:183], v[182:183], off
	ds_read_b128 v[192:195], v237 offset:32
	ds_read_b128 v[196:199], v237 offset:4640
	ds_read_b128 v[200:203], v231 offset:32
	ds_read_b128 v[204:207], v231 offset:4640
	ds_read_b128 v[208:211], v231 offset:9248
	ds_read_b128 v[212:215], v231 offset:13856
	s_waitcnt lgkmcnt(3)
	v_mfma_f32_32x32x16_bf16 v[112:127], v[192:195], v[200:203], v[112:127]
	s_waitcnt lgkmcnt(2)
	s_waitcnt lgkmcnt(1)
	s_waitcnt lgkmcnt(0)
	v_mfma_f32_32x32x16_bf16 v[96:111], v[196:199], v[200:203], v[96:111]
	v_mfma_f32_32x32x16_bf16 v[80:95], v[192:195], v[204:207], v[80:95]
	s_cmp_eq_u32 s100, 1
	s_cbranch_scc0 .Lddp3_skip5
	v_dot2c_f32_bf16_e32 v227, v200, v200
	v_dot2c_f32_bf16_e32 v226, v204, v204
	v_dot2c_f32_bf16_e32 v225, v208, v208
	v_dot2c_f32_bf16_e32 v224, v212, v212
	v_dot2c_f32_bf16_e32 v227, v201, v201
	v_dot2c_f32_bf16_e32 v226, v205, v205
	v_dot2c_f32_bf16_e32 v225, v209, v209
	v_dot2c_f32_bf16_e32 v224, v213, v213
	v_dot2c_f32_bf16_e32 v227, v202, v202
	v_dot2c_f32_bf16_e32 v226, v206, v206
	v_dot2c_f32_bf16_e32 v225, v210, v210
	v_dot2c_f32_bf16_e32 v224, v214, v214
	v_dot2c_f32_bf16_e32 v227, v203, v203
	v_dot2c_f32_bf16_e32 v226, v207, v207
	v_dot2c_f32_bf16_e32 v225, v211, v211
	v_dot2c_f32_bf16_e32 v224, v215, v215
.Lddp3_skip5:
	v_mfma_f32_32x32x16_bf16 v[64:79], v[196:199], v[204:207], v[64:79]
	v_mfma_f32_32x32x16_bf16 v[48:63], v[192:195], v[208:211], v[48:63]
	v_mfma_f32_32x32x16_bf16 v[32:47], v[196:199], v[208:211], v[32:47]
	v_mfma_f32_32x32x16_bf16 v[16:31], v[192:195], v[212:215], v[16:31]
	v_mfma_f32_32x32x16_bf16 v[0:15], v[196:199], v[212:215], v[0:15]
	ds_write_b128 v228, v[164:167] offset:18432
	ds_write_b128 v228, v[176:179] offset:55296
	v_add_co_u32_e32 v164, vcc, s43, v232
	s_nop 1
	v_addc_co_u32_e32 v165, vcc, 0, v233, vcc
	v_add_co_u32_e32 v176, vcc, s43, v238
	global_load_dwordx4 v[164:167], v[164:165], off
	s_nop 0
	v_addc_co_u32_e32 v177, vcc, 0, v239, vcc
	global_load_dwordx4 v[176:179], v[176:177], off
	ds_write_b128 v228, v[168:171] offset:27648
	ds_write_b128 v228, v[188:191] offset:64512
	v_add_co_u32_e32 v168, vcc, s75, v232
	s_nop 1
	v_addc_co_u32_e32 v169, vcc, 0, v233, vcc
	v_add_co_u32_e32 v188, vcc, s75, v238
	global_load_dwordx4 v[168:171], v[168:169], off
	s_nop 0
	v_addc_co_u32_e32 v189, vcc, 0, v239, vcc
	global_load_dwordx4 v[188:191], v[188:189], off
	ds_read_b128 v[192:195], v237 offset:64
	ds_read_b128 v[196:199], v237 offset:4672
	ds_read_b128 v[200:203], v231 offset:64
	ds_read_b128 v[204:207], v231 offset:4672
	ds_read_b128 v[208:211], v231 offset:9280
	ds_read_b128 v[212:215], v231 offset:13888
	s_waitcnt lgkmcnt(3)
	v_mfma_f32_32x32x16_bf16 v[112:127], v[192:195], v[200:203], v[112:127]
	s_waitcnt lgkmcnt(2)
	s_waitcnt lgkmcnt(1)
	s_waitcnt lgkmcnt(0)
	v_mfma_f32_32x32x16_bf16 v[96:111], v[196:199], v[200:203], v[96:111]
	v_mfma_f32_32x32x16_bf16 v[80:95], v[192:195], v[204:207], v[80:95]
	s_cmp_eq_u32 s100, 2
	s_cbranch_scc0 .Lddp3_skip6
	v_dot2c_f32_bf16_e32 v227, v200, v200
	v_dot2c_f32_bf16_e32 v226, v204, v204
	v_dot2c_f32_bf16_e32 v225, v208, v208
	v_dot2c_f32_bf16_e32 v224, v212, v212
	v_dot2c_f32_bf16_e32 v227, v201, v201
	v_dot2c_f32_bf16_e32 v226, v205, v205
	v_dot2c_f32_bf16_e32 v225, v209, v209
	v_dot2c_f32_bf16_e32 v224, v213, v213
	v_dot2c_f32_bf16_e32 v227, v202, v202
	v_dot2c_f32_bf16_e32 v226, v206, v206
	v_dot2c_f32_bf16_e32 v225, v210, v210
	v_dot2c_f32_bf16_e32 v224, v214, v214
	v_dot2c_f32_bf16_e32 v227, v203, v203
	v_dot2c_f32_bf16_e32 v226, v207, v207
	v_dot2c_f32_bf16_e32 v225, v211, v211
	v_dot2c_f32_bf16_e32 v224, v215, v215
; #define G_ITER(R, kt_) do { const int k3 = (kt_) + 3; \
;         const char* pa = k3 < nk ? ga + k3 * 128 : ga_n + (k3 - nk) * 128; const char* pb = k3 < nk ? gb + k3 * 128 : gb_n + (k3 - nk) * 128; \
;         G_BODY(R, kt_, pa, pb); } while (0)
; template <int EPI, bool RS>
; DI void gemm_epilogue(unsigned char* smem, f32x16 (&acc)[2][4], const float (&ssq)[4], int K, int m0, int nt256, const EpiArgs& ea, int wt, int wf, int r, int h) {
;     ...
;   if (RS) {
; #pragma unroll
;     for (int tb = 0; tb < 4; ++tb) { float s = ssq[tb]; s += __shfl_xor(s, 32); rstd[tb] = rsqrtf(s / (float)K + EPS); }
;   }
;   if (EPI == EPI_PLAIN) {
; #pragma unroll
;     for (int tb = 0; tb < 4; ++tb) {
;       const int tok = m0 + wt * 128 + tb * 32 + r; const float rs = rstd[tb];
;       bf16_t* rowp = ea.o0 + (size_t)tok * ea.ldc;
; #pragma unroll
;       for (int fb = 0; fb < 2; ++fb)
; #pragma unroll
;         for (int g4 = 0; g4 < 4; ++g4) {
;           const int col = n0 + wc * 64 + fb * 32 + g4 * 8 + 4 * h;
;           if (col < ea.nvalid && !ea.nostore) { u32x2 w; w[0] = pk2(acc[fb][tb][4 * g4] * rs, acc[fb][tb][4 * g4 + 1] * rs); w[1] = pk2(acc[fb][tb][4 * g4 + 2] * rs, acc[fb][tb][4 * g4 + 3] * rs); *(u32x2*)(rowp + col) = w; }
; template <int EPI, bool RS>
; DI void gemm_phase(unsigned char* smem, const bf16_t* __restrict__ A, int lda, const bf16_t* __restrict__ Bt, int K, int mt0, int nMt, int nNt, const EpiArgs& ea) {
;     ...
;     if (DEEP) {
;     ...
;       for (int kt = 0; kt < nk; kt += 2) { G_ITER(rg, kt); G_ITER(rh, kt + 1); }
.Lddp3_skip6:
	v_mfma_f32_32x32x16_bf16 v[64:79], v[196:199], v[204:207], v[64:79]
	v_mfma_f32_32x32x16_bf16 v[48:63], v[192:195], v[208:211], v[48:63]
	v_mfma_f32_32x32x16_bf16 v[32:47], v[196:199], v[208:211], v[32:47]
	v_mfma_f32_32x32x16_bf16 v[16:31], v[192:195], v[212:215], v[16:31]
	v_mfma_f32_32x32x16_bf16 v[0:15], v[196:199], v[212:215], v[0:15]
	ds_read_b128 v[192:195], v237 offset:96
	ds_read_b128 v[196:199], v237 offset:4704
	ds_read_b128 v[200:203], v231 offset:96
	ds_read_b128 v[204:207], v231 offset:4704
	ds_read_b128 v[208:211], v231 offset:9312
	ds_read_b128 v[212:215], v231 offset:13920
	s_waitcnt lgkmcnt(3)
	v_mfma_f32_32x32x16_bf16 v[112:127], v[192:195], v[200:203], v[112:127]
	s_waitcnt lgkmcnt(2)
	s_waitcnt lgkmcnt(1)
	s_waitcnt lgkmcnt(0)
	v_mfma_f32_32x32x16_bf16 v[96:111], v[196:199], v[200:203], v[96:111]
	v_mfma_f32_32x32x16_bf16 v[80:95], v[192:195], v[204:207], v[80:95]
	s_cmp_eq_u32 s100, 3
	s_cbranch_scc0 .Lddp3_skip7
	v_dot2c_f32_bf16_e32 v227, v200, v200
	v_dot2c_f32_bf16_e32 v226, v204, v204
	v_dot2c_f32_bf16_e32 v225, v208, v208
	v_dot2c_f32_bf16_e32 v224, v212, v212
	v_dot2c_f32_bf16_e32 v227, v201, v201
	v_dot2c_f32_bf16_e32 v226, v205, v205
	v_dot2c_f32_bf16_e32 v225, v209, v209
	v_dot2c_f32_bf16_e32 v224, v213, v213
	v_dot2c_f32_bf16_e32 v227, v202, v202
	v_dot2c_f32_bf16_e32 v226, v206, v206
	v_dot2c_f32_bf16_e32 v225, v210, v210
	v_dot2c_f32_bf16_e32 v224, v214, v214
	v_dot2c_f32_bf16_e32 v227, v203, v203
	v_dot2c_f32_bf16_e32 v226, v207, v207
	v_dot2c_f32_bf16_e32 v225, v211, v211
	v_dot2c_f32_bf16_e32 v224, v215, v215
.Lddp3_skip7:
	s_barrier
	v_mfma_f32_32x32x16_bf16 v[64:79], v[196:199], v[204:207], v[64:79]
	v_mfma_f32_32x32x16_bf16 v[48:63], v[192:195], v[208:211], v[48:63]
	v_mfma_f32_32x32x16_bf16 v[32:47], v[196:199], v[208:211], v[32:47]
	v_mfma_f32_32x32x16_bf16 v[16:31], v[192:195], v[212:215], v[16:31]
	v_mfma_f32_32x32x16_bf16 v[0:15], v[196:199], v[212:215], v[0:15]
	ds_read_b128 v[192:195], v229 offset:36864
	ds_read_b128 v[196:199], v229 offset:41472
	ds_read_b128 v[200:203], v230
	ds_read_b128 v[212:215], v230 offset:4608
	ds_read_b128 v[208:211], v230 offset:9216
	ds_read_b128 v[204:207], v230 offset:13824
	s_cmp_gt_u32 s7, 13
	s_mov_b32 s6, s7
	s_cbranch_scc0 .LBB0_605
	v_lshlrev_b32_e32 v242, 2, v219
	v_add_u32_e32 v242, 0x24010, v242
	ds_write_b32 v242, v227
	ds_write_b32 v242, v226 offset:2048
	ds_write_b32 v242, v225 offset:4096
	ds_write_b32 v242, v224 offset:6144
	v_and_b32_e32 v243, 0x13f, v219
	v_lshlrev_b32_e32 v243, 2, v243
	v_add_u32_e32 v243, 0x24010, v243
	s_waitcnt lgkmcnt(0)
	s_barrier
	ds_read_b32 v244, v243
	ds_read_b32 v245, v243 offset:256
	ds_read_b32 v248, v243 offset:512
	ds_read_b32 v249, v243 offset:768
	s_waitcnt lgkmcnt(0)
	v_add_f32_e32 v227, v244, v245
	v_add_f32_e32 v227, v227, v248
	v_add_f32_e32 v227, v227, v249
	ds_read_b32 v244, v243 offset:2048
	ds_read_b32 v245, v243 offset:2304
	ds_read_b32 v248, v243 offset:2560
	ds_read_b32 v249, v243 offset:2816
	s_waitcnt lgkmcnt(0)
	v_add_f32_e32 v226, v244, v245
	v_add_f32_e32 v226, v226, v248
	v_add_f32_e32 v226, v226, v249
	ds_read_b32 v244, v243 offset:4096
	ds_read_b32 v245, v243 offset:4352
	ds_read_b32 v248, v243 offset:4608
	ds_read_b32 v249, v243 offset:4864
	s_waitcnt lgkmcnt(0)
	v_add_f32_e32 v225, v244, v245
	v_add_f32_e32 v225, v225, v248
	v_add_f32_e32 v225, v225, v249
	ds_read_b32 v244, v243 offset:6144
	ds_read_b32 v245, v243 offset:6400
	ds_read_b32 v248, v243 offset:6656
	ds_read_b32 v249, v243 offset:6912
	s_waitcnt lgkmcnt(0)
	v_add_f32_e32 v224, v244, v245
	v_add_f32_e32 v224, v224, v248
	v_add_f32_e32 v224, v224, v249
	v_and_b32_e32 v229, 64, v253
	v_xor_b32_e32 v228, 32, v253
	v_add_u32_e32 v229, 64, v229
	v_cmp_lt_i32_e32 vcc, v228, v229
	v_mov_b32_e32 v233, v235
	s_nop 0
	v_cndmask_b32_e32 v228, v253, v228, vcc
	v_lshlrev_b32_e32 v232, 2, v228
	ds_bpermute_b32 v229, v232, v227
	ds_bpermute_b32 v228, v232, v226
	s_waitcnt lgkmcnt(0)
	v_pk_add_f32 v[226:227], v[226:227], v[228:229]
	s_nop 0
	v_pk_fma_f32 v[230:231], v[226:227], s[76:77], v[246:247] op_sel_hi:[1,0,0]
	ds_bpermute_b32 v229, v232, v225
	v_mul_f32_e32 v226, 0x4b800000, v231
	v_cmp_gt_f32_e32 vcc, s67, v231
	v_mov_b32_e32 v227, v236
	v_cmp_gt_f32_e64 s[16:17], s67, v230
	v_cndmask_b32_e32 v226, v231, v226, vcc
	v_rsq_f32_e32 v226, v226
	v_add3_u32 v231, s9, v221, v233
	v_mul_f32_e32 v228, 0x45800000, v226
	v_cndmask_b32_e32 v238, v226, v228, vcc
	ds_bpermute_b32 v228, v232, v224
	v_lshl_or_b32 v226, s8, 8, v234
	v_lshl_add_u32 v226, v227, 2, v226
	v_mov_b64_e32 v[232:233], s[54:55]
	v_mad_i64_i32 v[232:233], s[2:3], v231, s18, v[232:233]
	v_cmp_gt_i32_e32 vcc, s22, v226
	v_ashrrev_i32_e32 v227, 31, v226
	s_and_saveexec_b64 s[2:3], vcc
	s_cbranch_execz .LBB0_608
	v_mul_f32_e32 v112, v112, v238
	v_mul_f32_e32 v113, v113, v238
	v_cvt_pk_bf16_f32 v112, v112, v113
	v_mul_f32_e32 v113, v114, v238
	v_mul_f32_e32 v114, v115, v238
	v_cvt_pk_bf16_f32 v113, v113, v114
	v_lshl_add_u64 v[114:115], v[226:227], 1, v[232:233]
	global_store_dwordx2 v[114:115], v[112:113], off
